# gelu peepholes: select at 151 of 192 sites (adds the -qe*x+x operand order), abs at 169
# baseline (speedup 1.0000x reference)
.LBB0_443:
	s_waitcnt vmcnt(0)
	v_mov_b32_e32 v55, v0
	s_mov_b64 s[12:13], s[74:75]
	v_readfirstlane_b32 s0, v55
	s_ashr_i32 s10, s0, 6
	s_add_u32 s4, s12, 0x696e000
	v_bfe_u32 v3, v55, 4, 2
	s_addc_u32 s5, s13, 0
	s_lshl_b32 s11, s10, 4
	s_ashr_i32 s71, s70, 31
	v_or_b32_e32 v16, s11, v3
	s_lshl_b64 s[6:7], s[70:71], 7
	v_ashrrev_i32_e32 v17, 31, v16
	v_lshl_add_u64 v[4:5], s[6:7], 0, v[16:17]
	v_and_b32_e32 v54, 15, v55
	v_lshlrev_b64 v[4:5], 11, v[4:5]
	v_lshl_add_u64 v[4:5], s[4:5], 0, v[4:5]
	v_lshlrev_b32_e32 v6, 4, v54
	s_waitcnt lgkmcnt(0)
	v_mov_b32_e32 v7, v2
	v_lshl_add_u64 v[20:21], v[4:5], 0, v[6:7]
	s_barrier
	global_load_dwordx4 v[8:11], v[20:21], off
	global_load_dwordx4 v[4:7], v[20:21], off offset:256
	v_mov_b64_e32 v[18:19], s[44:45]
	v_mov_b32_e32 v13, v2
	s_waitcnt vmcnt(1)
	v_lshlrev_b32_e32 v24, 16, v10
	v_and_b32_e32 v25, 0xffff0000, v10
	v_and_b32_e32 v15, 0xffff0000, v8
	v_and_b32_e32 v23, 0xffff0000, v9
	v_lshlrev_b32_e32 v22, 16, v9
	v_lshlrev_b32_e32 v14, 16, v8
	v_lshlrev_b32_e32 v8, 16, v11
	v_and_b32_e32 v9, 0xffff0000, v11
	v_fma_f32 v10, |v24|, s40, 1.0
	v_fma_f32 v11, |v25|, s40, 1.0
	v_fma_f32 v28, |v14|, s40, 1.0
	v_fma_f32 v29, |v15|, s40, 1.0
	v_rcp_f32_e32 v10, v10
	v_rcp_f32_e32 v11, v11
	v_fma_f32 v32, |v22|, s40, 1.0
	v_fma_f32 v33, |v23|, s40, 1.0
	v_rcp_f32_e32 v28, v28
	v_rcp_f32_e32 v29, v29
	v_rcp_f32_e32 v32, v32
	v_rcp_f32_e32 v33, v33
	v_pk_mul_f32 v[26:27], v[24:25], v[24:25]
	v_pk_mul_f32 v[30:31], v[14:15], v[14:15]
	v_pk_mul_f32 v[26:27], v[26:27], s[64:65] op_sel_hi:[1,0]
	v_pk_fma_f32 v[36:37], v[10:11], s[42:43], v[18:19] op_sel_hi:[1,0,0]
	v_pk_mul_f32 v[34:35], v[22:23], v[22:23]
	v_pk_mul_f32 v[30:31], v[30:31], s[64:65] op_sel_hi:[1,0]
	v_exp_f32_e32 v26, v26
	v_exp_f32_e32 v27, v27
	v_pk_fma_f32 v[38:39], v[28:29], s[42:43], v[18:19] op_sel_hi:[1,0,0]
	v_pk_fma_f32 v[36:37], v[10:11], v[36:37], s[48:49] op_sel_hi:[1,1,0]
	v_pk_mul_f32 v[34:35], v[34:35], s[64:65] op_sel_hi:[1,0]
	v_exp_f32_e32 v30, v30
	v_exp_f32_e32 v31, v31
	v_pk_fma_f32 v[40:41], v[32:33], s[42:43], v[18:19] op_sel_hi:[1,0,0]
	v_pk_fma_f32 v[38:39], v[28:29], v[38:39], s[48:49] op_sel_hi:[1,1,0]
	v_pk_fma_f32 v[36:37], v[10:11], v[36:37], s[50:51] op_sel_hi:[1,1,0]
	v_exp_f32_e32 v34, v34
	v_exp_f32_e32 v35, v35
	v_pk_fma_f32 v[40:41], v[32:33], v[40:41], s[48:49] op_sel_hi:[1,1,0]
	v_pk_fma_f32 v[38:39], v[28:29], v[38:39], s[50:51] op_sel_hi:[1,1,0]
	v_pk_fma_f32 v[36:37], v[10:11], v[36:37], s[56:57] op_sel_hi:[1,1,0]
	v_pk_fma_f32 v[40:41], v[32:33], v[40:41], s[50:51] op_sel_hi:[1,1,0]
	v_pk_fma_f32 v[38:39], v[28:29], v[38:39], s[56:57] op_sel_hi:[1,1,0]
	v_pk_mul_f32 v[10:11], v[10:11], v[36:37]
	v_pk_fma_f32 v[40:41], v[32:33], v[40:41], s[56:57] op_sel_hi:[1,1,0]
	v_pk_mul_f32 v[28:29], v[28:29], v[38:39]
	v_pk_mul_f32 v[10:11], v[26:27], v[10:11]
	v_pk_mul_f32 v[32:33], v[32:33], v[40:41]
	v_pk_mul_f32 v[26:27], v[30:31], v[28:29]
	v_max_f32_e32 v80, 0, v24
	v_fma_f32 v37, -|v24|, v10, v80
	v_max_f32_e32 v81, 0, v25
	v_fma_f32 v11, -|v25|, v11, v81
	v_pk_mul_f32 v[28:29], v[34:35], v[32:33]
	v_max_f32_e32 v82, 0, v22
	v_fma_f32 v25, -|v22|, v28, v82
	v_max_f32_e32 v83, 0, v23
	v_fma_f32 v23, -|v23|, v29, v83
	v_max_f32_e32 v84, 0, v14
	v_fma_f32 v24, -|v14|, v26, v84
	v_max_f32_e32 v85, 0, v15
	v_fma_f32 v15, -|v15|, v27, v85
	v_mul_f32_e32 v36, v37, v37
	v_mov_b32_e32 v14, v25
	v_mul_f32_e32 v10, v11, v11
	v_mul_f32_e32 v26, v24, v24
	v_pk_add_f32 v[10:11], v[36:37], v[10:11]
	v_mov_b32_e32 v27, v25
	v_mul_f32_e32 v22, v15, v15
	v_mul_f32_e32 v12, v23, v23
	v_pk_add_f32 v[22:23], v[26:27], v[22:23]
	v_pk_mul_f32 v[26:27], v[24:25], v[14:15] op_sel:[1,0] op_sel_hi:[0,1]
	v_pk_add_f32 v[14:15], v[24:25], v[14:15] op_sel:[1,0] op_sel_hi:[0,1]
	v_mov_b32_e32 v27, v15
	v_fma_f32 v14, |v8|, s40, 1.0
	v_fma_f32 v15, |v9|, s40, 1.0
	v_pk_add_f32 v[12:13], v[26:27], v[12:13]
	v_rcp_f32_e32 v14, v14
	v_rcp_f32_e32 v15, v15
	v_pk_add_f32 v[12:13], v[22:23], v[12:13]
	v_cmp_gt_f32_e32 vcc, 0, v8
	v_pk_add_f32 v[22:23], v[10:11], v[12:13]
	v_pk_mul_f32 v[12:13], v[8:9], v[8:9]
	v_pk_fma_f32 v[10:11], v[14:15], s[42:43], v[18:19] op_sel_hi:[1,0,0]
	v_pk_mul_f32 v[12:13], v[12:13], s[64:65] op_sel_hi:[1,0]
	v_pk_fma_f32 v[10:11], v[14:15], v[10:11], s[48:49] op_sel_hi:[1,1,0]
	v_exp_f32_e32 v12, v12
	v_exp_f32_e32 v13, v13
	v_pk_fma_f32 v[10:11], v[14:15], v[10:11], s[50:51] op_sel_hi:[1,1,0]
	s_waitcnt vmcnt(0)
	v_lshlrev_b32_e32 v36, 16, v6
	v_pk_fma_f32 v[10:11], v[14:15], v[10:11], s[56:57] op_sel_hi:[1,1,0]
	v_and_b32_e32 v37, 0xffff0000, v6
	v_pk_mul_f32 v[10:11], v[14:15], v[10:11]
	v_pk_mul_f32 v[10:11], v[12:13], v[10:11]
	v_pk_mul_f32 v[12:13], v[8:9], v[10:11]
	v_pk_fma_f32 v[10:11], v[8:9], v[10:11], v[8:9] neg_lo:[1,0,0] neg_hi:[1,0,0]
	v_fma_f32 v32, |v36|, s40, 1.0
	v_fma_f32 v33, |v37|, s40, 1.0
	v_cndmask_b32_e32 v15, v10, v12, vcc
	v_cmp_gt_f32_e32 vcc, 0, v9
	v_lshlrev_b32_e32 v12, 16, v4
	v_and_b32_e32 v10, 0x7fffffff, v12
	v_cndmask_b32_e32 v9, v11, v13, vcc
	v_and_b32_e32 v13, 0xffff0000, v4
	v_and_b32_e32 v11, 0x7fffffff, v13
	v_pk_fma_f32 v[10:11], v[10:11], s[40:41], 1.0 op_sel_hi:[1,0,0]
	v_mul_f32_e32 v14, v15, v15
	v_rcp_f32_e32 v10, v10
	v_rcp_f32_e32 v11, v11
	v_mul_f32_e32 v8, v9, v9
	v_pk_add_f32 v[24:25], v[14:15], v[8:9]
	v_pk_mul_f32 v[14:15], v[12:13], v[12:13]
	v_pk_fma_f32 v[8:9], v[10:11], s[42:43], v[18:19] op_sel_hi:[1,0,0]
	v_pk_mul_f32 v[14:15], v[14:15], s[64:65] op_sel_hi:[1,0]
	v_pk_fma_f32 v[8:9], v[10:11], v[8:9], s[48:49] op_sel_hi:[1,1,0]
	v_exp_f32_e32 v14, v14
	v_exp_f32_e32 v15, v15
	v_pk_fma_f32 v[8:9], v[10:11], v[8:9], s[50:51] op_sel_hi:[1,1,0]
	v_lshlrev_b32_e32 v4, 16, v5
	v_pk_fma_f32 v[8:9], v[10:11], v[8:9], s[56:57] op_sel_hi:[1,1,0]
	v_and_b32_e32 v5, 0xffff0000, v5
	v_pk_mul_f32 v[8:9], v[10:11], v[8:9]
	v_pk_mul_f32 v[14:15], v[14:15], v[8:9]
	global_load_dwordx4 v[8:11], v[20:21], off offset:512
	v_fma_f32 v30, |v4|, s40, 1.0
	v_fma_f32 v31, |v5|, s40, 1.0
	v_rcp_f32_e32 v30, v30
	v_rcp_f32_e32 v31, v31
	v_max_f32_e32 v86, 0, v12
	v_fma_f32 v27, -|v12|, v14, v86
	v_max_f32_e32 v90, 0, v13
	v_fma_f32 v29, -|v13|, v15, v90
	v_rcp_f32_e32 v34, v32
	v_rcp_f32_e32 v35, v33
	v_pk_fma_f32 v[12:13], v[30:31], s[42:43], v[18:19] op_sel_hi:[1,0,0]
	v_mul_f32_e32 v26, v27, v27
	v_pk_mul_f32 v[14:15], v[4:5], v[4:5]
	v_pk_fma_f32 v[12:13], v[30:31], v[12:13], s[48:49] op_sel_hi:[1,1,0]
	v_pk_mul_f32 v[14:15], v[14:15], s[64:65] op_sel_hi:[1,0]
	v_pk_fma_f32 v[12:13], v[30:31], v[12:13], s[50:51] op_sel_hi:[1,1,0]
	v_exp_f32_e32 v14, v14
	v_exp_f32_e32 v15, v15
	v_pk_fma_f32 v[12:13], v[30:31], v[12:13], s[56:57] op_sel_hi:[1,1,0]
	v_pk_mul_f32 v[12:13], v[30:31], v[12:13]
	v_mul_f32_e32 v28, v29, v29
	v_pk_mul_f32 v[12:13], v[14:15], v[12:13]
	v_pk_add_f32 v[22:23], v[24:25], v[22:23]
	v_max_f32_e32 v91, 0, v4
	v_fma_f32 v31, -|v4|, v12, v91
	v_max_f32_e32 v92, 0, v5
	v_fma_f32 v33, -|v5|, v13, v92
	v_pk_add_f32 v[24:25], v[26:27], v[28:29]
	v_pk_fma_f32 v[4:5], v[34:35], s[42:43], v[18:19] op_sel_hi:[1,0,0]
	v_lshlrev_b32_e32 v14, 16, v7
	v_pk_mul_f32 v[12:13], v[36:37], v[36:37]
	v_pk_fma_f32 v[4:5], v[34:35], v[4:5], s[48:49] op_sel_hi:[1,1,0]
	v_pk_mul_f32 v[12:13], v[12:13], s[64:65] op_sel_hi:[1,0]
	v_pk_fma_f32 v[4:5], v[34:35], v[4:5], s[50:51] op_sel_hi:[1,1,0]
	v_exp_f32_e32 v12, v12
	v_exp_f32_e32 v13, v13
	v_and_b32_e32 v15, 0xffff0000, v7
	v_pk_fma_f32 v[4:5], v[34:35], v[4:5], s[56:57] op_sel_hi:[1,1,0]
	v_pk_mul_f32 v[4:5], v[34:35], v[4:5]
	v_fma_f32 v6, |v14|, s40, 1.0
	v_fma_f32 v7, |v15|, s40, 1.0
	v_pk_mul_f32 v[4:5], v[12:13], v[4:5]
	v_rcp_f32_e32 v6, v6
	v_rcp_f32_e32 v7, v7
	v_max_f32_e32 v93, 0, v36
	v_fma_f32 v35, -|v36|, v4, v93
	v_max_f32_e32 v94, 0, v37
	v_fma_f32 v37, -|v37|, v5, v94
	v_mul_f32_e32 v30, v31, v31
	v_mul_f32_e32 v32, v33, v33
	v_mul_f32_e32 v34, v35, v35
	v_pk_add_f32 v[22:23], v[24:25], v[22:23]
	v_pk_mul_f32 v[12:13], v[14:15], v[14:15]
	v_pk_fma_f32 v[4:5], v[6:7], s[42:43], v[18:19] op_sel_hi:[1,0,0]
	v_pk_mul_f32 v[12:13], v[12:13], s[64:65] op_sel_hi:[1,0]
	v_pk_fma_f32 v[4:5], v[6:7], v[4:5], s[48:49] op_sel_hi:[1,1,0]
	v_exp_f32_e32 v12, v12
	v_exp_f32_e32 v13, v13
	v_pk_fma_f32 v[4:5], v[6:7], v[4:5], s[50:51] op_sel_hi:[1,1,0]
	v_pk_fma_f32 v[4:5], v[6:7], v[4:5], s[56:57] op_sel_hi:[1,1,0]
	v_mul_f32_e32 v36, v37, v37
	v_pk_mul_f32 v[4:5], v[6:7], v[4:5]
	v_pk_add_f32 v[24:25], v[30:31], v[32:33]
	v_pk_mul_f32 v[4:5], v[12:13], v[4:5]
	v_pk_add_f32 v[22:23], v[24:25], v[22:23]
	v_max_f32_e32 v95, 0, v14
	v_fma_f32 v39, -|v14|, v4, v95
	v_max_f32_e32 v96, 0, v15
	v_fma_f32 v41, -|v15|, v5, v96
	global_load_dwordx4 v[4:7], v[20:21], off offset:768
	v_mul_f32_e32 v38, v39, v39
	s_waitcnt vmcnt(1)
	v_lshlrev_b32_e32 v44, 16, v8
	v_and_b32_e32 v45, 0xffff0000, v8
	v_fma_f32 v42, |v44|, s40, 1.0
	v_fma_f32 v43, |v45|, s40, 1.0
	v_pk_mul_f32 v[14:15], v[44:45], v[44:45]
	v_rcp_f32_e32 v42, v42
	v_rcp_f32_e32 v43, v43
	v_pk_mul_f32 v[14:15], v[14:15], s[64:65] op_sel_hi:[1,0]
	v_lshlrev_b32_e32 v46, 16, v9
	v_pk_fma_f32 v[12:13], v[42:43], s[42:43], v[18:19] op_sel_hi:[1,0,0]
	v_exp_f32_e32 v14, v14
	v_pk_fma_f32 v[12:13], v[42:43], v[12:13], s[48:49] op_sel_hi:[1,1,0]
	v_exp_f32_e32 v15, v15
	v_and_b32_e32 v47, 0xffff0000, v9
	v_pk_fma_f32 v[12:13], v[42:43], v[12:13], s[50:51] op_sel_hi:[1,1,0]
	v_pk_fma_f32 v[12:13], v[42:43], v[12:13], s[56:57] op_sel_hi:[1,1,0]
	v_fma_f32 v8, |v46|, s40, 1.0
	v_fma_f32 v9, |v47|, s40, 1.0
	v_pk_mul_f32 v[12:13], v[42:43], v[12:13]
	v_rcp_f32_e32 v48, v8
	v_rcp_f32_e32 v49, v9
	v_pk_mul_f32 v[12:13], v[14:15], v[12:13]
	v_max_f32_e32 v97, 0, v44
	v_fma_f32 v43, -|v44|, v12, v97
	v_max_f32_e32 v98, 0, v45
	v_fma_f32 v9, -|v45|, v13, v98
	v_lshlrev_b32_e32 v50, 16, v10
	v_and_b32_e32 v51, 0xffff0000, v10
	v_lshlrev_b32_e32 v10, 16, v11
	v_pk_fma_f32 v[12:13], v[48:49], s[42:43], v[18:19] op_sel_hi:[1,0,0]
	v_pk_mul_f32 v[14:15], v[46:47], v[46:47]
	v_pk_fma_f32 v[12:13], v[48:49], v[12:13], s[48:49] op_sel_hi:[1,1,0]
	v_pk_mul_f32 v[14:15], v[14:15], s[64:65] op_sel_hi:[1,0]
	v_pk_fma_f32 v[12:13], v[48:49], v[12:13], s[50:51] op_sel_hi:[1,1,0]
	v_exp_f32_e32 v14, v14
	v_exp_f32_e32 v15, v15
	v_pk_fma_f32 v[12:13], v[48:49], v[12:13], s[56:57] op_sel_hi:[1,1,0]
	v_pk_mul_f32 v[12:13], v[48:49], v[12:13]
	v_fma_f32 v48, |v50|, s40, 1.0
	v_fma_f32 v49, |v51|, s40, 1.0
	v_pk_mul_f32 v[12:13], v[14:15], v[12:13]
	v_rcp_f32_e32 v48, v48
	v_rcp_f32_e32 v49, v49
	v_max_f32_e32 v99, 0, v46
	v_fma_f32 v45, -|v46|, v12, v99
	v_max_f32_e32 v100, 0, v47
	v_fma_f32 v47, -|v47|, v13, v100
	v_and_b32_e32 v11, 0xffff0000, v11
	v_pk_mul_f32 v[14:15], v[50:51], v[50:51]
	v_pk_fma_f32 v[12:13], v[48:49], s[42:43], v[18:19] op_sel_hi:[1,0,0]
	v_pk_mul_f32 v[14:15], v[14:15], s[64:65] op_sel_hi:[1,0]
	v_pk_fma_f32 v[12:13], v[48:49], v[12:13], s[48:49] op_sel_hi:[1,1,0]
	v_exp_f32_e32 v14, v14
	v_exp_f32_e32 v15, v15
	v_pk_fma_f32 v[12:13], v[48:49], v[12:13], s[50:51] op_sel_hi:[1,1,0]
	v_fma_f32 v52, |v10|, s40, 1.0
	v_fma_f32 v53, |v11|, s40, 1.0
	v_pk_fma_f32 v[12:13], v[48:49], v[12:13], s[56:57] op_sel_hi:[1,1,0]
	v_rcp_f32_e32 v52, v52
	v_pk_mul_f32 v[12:13], v[48:49], v[12:13]
	v_rcp_f32_e32 v53, v53
	v_pk_mul_f32 v[12:13], v[14:15], v[12:13]
	v_max_f32_e32 v104, 0, v50
	v_fma_f32 v49, -|v50|, v12, v104
	v_max_f32_e32 v105, 0, v51
	v_fma_f32 v51, -|v51|, v13, v105
	v_mul_f32_e32 v40, v41, v41
	s_waitcnt vmcnt(0)
	v_lshlrev_b32_e32 v56, 16, v4
	v_and_b32_e32 v57, 0xffff0000, v4
	v_pk_mul_f32 v[14:15], v[10:11], v[10:11]
	v_pk_fma_f32 v[12:13], v[52:53], s[42:43], v[18:19] op_sel_hi:[1,0,0]
	v_pk_mul_f32 v[14:15], v[14:15], s[64:65] op_sel_hi:[1,0]
	v_pk_fma_f32 v[12:13], v[52:53], v[12:13], s[48:49] op_sel_hi:[1,1,0]
	v_exp_f32_e32 v14, v14
	v_exp_f32_e32 v15, v15
	v_pk_fma_f32 v[12:13], v[52:53], v[12:13], s[50:51] op_sel_hi:[1,1,0]
	v_pk_fma_f32 v[12:13], v[52:53], v[12:13], s[56:57] op_sel_hi:[1,1,0]
	v_pk_mul_f32 v[12:13], v[52:53], v[12:13]
	v_fma_f32 v58, |v56|, s40, 1.0
	v_fma_f32 v59, |v57|, s40, 1.0
	v_pk_mul_f32 v[12:13], v[14:15], v[12:13]
	v_rcp_f32_e32 v58, v58
	v_rcp_f32_e32 v59, v59
	v_max_f32_e32 v106, 0, v10
	v_fma_f32 v53, -|v10|, v12, v106
	v_max_f32_e32 v107, 0, v11
	v_fma_f32 v11, -|v11|, v13, v107
	v_lshlrev_b32_e32 v4, 16, v5
	v_and_b32_e32 v5, 0xffff0000, v5
	v_pk_mul_f32 v[14:15], v[56:57], v[56:57]
	v_pk_fma_f32 v[12:13], v[58:59], s[42:43], v[18:19] op_sel_hi:[1,0,0]
	v_pk_mul_f32 v[14:15], v[14:15], s[64:65] op_sel_hi:[1,0]
	v_pk_fma_f32 v[12:13], v[58:59], v[12:13], s[48:49] op_sel_hi:[1,1,0]
	v_exp_f32_e32 v14, v14
	v_exp_f32_e32 v15, v15
	v_pk_fma_f32 v[12:13], v[58:59], v[12:13], s[50:51] op_sel_hi:[1,1,0]
	v_fma_f32 v60, |v4|, s40, 1.0
	v_fma_f32 v61, |v5|, s40, 1.0
	v_pk_fma_f32 v[12:13], v[58:59], v[12:13], s[56:57] op_sel_hi:[1,1,0]
	v_rcp_f32_e32 v60, v60
	v_pk_mul_f32 v[12:13], v[58:59], v[12:13]
	v_rcp_f32_e32 v61, v61
	v_pk_mul_f32 v[12:13], v[14:15], v[12:13]
	v_max_f32_e32 v108, 0, v56
	v_fma_f32 v59, -|v56|, v12, v108
	v_max_f32_e32 v109, 0, v57
	v_fma_f32 v57, -|v57|, v13, v109
	v_pk_add_f32 v[24:25], v[34:35], v[36:37]
	v_mul_f32_e32 v42, v43, v43
	v_mul_f32_e32 v8, v9, v9
	v_pk_fma_f32 v[12:13], v[60:61], s[42:43], v[18:19] op_sel_hi:[1,0,0]
	v_pk_mul_f32 v[14:15], v[4:5], v[4:5]
	v_pk_fma_f32 v[12:13], v[60:61], v[12:13], s[48:49] op_sel_hi:[1,1,0]
	v_pk_mul_f32 v[14:15], v[14:15], s[64:65] op_sel_hi:[1,0]
	v_pk_fma_f32 v[12:13], v[60:61], v[12:13], s[50:51] op_sel_hi:[1,1,0]
	v_exp_f32_e32 v62, v14
	v_exp_f32_e32 v63, v15
	v_pk_fma_f32 v[64:65], v[60:61], v[12:13], s[56:57] op_sel_hi:[1,1,0]
	global_load_dwordx4 v[12:15], v[20:21], off offset:1024
	v_pk_add_f32 v[22:23], v[24:25], v[22:23]
	v_pk_add_f32 v[24:25], v[38:39], v[40:41]
	v_mul_f32_e32 v44, v45, v45
	v_mul_f32_e32 v46, v47, v47
	v_pk_add_f32 v[22:23], v[24:25], v[22:23]
	v_pk_add_f32 v[8:9], v[42:43], v[8:9]
	v_mul_f32_e32 v48, v49, v49
	v_mul_f32_e32 v50, v51, v51
	v_pk_mul_f32 v[60:61], v[60:61], v[64:65]
	v_pk_add_f32 v[8:9], v[8:9], v[22:23]
	v_pk_add_f32 v[22:23], v[44:45], v[46:47]
	v_pk_mul_f32 v[60:61], v[62:63], v[60:61]
	v_pk_add_f32 v[8:9], v[22:23], v[8:9]
	v_pk_add_f32 v[22:23], v[48:49], v[50:51]
	v_lshlrev_b32_e32 v24, 16, v6
	v_and_b32_e32 v25, 0xffff0000, v6
	v_max_f32_e32 v110, 0, v4
	v_fma_f32 v65, -|v4|, v60, v110
	v_max_f32_e32 v111, 0, v5
	v_fma_f32 v5, -|v5|, v61, v111
	v_pk_add_f32 v[8:9], v[22:23], v[8:9]
	v_mul_f32_e32 v52, v53, v53
	v_mul_f32_e32 v10, v11, v11
	v_fma_f32 v22, |v24|, s40, 1.0
	v_fma_f32 v23, |v25|, s40, 1.0
	v_mul_f32_e32 v58, v59, v59
	v_mul_f32_e32 v56, v57, v57
	v_pk_add_f32 v[10:11], v[52:53], v[10:11]
	v_rcp_f32_e32 v26, v22
	v_rcp_f32_e32 v27, v23
	v_mul_f32_e32 v64, v65, v65
	v_mul_f32_e32 v4, v5, v5
	v_pk_add_f32 v[8:9], v[10:11], v[8:9]
	v_pk_add_f32 v[10:11], v[58:59], v[56:57]
	v_pk_add_f32 v[4:5], v[64:65], v[4:5]
	v_pk_add_f32 v[8:9], v[10:11], v[8:9]
	v_cmp_gt_f32_e32 vcc, 0, v24
	v_pk_add_f32 v[22:23], v[4:5], v[8:9]
	v_pk_mul_f32 v[8:9], v[24:25], v[24:25]
	v_pk_fma_f32 v[4:5], v[26:27], s[42:43], v[18:19] op_sel_hi:[1,0,0]
	v_pk_mul_f32 v[8:9], v[8:9], s[64:65] op_sel_hi:[1,0]
	v_pk_fma_f32 v[4:5], v[26:27], v[4:5], s[48:49] op_sel_hi:[1,1,0]
	v_exp_f32_e32 v8, v8
	v_exp_f32_e32 v9, v9
	v_pk_fma_f32 v[4:5], v[26:27], v[4:5], s[50:51] op_sel_hi:[1,1,0]
	v_lshlrev_b32_e32 v6, 16, v7
	v_pk_fma_f32 v[4:5], v[26:27], v[4:5], s[56:57] op_sel_hi:[1,1,0]
	v_and_b32_e32 v7, 0xffff0000, v7
	v_pk_mul_f32 v[4:5], v[26:27], v[4:5]
	s_nop 0
	v_pk_mul_f32 v[4:5], v[8:9], v[4:5]
	s_nop 0
	v_pk_mul_f32 v[8:9], v[24:25], v[4:5]
	v_pk_fma_f32 v[4:5], v[24:25], v[4:5], v[24:25] neg_lo:[1,0,0] neg_hi:[1,0,0]
	s_nop 0
	v_cndmask_b32_e32 v11, v4, v8, vcc
	v_cmp_gt_f32_e32 vcc, 0, v25
	v_and_b32_e32 v8, 0x7fffffff, v6
	v_mul_f32_e32 v10, v11, v11
	v_cndmask_b32_e32 v5, v5, v9, vcc
	v_and_b32_e32 v9, 0x7fffffff, v7
	v_pk_fma_f32 v[8:9], v[8:9], s[40:41], 1.0 op_sel_hi:[1,0,0]
	v_mul_f32_e32 v4, v5, v5
	v_rcp_f32_e32 v8, v8
	v_rcp_f32_e32 v9, v9
	v_pk_add_f32 v[24:25], v[10:11], v[4:5]
	v_pk_mul_f32 v[10:11], v[6:7], v[6:7]
	v_cmp_gt_f32_e32 vcc, 0, v6
	v_pk_fma_f32 v[4:5], v[8:9], s[42:43], v[18:19] op_sel_hi:[1,0,0]
	v_pk_mul_f32 v[10:11], v[10:11], s[64:65] op_sel_hi:[1,0]
	v_pk_fma_f32 v[4:5], v[8:9], v[4:5], s[48:49] op_sel_hi:[1,1,0]
	v_exp_f32_e32 v10, v10
	v_exp_f32_e32 v11, v11
	v_pk_fma_f32 v[4:5], v[8:9], v[4:5], s[50:51] op_sel_hi:[1,1,0]
	v_pk_add_f32 v[22:23], v[24:25], v[22:23]
	v_pk_fma_f32 v[4:5], v[8:9], v[4:5], s[56:57] op_sel_hi:[1,1,0]
	s_nop 0
	v_pk_mul_f32 v[4:5], v[8:9], v[4:5]
	s_nop 0
	v_pk_mul_f32 v[4:5], v[10:11], v[4:5]
	global_load_dwordx4 v[8:11], v[20:21], off offset:1280
	s_waitcnt vmcnt(1)
	v_lshlrev_b32_e32 v32, 16, v12
	v_and_b32_e32 v33, 0xffff0000, v12
	v_fma_f32 v30, |v32|, s40, 1.0
	v_fma_f32 v31, |v33|, s40, 1.0
	v_pk_mul_f32 v[28:29], v[6:7], v[4:5]
	v_rcp_f32_e32 v30, v30
	v_rcp_f32_e32 v31, v31
	v_pk_fma_f32 v[4:5], v[6:7], v[4:5], v[6:7] neg_lo:[1,0,0] neg_hi:[1,0,0]
	v_lshlrev_b32_e32 v34, 16, v13
	v_cndmask_b32_e32 v27, v4, v28, vcc
	v_cmp_gt_f32_e32 vcc, 0, v7
	v_pk_mul_f32 v[6:7], v[32:33], v[32:33]
	v_and_b32_e32 v35, 0xffff0000, v13
	v_cndmask_b32_e32 v29, v5, v29, vcc
	v_pk_fma_f32 v[4:5], v[30:31], s[42:43], v[18:19] op_sel_hi:[1,0,0]
	v_pk_mul_f32 v[6:7], v[6:7], s[64:65] op_sel_hi:[1,0]
	v_pk_fma_f32 v[4:5], v[30:31], v[4:5], s[48:49] op_sel_hi:[1,1,0]
	v_exp_f32_e32 v6, v6
	v_exp_f32_e32 v7, v7
	v_pk_fma_f32 v[4:5], v[30:31], v[4:5], s[50:51] op_sel_hi:[1,1,0]
	v_pk_fma_f32 v[4:5], v[30:31], v[4:5], s[56:57] op_sel_hi:[1,1,0]
	v_fma_f32 v12, |v34|, s40, 1.0
	v_fma_f32 v13, |v35|, s40, 1.0
	v_pk_mul_f32 v[4:5], v[30:31], v[4:5]
	v_rcp_f32_e32 v36, v12
	v_rcp_f32_e32 v37, v13
	v_pk_mul_f32 v[4:5], v[6:7], v[4:5]
	v_max_f32_e32 v112, 0, v32
	v_fma_f32 v31, -|v32|, v4, v112
	v_max_f32_e32 v113, 0, v33
	v_fma_f32 v13, -|v33|, v5, v113
	v_lshlrev_b32_e32 v38, 16, v14
	v_and_b32_e32 v39, 0xffff0000, v14
	v_lshlrev_b32_e32 v40, 16, v15
	v_pk_fma_f32 v[4:5], v[36:37], s[42:43], v[18:19] op_sel_hi:[1,0,0]
	v_pk_mul_f32 v[6:7], v[34:35], v[34:35]
	v_pk_fma_f32 v[4:5], v[36:37], v[4:5], s[48:49] op_sel_hi:[1,1,0]
	v_pk_mul_f32 v[6:7], v[6:7], s[64:65] op_sel_hi:[1,0]
	v_pk_fma_f32 v[4:5], v[36:37], v[4:5], s[50:51] op_sel_hi:[1,1,0]
	v_exp_f32_e32 v6, v6
	v_exp_f32_e32 v7, v7
	v_pk_fma_f32 v[4:5], v[36:37], v[4:5], s[56:57] op_sel_hi:[1,1,0]
	v_pk_mul_f32 v[4:5], v[36:37], v[4:5]
	v_fma_f32 v36, |v38|, s40, 1.0
	v_fma_f32 v37, |v39|, s40, 1.0
	v_pk_mul_f32 v[4:5], v[6:7], v[4:5]
	v_rcp_f32_e32 v36, v36
	v_rcp_f32_e32 v37, v37
	v_max_f32_e32 v114, 0, v34
	v_fma_f32 v33, -|v34|, v4, v114
	v_max_f32_e32 v115, 0, v35
	v_fma_f32 v35, -|v35|, v5, v115
	v_and_b32_e32 v41, 0xffff0000, v15
	v_pk_mul_f32 v[6:7], v[38:39], v[38:39]
	v_pk_fma_f32 v[4:5], v[36:37], s[42:43], v[18:19] op_sel_hi:[1,0,0]
	v_pk_mul_f32 v[6:7], v[6:7], s[64:65] op_sel_hi:[1,0]
	v_pk_fma_f32 v[4:5], v[36:37], v[4:5], s[48:49] op_sel_hi:[1,1,0]
	v_exp_f32_e32 v6, v6
	v_exp_f32_e32 v7, v7
	v_pk_fma_f32 v[4:5], v[36:37], v[4:5], s[50:51] op_sel_hi:[1,1,0]
	v_fma_f32 v14, |v40|, s40, 1.0
	v_fma_f32 v15, |v41|, s40, 1.0
	v_pk_fma_f32 v[4:5], v[36:37], v[4:5], s[56:57] op_sel_hi:[1,1,0]
	v_rcp_f32_e32 v42, v14
	v_pk_mul_f32 v[4:5], v[36:37], v[4:5]
	v_rcp_f32_e32 v43, v15
	v_pk_mul_f32 v[4:5], v[6:7], v[4:5]
	v_max_f32_e32 v116, 0, v38
	v_fma_f32 v37, -|v38|, v4, v116
	v_max_f32_e32 v117, 0, v39
	v_fma_f32 v15, -|v39|, v5, v117
	v_mul_f32_e32 v26, v27, v27
	s_waitcnt vmcnt(0)
	v_lshlrev_b32_e32 v44, 16, v8
	v_and_b32_e32 v45, 0xffff0000, v8
	v_pk_fma_f32 v[4:5], v[42:43], s[42:43], v[18:19] op_sel_hi:[1,0,0]
	v_pk_mul_f32 v[6:7], v[40:41], v[40:41]
	v_pk_fma_f32 v[4:5], v[42:43], v[4:5], s[48:49] op_sel_hi:[1,1,0]
	v_pk_mul_f32 v[6:7], v[6:7], s[64:65] op_sel_hi:[1,0]
	v_pk_fma_f32 v[4:5], v[42:43], v[4:5], s[50:51] op_sel_hi:[1,1,0]
	v_exp_f32_e32 v6, v6
	v_exp_f32_e32 v7, v7
	v_pk_fma_f32 v[4:5], v[42:43], v[4:5], s[56:57] op_sel_hi:[1,1,0]
	v_pk_mul_f32 v[4:5], v[42:43], v[4:5]
	v_fma_f32 v42, |v44|, s40, 1.0
	v_fma_f32 v43, |v45|, s40, 1.0
	v_pk_mul_f32 v[4:5], v[6:7], v[4:5]
	v_rcp_f32_e32 v42, v42
	v_rcp_f32_e32 v43, v43
	v_max_f32_e32 v80, 0, v40
	v_fma_f32 v39, -|v40|, v4, v80
	v_max_f32_e32 v81, 0, v41
	v_fma_f32 v41, -|v41|, v5, v81
	v_lshlrev_b32_e32 v50, 16, v9
	v_and_b32_e32 v51, 0xffff0000, v9
	v_pk_mul_f32 v[6:7], v[44:45], v[44:45]
	v_pk_fma_f32 v[4:5], v[42:43], s[42:43], v[18:19] op_sel_hi:[1,0,0]
	v_pk_mul_f32 v[6:7], v[6:7], s[64:65] op_sel_hi:[1,0]
	v_pk_fma_f32 v[4:5], v[42:43], v[4:5], s[48:49] op_sel_hi:[1,1,0]
	v_exp_f32_e32 v6, v6
	v_exp_f32_e32 v7, v7
	v_pk_fma_f32 v[4:5], v[42:43], v[4:5], s[50:51] op_sel_hi:[1,1,0]
	v_pk_fma_f32 v[4:5], v[42:43], v[4:5], s[56:57] op_sel_hi:[1,1,0]
	v_fma_f32 v8, |v50|, s40, 1.0
	v_fma_f32 v9, |v51|, s40, 1.0
	v_pk_mul_f32 v[4:5], v[42:43], v[4:5]
	v_rcp_f32_e32 v52, v8
	v_pk_mul_f32 v[42:43], v[6:7], v[4:5]
	global_load_dwordx4 v[4:7], v[20:21], off offset:1536
	v_rcp_f32_e32 v53, v9
	v_max_f32_e32 v83, 0, v45
	v_fma_f32 v9, -|v45|, v43, v83
	v_max_f32_e32 v82, 0, v44
	v_fma_f32 v43, -|v44|, v42, v82
	v_lshlrev_b32_e32 v58, 16, v11
	v_and_b32_e32 v59, 0xffff0000, v11
	v_pk_fma_f32 v[44:45], v[52:53], s[42:43], v[18:19] op_sel_hi:[1,0,0]
	v_and_b32_e32 v11, 0x7fffffff, v59
	v_pk_fma_f32 v[44:45], v[52:53], v[44:45], s[48:49] op_sel_hi:[1,1,0]
	v_pk_mul_f32 v[46:47], v[50:51], v[50:51]
	v_pk_fma_f32 v[44:45], v[52:53], v[44:45], s[50:51] op_sel_hi:[1,1,0]
	v_pk_mul_f32 v[46:47], v[46:47], s[64:65] op_sel_hi:[1,0]
	v_pk_fma_f32 v[44:45], v[52:53], v[44:45], s[56:57] op_sel_hi:[1,1,0]
	v_exp_f32_e32 v46, v46
	v_exp_f32_e32 v47, v47
	v_pk_mul_f32 v[44:45], v[52:53], v[44:45]
	v_lshlrev_b32_e32 v52, 16, v10
	v_and_b32_e32 v53, 0xffff0000, v10
	v_fma_f32 v56, |v52|, s40, 1.0
	v_fma_f32 v57, |v53|, s40, 1.0
	v_pk_mul_f32 v[44:45], v[46:47], v[44:45]
	v_rcp_f32_e32 v56, v56
	v_rcp_f32_e32 v57, v57
	v_max_f32_e32 v85, 0, v51
	v_fma_f32 v47, -|v51|, v45, v85
	v_max_f32_e32 v84, 0, v50
	v_fma_f32 v45, -|v50|, v44, v84
	v_and_b32_e32 v10, 0x7fffffff, v58
	v_pk_fma_f32 v[10:11], v[10:11], s[40:41], 1.0 op_sel_hi:[1,0,0]
	v_pk_mul_f32 v[50:51], v[52:53], v[52:53]
	v_rcp_f32_e32 v60, v10
	v_pk_fma_f32 v[48:49], v[56:57], s[42:43], v[18:19] op_sel_hi:[1,0,0]
	v_pk_mul_f32 v[50:51], v[50:51], s[64:65] op_sel_hi:[1,0]
	v_pk_fma_f32 v[48:49], v[56:57], v[48:49], s[48:49] op_sel_hi:[1,1,0]
	v_exp_f32_e32 v50, v50
	v_exp_f32_e32 v51, v51
	v_pk_fma_f32 v[48:49], v[56:57], v[48:49], s[50:51] op_sel_hi:[1,1,0]
	v_rcp_f32_e32 v61, v11
	v_pk_fma_f32 v[48:49], v[56:57], v[48:49], s[56:57] op_sel_hi:[1,1,0]
	v_pk_mul_f32 v[48:49], v[56:57], v[48:49]
	v_mul_f32_e32 v28, v29, v29
	v_pk_mul_f32 v[48:49], v[50:51], v[48:49]
	v_mul_f32_e32 v30, v31, v31
	v_max_f32_e32 v90, 0, v53
	v_fma_f32 v11, -|v53|, v49, v90
	v_max_f32_e32 v86, 0, v52
	v_fma_f32 v49, -|v52|, v48, v86
	v_mul_f32_e32 v12, v13, v13
	v_pk_mul_f32 v[52:53], v[58:59], v[58:59]
	v_pk_add_f32 v[24:25], v[26:27], v[28:29]
	v_pk_fma_f32 v[50:51], v[60:61], s[42:43], v[18:19] op_sel_hi:[1,0,0]
	v_pk_mul_f32 v[52:53], v[52:53], s[64:65] op_sel_hi:[1,0]
	v_pk_fma_f32 v[50:51], v[60:61], v[50:51], s[48:49] op_sel_hi:[1,1,0]
	v_exp_f32_e32 v52, v52
	v_exp_f32_e32 v53, v53
	v_pk_fma_f32 v[50:51], v[60:61], v[50:51], s[50:51] op_sel_hi:[1,1,0]
	v_pk_fma_f32 v[50:51], v[60:61], v[50:51], s[56:57] op_sel_hi:[1,1,0]
	v_mul_f32_e32 v32, v33, v33
	v_pk_mul_f32 v[50:51], v[60:61], v[50:51]
	v_mul_f32_e32 v34, v35, v35
	v_pk_mul_f32 v[50:51], v[52:53], v[50:51]
	v_pk_add_f32 v[22:23], v[24:25], v[22:23]
	v_max_f32_e32 v91, 0, v58
	v_fma_f32 v63, -|v58|, v50, v91
	v_max_f32_e32 v92, 0, v59
	v_fma_f32 v57, -|v59|, v51, v92
	global_load_dwordx4 v[50:53], v[20:21], off offset:1792
	v_pk_add_f32 v[12:13], v[30:31], v[12:13]
	v_mul_f32_e32 v36, v37, v37
	s_waitcnt vmcnt(1)
	v_lshlrev_b32_e32 v20, 16, v4
	v_and_b32_e32 v21, 0xffff0000, v4
	v_fma_f32 v64, |v20|, s40, 1.0
	v_fma_f32 v65, |v21|, s40, 1.0
	v_pk_mul_f32 v[60:61], v[20:21], v[20:21]
	v_rcp_f32_e32 v64, v64
	v_rcp_f32_e32 v65, v65
	v_mul_f32_e32 v14, v15, v15
	v_pk_mul_f32 v[60:61], v[60:61], s[64:65] op_sel_hi:[1,0]
	v_pk_add_f32 v[12:13], v[12:13], v[22:23]
	v_pk_fma_f32 v[58:59], v[64:65], s[42:43], v[18:19] op_sel_hi:[1,0,0]
	v_pk_add_f32 v[22:23], v[32:33], v[34:35]
	v_mul_f32_e32 v38, v39, v39
	v_mul_f32_e32 v40, v41, v41
	v_pk_fma_f32 v[58:59], v[64:65], v[58:59], s[48:49] op_sel_hi:[1,1,0]
	v_exp_f32_e32 v60, v60
	v_exp_f32_e32 v61, v61
	v_pk_add_f32 v[12:13], v[22:23], v[12:13]
	v_pk_add_f32 v[14:15], v[36:37], v[14:15]
	v_mul_f32_e32 v42, v43, v43
	v_mul_f32_e32 v8, v9, v9
	v_pk_fma_f32 v[58:59], v[64:65], v[58:59], s[50:51] op_sel_hi:[1,1,0]
	v_pk_add_f32 v[12:13], v[14:15], v[12:13]
	v_pk_add_f32 v[14:15], v[38:39], v[40:41]
	v_mul_f32_e32 v44, v45, v45
	v_mul_f32_e32 v46, v47, v47
	v_pk_fma_f32 v[58:59], v[64:65], v[58:59], s[56:57] op_sel_hi:[1,1,0]
	v_pk_add_f32 v[12:13], v[14:15], v[12:13]
	v_pk_add_f32 v[8:9], v[42:43], v[8:9]
	v_pk_mul_f32 v[58:59], v[64:65], v[58:59]
	v_pk_add_f32 v[8:9], v[8:9], v[12:13]
	v_pk_add_f32 v[12:13], v[44:45], v[46:47]
	v_lshlrev_b32_e32 v4, 16, v5
	v_and_b32_e32 v5, 0xffff0000, v5
	v_pk_mul_f32 v[58:59], v[60:61], v[58:59]
	v_pk_add_f32 v[8:9], v[12:13], v[8:9]
	v_max_f32_e32 v93, 0, v20
	v_fma_f32 v65, -|v20|, v58, v93
	v_max_f32_e32 v94, 0, v21
	v_fma_f32 v21, -|v21|, v59, v94
	v_fma_f32 v12, |v4|, s40, 1.0
	v_fma_f32 v13, |v5|, s40, 1.0
	v_mul_f32_e32 v48, v49, v49
	v_mul_f32_e32 v10, v11, v11
	v_rcp_f32_e32 v12, v12
	v_rcp_f32_e32 v13, v13
	v_mul_f32_e32 v62, v63, v63
	v_mul_f32_e32 v56, v57, v57
	v_pk_add_f32 v[10:11], v[48:49], v[10:11]
	v_mul_f32_e32 v64, v65, v65
	v_mul_f32_e32 v20, v21, v21
	v_pk_add_f32 v[8:9], v[10:11], v[8:9]
	v_pk_add_f32 v[10:11], v[62:63], v[56:57]
	v_pk_mul_f32 v[14:15], v[4:5], v[4:5]
	v_pk_add_f32 v[8:9], v[10:11], v[8:9]
	v_pk_add_f32 v[10:11], v[64:65], v[20:21]
	v_pk_mul_f32 v[14:15], v[14:15], s[64:65] op_sel_hi:[1,0]
	v_pk_add_f32 v[8:9], v[10:11], v[8:9]
	v_pk_fma_f32 v[10:11], v[12:13], s[42:43], v[18:19] op_sel_hi:[1,0,0]
	v_exp_f32_e32 v14, v14
	v_pk_fma_f32 v[10:11], v[12:13], v[10:11], s[48:49] op_sel_hi:[1,1,0]
	v_exp_f32_e32 v15, v15
	v_pk_fma_f32 v[10:11], v[12:13], v[10:11], s[50:51] op_sel_hi:[1,1,0]
	v_pk_fma_f32 v[10:11], v[12:13], v[10:11], s[56:57] op_sel_hi:[1,1,0]
	s_waitcnt vmcnt(0)
	v_lshlrev_b32_e32 v24, 16, v50
	v_pk_mul_f32 v[10:11], v[12:13], v[10:11]
	v_and_b32_e32 v25, 0xffff0000, v50
	v_pk_mul_f32 v[10:11], v[14:15], v[10:11]
	v_and_b32_e32 v27, 0x7fffffff, v25
	v_max_f32_e32 v95, 0, v4
	v_fma_f32 v15, -|v4|, v10, v95
	v_max_f32_e32 v96, 0, v5
	v_fma_f32 v5, -|v5|, v11, v96
	v_and_b32_e32 v26, 0x7fffffff, v24
	v_lshlrev_b32_e32 v10, 16, v6
	v_and_b32_e32 v12, 0x7fffffff, v10
	v_and_b32_e32 v11, 0xffff0000, v6
	v_and_b32_e32 v13, 0x7fffffff, v11
	v_pk_fma_f32 v[12:13], v[12:13], s[40:41], 1.0 op_sel_hi:[1,0,0]
	v_mul_f32_e32 v14, v15, v15
	v_rcp_f32_e32 v12, v12
	v_rcp_f32_e32 v13, v13
	v_mul_f32_e32 v4, v5, v5
	v_pk_mul_f32 v[20:21], v[10:11], v[10:11]
	v_pk_add_f32 v[4:5], v[14:15], v[4:5]
	v_pk_fma_f32 v[14:15], v[12:13], s[42:43], v[18:19] op_sel_hi:[1,0,0]
	v_pk_mul_f32 v[20:21], v[20:21], s[64:65] op_sel_hi:[1,0]
	v_pk_fma_f32 v[14:15], v[12:13], v[14:15], s[48:49] op_sel_hi:[1,1,0]
	v_exp_f32_e32 v20, v20
	v_exp_f32_e32 v21, v21
	v_pk_fma_f32 v[14:15], v[12:13], v[14:15], s[50:51] op_sel_hi:[1,1,0]
	v_lshlrev_b32_e32 v6, 16, v7
	v_and_b32_e32 v7, 0xffff0000, v7
	v_pk_fma_f32 v[14:15], v[12:13], v[14:15], s[56:57] op_sel_hi:[1,1,0]
	v_pk_mul_f32 v[12:13], v[12:13], v[14:15]
	v_fma_f32 v22, |v6|, s40, 1.0
	v_fma_f32 v23, |v7|, s40, 1.0
	v_pk_mul_f32 v[12:13], v[20:21], v[12:13]
	v_rcp_f32_e32 v22, v22
	v_rcp_f32_e32 v23, v23
	v_max_f32_e32 v97, 0, v10
	v_fma_f32 v21, -|v10|, v12, v97
	v_max_f32_e32 v98, 0, v11
	v_fma_f32 v11, -|v11|, v13, v98
	v_pk_fma_f32 v[26:27], v[26:27], s[40:41], 1.0 op_sel_hi:[1,0,0]
	v_lshlrev_b32_e32 v28, 16, v51
	v_rcp_f32_e32 v26, v26
	v_rcp_f32_e32 v27, v27
	v_pk_mul_f32 v[14:15], v[6:7], v[6:7]
	v_pk_fma_f32 v[12:13], v[22:23], s[42:43], v[18:19] op_sel_hi:[1,0,0]
	v_pk_mul_f32 v[14:15], v[14:15], s[64:65] op_sel_hi:[1,0]
	v_pk_fma_f32 v[12:13], v[22:23], v[12:13], s[48:49] op_sel_hi:[1,1,0]
	v_exp_f32_e32 v14, v14
	v_exp_f32_e32 v15, v15
	v_pk_fma_f32 v[12:13], v[22:23], v[12:13], s[50:51] op_sel_hi:[1,1,0]
	v_pk_fma_f32 v[12:13], v[22:23], v[12:13], s[56:57] op_sel_hi:[1,1,0]
	v_and_b32_e32 v29, 0xffff0000, v51
	v_pk_mul_f32 v[12:13], v[22:23], v[12:13]
	v_pk_mul_f32 v[12:13], v[14:15], v[12:13]
	v_max_f32_e32 v99, 0, v6
	v_fma_f32 v23, -|v6|, v12, v99
	v_max_f32_e32 v100, 0, v7
	v_fma_f32 v7, -|v7|, v13, v100
	v_fma_f32 v30, |v28|, s40, 1.0
	v_fma_f32 v31, |v29|, s40, 1.0
	v_rcp_f32_e32 v30, v30
	v_rcp_f32_e32 v31, v31
	v_pk_mul_f32 v[14:15], v[24:25], v[24:25]
	v_pk_fma_f32 v[12:13], v[26:27], s[42:43], v[18:19] op_sel_hi:[1,0,0]
	v_pk_mul_f32 v[14:15], v[14:15], s[64:65] op_sel_hi:[1,0]
	v_pk_fma_f32 v[12:13], v[26:27], v[12:13], s[48:49] op_sel_hi:[1,1,0]
	v_exp_f32_e32 v14, v14
	v_exp_f32_e32 v15, v15
	v_pk_fma_f32 v[12:13], v[26:27], v[12:13], s[50:51] op_sel_hi:[1,1,0]
	v_pk_fma_f32 v[12:13], v[26:27], v[12:13], s[56:57] op_sel_hi:[1,1,0]
	v_lshlrev_b32_e32 v32, 16, v52
	v_pk_mul_f32 v[12:13], v[26:27], v[12:13]
	v_and_b32_e32 v33, 0xffff0000, v52
	v_pk_mul_f32 v[12:13], v[14:15], v[12:13]
	v_max_f32_e32 v104, 0, v24
	v_fma_f32 v27, -|v24|, v12, v104
	v_max_f32_e32 v105, 0, v25
	v_fma_f32 v13, -|v25|, v13, v105
	v_pk_mul_f32 v[24:25], v[28:29], v[28:29]
	v_fma_f32 v34, |v32|, s40, 1.0
	v_fma_f32 v35, |v33|, s40, 1.0
	v_pk_fma_f32 v[14:15], v[30:31], s[42:43], v[18:19] op_sel_hi:[1,0,0]
	v_pk_mul_f32 v[24:25], v[24:25], s[64:65] op_sel_hi:[1,0]
	v_pk_fma_f32 v[14:15], v[30:31], v[14:15], s[48:49] op_sel_hi:[1,1,0]
	v_exp_f32_e32 v24, v24
	v_exp_f32_e32 v25, v25
	v_pk_fma_f32 v[14:15], v[30:31], v[14:15], s[50:51] op_sel_hi:[1,1,0]
	v_rcp_f32_e32 v34, v34
	v_pk_fma_f32 v[14:15], v[30:31], v[14:15], s[56:57] op_sel_hi:[1,1,0]
	v_rcp_f32_e32 v35, v35
	v_pk_mul_f32 v[14:15], v[30:31], v[14:15]
	v_pk_mul_f32 v[14:15], v[24:25], v[14:15]
	v_lshlrev_b32_e32 v36, 16, v53
	v_max_f32_e32 v106, 0, v28
	v_fma_f32 v31, -|v28|, v14, v106
	v_max_f32_e32 v107, 0, v29
	v_fma_f32 v15, -|v29|, v15, v107
	v_and_b32_e32 v37, 0xffff0000, v53
	v_pk_mul_f32 v[28:29], v[32:33], v[32:33]
	v_pk_fma_f32 v[24:25], v[34:35], s[42:43], v[18:19] op_sel_hi:[1,0,0]
	v_pk_mul_f32 v[28:29], v[28:29], s[64:65] op_sel_hi:[1,0]
	v_pk_fma_f32 v[24:25], v[34:35], v[24:25], s[48:49] op_sel_hi:[1,1,0]
	v_exp_f32_e32 v28, v28
	v_exp_f32_e32 v29, v29
	v_pk_fma_f32 v[24:25], v[34:35], v[24:25], s[50:51] op_sel_hi:[1,1,0]
	v_pk_fma_f32 v[24:25], v[34:35], v[24:25], s[56:57] op_sel_hi:[1,1,0]
	v_fma_f32 v38, |v36|, s40, 1.0
	v_fma_f32 v39, |v37|, s40, 1.0
	v_pk_mul_f32 v[24:25], v[34:35], v[24:25]
	v_rcp_f32_e32 v38, v38
	v_pk_mul_f32 v[24:25], v[28:29], v[24:25]
	v_rcp_f32_e32 v39, v39
	v_max_f32_e32 v108, 0, v32
	v_fma_f32 v35, -|v32|, v24, v108
	v_max_f32_e32 v109, 0, v33
	v_fma_f32 v25, -|v33|, v25, v109
	v_pk_fma_f32 v[18:19], v[38:39], s[42:43], v[18:19] op_sel_hi:[1,0,0]
	v_mul_f32_e32 v20, v21, v21
	v_pk_fma_f32 v[18:19], v[38:39], v[18:19], s[48:49] op_sel_hi:[1,1,0]
	v_mul_f32_e32 v10, v11, v11
	v_pk_mul_f32 v[28:29], v[36:37], v[36:37]
	v_pk_fma_f32 v[18:19], v[38:39], v[18:19], s[50:51] op_sel_hi:[1,1,0]
	v_pk_mul_f32 v[28:29], v[28:29], s[64:65] op_sel_hi:[1,0]
	v_pk_fma_f32 v[18:19], v[38:39], v[18:19], s[56:57] op_sel_hi:[1,1,0]
	v_exp_f32_e32 v28, v28
	v_exp_f32_e32 v29, v29
	v_pk_mul_f32 v[18:19], v[38:39], v[18:19]
	v_mul_f32_e32 v22, v23, v23
	v_mul_f32_e32 v6, v7, v7
	v_pk_mul_f32 v[18:19], v[28:29], v[18:19]
	v_pk_add_f32 v[4:5], v[4:5], v[8:9]
	v_pk_add_f32 v[8:9], v[20:21], v[10:11]
	v_mul_f32_e32 v26, v27, v27
	v_mul_f32_e32 v12, v13, v13
	v_max_f32_e32 v110, 0, v36
	v_fma_f32 v33, -|v36|, v18, v110
	v_max_f32_e32 v111, 0, v37
	v_fma_f32 v19, -|v37|, v19, v111
	v_pk_add_f32 v[4:5], v[8:9], v[4:5]
	v_pk_add_f32 v[6:7], v[22:23], v[6:7]
	v_mul_f32_e32 v30, v31, v31
	v_mul_f32_e32 v14, v15, v15
	v_pk_add_f32 v[4:5], v[6:7], v[4:5]
	v_pk_add_f32 v[6:7], v[26:27], v[12:13]
	v_mul_f32_e32 v34, v35, v35
	v_mul_f32_e32 v24, v25, v25
	v_pk_add_f32 v[4:5], v[6:7], v[4:5]
	v_pk_add_f32 v[6:7], v[30:31], v[14:15]
	v_mul_f32_e32 v32, v33, v33
	v_mul_f32_e32 v18, v19, v19
	v_cmp_lt_i32_e32 vcc, v167, v161
	v_pk_add_f32 v[4:5], v[6:7], v[4:5]
	v_pk_add_f32 v[6:7], v[34:35], v[24:25]
	v_cndmask_b32_e32 v17, v160, v167, vcc
	v_pk_add_f32 v[4:5], v[6:7], v[4:5]
	v_pk_add_f32 v[6:7], v[32:33], v[18:19]
	v_lshlrev_b32_e32 v56, 2, v17
	v_pk_add_f32 v[4:5], v[6:7], v[4:5]
	ds_bpermute_b32 v7, v56, v5
	ds_bpermute_b32 v6, v56, v4
	v_cmp_lt_i32_e32 vcc, v166, v161
	s_waitcnt lgkmcnt(0)
	v_pk_add_f32 v[4:5], v[4:5], v[6:7]
	v_cndmask_b32_e32 v8, v160, v166, vcc
	v_lshlrev_b32_e32 v57, 2, v8
	ds_bpermute_b32 v7, v57, v5
	ds_bpermute_b32 v6, v57, v4
	v_cmp_lt_i32_e32 vcc, v165, v161
	s_waitcnt lgkmcnt(0)
	v_pk_add_f32 v[4:5], v[4:5], v[6:7]
	v_cndmask_b32_e32 v8, v160, v165, vcc
	v_lshlrev_b32_e32 v58, 2, v8
	ds_bpermute_b32 v7, v58, v5
	ds_bpermute_b32 v6, v58, v4
	v_cmp_lt_i32_e32 vcc, v164, v161
	s_waitcnt lgkmcnt(0)
	v_pk_add_f32 v[4:5], v[4:5], v[6:7]
	v_cndmask_b32_e32 v6, v160, v164, vcc
	v_lshlrev_b32_e32 v59, 2, v6
	ds_bpermute_b32 v7, v59, v5
	ds_bpermute_b32 v6, v59, v4
	v_cmp_eq_u32_e32 vcc, 0, v54
	s_and_saveexec_b64 s[8:9], vcc
	s_cbranch_execz .LBB0_445
	s_waitcnt lgkmcnt(0)
	v_pk_add_f32 v[4:5], v[4:5], v[6:7]
	s_nop 0
	v_pk_mul_f32 v[4:5], v[4:5], s[66:67] op_sel_hi:[1,0]
	s_nop 0
	v_fma_f32 v4, -v5, v5, v4
	v_max_f32_e32 v4, 0, v4
	v_add_f32_e32 v4, 0x358637bd, v4
	v_mul_f32_e32 v6, 0x4b800000, v4
	v_cmp_gt_f32_e64 s[0:1], s36, v4
	s_nop 1
	v_cndmask_b32_e64 v4, v4, v6, s[0:1]
	v_rsq_f32_e32 v4, v4
	v_lshl_add_u32 v6, v16, 2, 0
	v_add_u32_e32 v7, 0x11000, v6
	ds_write_b32 v7, v5
	v_mul_f32_e32 v5, 0x45800000, v4
	v_cndmask_b32_e64 v4, v4, v5, s[0:1]
	v_add_u32_e32 v5, 0x11200, v6
	ds_write_b32 v5, v4
.LBB0_445:
	s_or_b64 exec, exec, s[8:9]
	v_or_b32_e32 v20, 4, v16
	v_ashrrev_i32_e32 v21, 31, v20
	v_lshl_add_u64 v[4:5], s[6:7], 0, v[20:21]
	s_waitcnt lgkmcnt(0)
	v_lshlrev_b32_e32 v6, 3, v54
	v_lshlrev_b64 v[4:5], 11, v[4:5]
	v_lshl_add_u64 v[4:5], s[4:5], 0, v[4:5]
	v_lshlrev_b32_e32 v18, 1, v6
	v_mov_b32_e32 v19, v2
	v_lshl_add_u64 v[24:25], v[4:5], 0, v[18:19]
	global_load_dwordx4 v[8:11], v[24:25], off
	global_load_dwordx4 v[4:7], v[24:25], off offset:256
	v_mov_b64_e32 v[22:23], s[44:45]
	v_mov_b32_e32 v13, v2
	s_waitcnt vmcnt(1)
	v_lshlrev_b32_e32 v28, 16, v10
	v_and_b32_e32 v29, 0xffff0000, v10
	v_and_b32_e32 v15, 0xffff0000, v8
	v_and_b32_e32 v27, 0xffff0000, v9
	v_lshlrev_b32_e32 v26, 16, v9
	v_lshlrev_b32_e32 v14, 16, v8
	v_lshlrev_b32_e32 v8, 16, v11
	v_and_b32_e32 v9, 0xffff0000, v11
	v_fma_f32 v10, |v28|, s40, 1.0
	v_fma_f32 v11, |v29|, s40, 1.0
	v_fma_f32 v32, |v14|, s40, 1.0
	v_fma_f32 v33, |v15|, s40, 1.0
	v_rcp_f32_e32 v10, v10
	v_rcp_f32_e32 v11, v11
	v_fma_f32 v36, |v26|, s40, 1.0
	v_fma_f32 v37, |v27|, s40, 1.0
	v_rcp_f32_e32 v32, v32
	v_rcp_f32_e32 v33, v33
	v_rcp_f32_e32 v36, v36
	v_rcp_f32_e32 v37, v37
	v_pk_mul_f32 v[30:31], v[28:29], v[28:29]
	v_pk_mul_f32 v[34:35], v[14:15], v[14:15]
	v_pk_mul_f32 v[30:31], v[30:31], s[64:65] op_sel_hi:[1,0]
	v_pk_fma_f32 v[44:45], v[10:11], s[42:43], v[22:23] op_sel_hi:[1,0,0]
	v_pk_mul_f32 v[38:39], v[26:27], v[26:27]
	v_pk_mul_f32 v[34:35], v[34:35], s[64:65] op_sel_hi:[1,0]
	v_exp_f32_e32 v30, v30
	v_exp_f32_e32 v31, v31
	v_pk_fma_f32 v[46:47], v[32:33], s[42:43], v[22:23] op_sel_hi:[1,0,0]
	v_pk_fma_f32 v[44:45], v[10:11], v[44:45], s[48:49] op_sel_hi:[1,1,0]
	v_pk_mul_f32 v[38:39], v[38:39], s[64:65] op_sel_hi:[1,0]
	v_exp_f32_e32 v34, v34
	v_exp_f32_e32 v35, v35
	v_pk_fma_f32 v[48:49], v[36:37], s[42:43], v[22:23] op_sel_hi:[1,0,0]
	v_pk_fma_f32 v[46:47], v[32:33], v[46:47], s[48:49] op_sel_hi:[1,1,0]
	v_pk_fma_f32 v[44:45], v[10:11], v[44:45], s[50:51] op_sel_hi:[1,1,0]
	v_exp_f32_e32 v38, v38
	v_exp_f32_e32 v39, v39
	v_pk_fma_f32 v[48:49], v[36:37], v[48:49], s[48:49] op_sel_hi:[1,1,0]
	v_pk_fma_f32 v[46:47], v[32:33], v[46:47], s[50:51] op_sel_hi:[1,1,0]
	v_pk_fma_f32 v[44:45], v[10:11], v[44:45], s[56:57] op_sel_hi:[1,1,0]
	v_pk_fma_f32 v[48:49], v[36:37], v[48:49], s[50:51] op_sel_hi:[1,1,0]
	v_pk_fma_f32 v[46:47], v[32:33], v[46:47], s[56:57] op_sel_hi:[1,1,0]
	v_pk_mul_f32 v[10:11], v[10:11], v[44:45]
	v_pk_fma_f32 v[48:49], v[36:37], v[48:49], s[56:57] op_sel_hi:[1,1,0]
	v_pk_mul_f32 v[32:33], v[32:33], v[46:47]
	v_pk_mul_f32 v[10:11], v[30:31], v[10:11]
	v_pk_mul_f32 v[36:37], v[36:37], v[48:49]
	v_pk_mul_f32 v[30:31], v[34:35], v[32:33]
	v_max_f32_e32 v112, 0, v28
	v_fma_f32 v45, -|v28|, v10, v112
	v_max_f32_e32 v113, 0, v29
	v_fma_f32 v11, -|v29|, v11, v113
	v_pk_mul_f32 v[32:33], v[38:39], v[36:37]
	v_max_f32_e32 v114, 0, v26
	v_fma_f32 v29, -|v26|, v32, v114
	v_max_f32_e32 v115, 0, v27
	v_fma_f32 v27, -|v27|, v33, v115
	v_max_f32_e32 v116, 0, v14
	v_fma_f32 v28, -|v14|, v30, v116
	v_max_f32_e32 v117, 0, v15
	v_fma_f32 v15, -|v15|, v31, v117
	v_fma_f32 v40, |v8|, s40, 1.0
	v_fma_f32 v41, |v9|, s40, 1.0
	v_mul_f32_e32 v30, v28, v28
	v_mov_b32_e32 v14, v29
	v_mov_b32_e32 v31, v29
	v_mul_f32_e32 v26, v15, v15
	v_rcp_f32_e32 v40, v40
	v_rcp_f32_e32 v41, v41
	v_mul_f32_e32 v12, v27, v27
	v_pk_add_f32 v[26:27], v[30:31], v[26:27]
	v_pk_mul_f32 v[30:31], v[28:29], v[14:15] op_sel:[1,0] op_sel_hi:[0,1]
	v_pk_add_f32 v[14:15], v[28:29], v[14:15] op_sel:[1,0] op_sel_hi:[0,1]
	v_mov_b32_e32 v31, v15
	v_mul_f32_e32 v44, v45, v45
	v_mul_f32_e32 v10, v11, v11
	v_pk_add_f32 v[12:13], v[30:31], v[12:13]
	v_pk_mul_f32 v[42:43], v[8:9], v[8:9]
	v_pk_add_f32 v[10:11], v[44:45], v[10:11]
	v_pk_add_f32 v[12:13], v[26:27], v[12:13]
	v_pk_fma_f32 v[50:51], v[40:41], s[42:43], v[22:23] op_sel_hi:[1,0,0]
	v_pk_add_f32 v[26:27], v[10:11], v[12:13]
	v_pk_mul_f32 v[10:11], v[42:43], s[64:65] op_sel_hi:[1,0]
	v_pk_fma_f32 v[50:51], v[40:41], v[50:51], s[48:49] op_sel_hi:[1,1,0]
	v_exp_f32_e32 v10, v10
	v_exp_f32_e32 v11, v11
	v_pk_fma_f32 v[12:13], v[40:41], v[50:51], s[50:51] op_sel_hi:[1,1,0]
	v_pk_fma_f32 v[12:13], v[40:41], v[12:13], s[56:57] op_sel_hi:[1,1,0]
	s_nop 0
	v_pk_mul_f32 v[12:13], v[40:41], v[12:13]
	s_waitcnt vmcnt(0)
	v_lshlrev_b32_e32 v40, 16, v6
	v_pk_mul_f32 v[10:11], v[10:11], v[12:13]
	v_and_b32_e32 v41, 0xffff0000, v6
	v_max_f32_e32 v80, 0, v8
	v_fma_f32 v15, -|v8|, v10, v80
	v_max_f32_e32 v81, 0, v9
	v_fma_f32 v9, -|v9|, v11, v81
	v_and_b32_e32 v37, 0x7fffffff, v41
	v_lshlrev_b32_e32 v12, 16, v4
	v_and_b32_e32 v10, 0x7fffffff, v12
	v_and_b32_e32 v13, 0xffff0000, v4
	v_and_b32_e32 v11, 0x7fffffff, v13
	v_pk_fma_f32 v[10:11], v[10:11], s[40:41], 1.0 op_sel_hi:[1,0,0]
	v_mul_f32_e32 v14, v15, v15
	v_rcp_f32_e32 v10, v10
	v_rcp_f32_e32 v11, v11
	v_mul_f32_e32 v8, v9, v9
	v_pk_add_f32 v[28:29], v[14:15], v[8:9]
	v_pk_mul_f32 v[14:15], v[12:13], v[12:13]
	v_pk_fma_f32 v[8:9], v[10:11], s[42:43], v[22:23] op_sel_hi:[1,0,0]
	v_pk_mul_f32 v[14:15], v[14:15], s[64:65] op_sel_hi:[1,0]
	v_pk_fma_f32 v[8:9], v[10:11], v[8:9], s[48:49] op_sel_hi:[1,1,0]
	v_exp_f32_e32 v14, v14
	v_exp_f32_e32 v15, v15
	v_pk_fma_f32 v[8:9], v[10:11], v[8:9], s[50:51] op_sel_hi:[1,1,0]
	v_lshlrev_b32_e32 v4, 16, v5
	v_pk_fma_f32 v[8:9], v[10:11], v[8:9], s[56:57] op_sel_hi:[1,1,0]
	v_and_b32_e32 v5, 0xffff0000, v5
	v_pk_mul_f32 v[8:9], v[10:11], v[8:9]
	v_pk_mul_f32 v[14:15], v[14:15], v[8:9]
	global_load_dwordx4 v[8:11], v[24:25], off offset:512
	v_fma_f32 v34, |v4|, s40, 1.0
	v_fma_f32 v35, |v5|, s40, 1.0
	v_rcp_f32_e32 v34, v34
	v_rcp_f32_e32 v35, v35
	v_max_f32_e32 v82, 0, v12
	v_fma_f32 v31, -|v12|, v14, v82
	v_max_f32_e32 v83, 0, v13
	v_fma_f32 v33, -|v13|, v15, v83
	v_and_b32_e32 v36, 0x7fffffff, v40
	v_pk_fma_f32 v[36:37], v[36:37], s[40:41], 1.0 op_sel_hi:[1,0,0]
	v_pk_fma_f32 v[12:13], v[34:35], s[42:43], v[22:23] op_sel_hi:[1,0,0]
	v_rcp_f32_e32 v38, v36
	v_pk_mul_f32 v[14:15], v[4:5], v[4:5]
	v_pk_fma_f32 v[12:13], v[34:35], v[12:13], s[48:49] op_sel_hi:[1,1,0]
	v_pk_mul_f32 v[14:15], v[14:15], s[64:65] op_sel_hi:[1,0]
	v_pk_fma_f32 v[12:13], v[34:35], v[12:13], s[50:51] op_sel_hi:[1,1,0]
	v_exp_f32_e32 v14, v14
	v_exp_f32_e32 v15, v15
	v_pk_fma_f32 v[12:13], v[34:35], v[12:13], s[56:57] op_sel_hi:[1,1,0]
	v_rcp_f32_e32 v39, v37
	v_pk_mul_f32 v[12:13], v[34:35], v[12:13]
	v_pk_mul_f32 v[12:13], v[14:15], v[12:13]
	v_mul_f32_e32 v30, v31, v31
	v_max_f32_e32 v84, 0, v4
	v_fma_f32 v35, -|v4|, v12, v84
	v_max_f32_e32 v85, 0, v5
	v_fma_f32 v37, -|v5|, v13, v85
	v_mul_f32_e32 v32, v33, v33
	v_pk_fma_f32 v[4:5], v[38:39], s[42:43], v[22:23] op_sel_hi:[1,0,0]
	v_lshlrev_b32_e32 v14, 16, v7
	v_pk_mul_f32 v[12:13], v[40:41], v[40:41]
	v_pk_fma_f32 v[4:5], v[38:39], v[4:5], s[48:49] op_sel_hi:[1,1,0]
	v_pk_mul_f32 v[12:13], v[12:13], s[64:65] op_sel_hi:[1,0]
	v_pk_fma_f32 v[4:5], v[38:39], v[4:5], s[50:51] op_sel_hi:[1,1,0]
	v_exp_f32_e32 v12, v12
	v_exp_f32_e32 v13, v13
	v_and_b32_e32 v15, 0xffff0000, v7
	v_pk_fma_f32 v[4:5], v[38:39], v[4:5], s[56:57] op_sel_hi:[1,1,0]
	v_pk_mul_f32 v[4:5], v[38:39], v[4:5]
	v_fma_f32 v6, |v14|, s40, 1.0
	v_fma_f32 v7, |v15|, s40, 1.0
	v_pk_mul_f32 v[4:5], v[12:13], v[4:5]
	v_rcp_f32_e32 v6, v6
	v_rcp_f32_e32 v7, v7
	v_max_f32_e32 v86, 0, v40
	v_fma_f32 v39, -|v40|, v4, v86
	v_max_f32_e32 v90, 0, v41
	v_fma_f32 v41, -|v41|, v5, v90
	v_mul_f32_e32 v34, v35, v35
	v_mul_f32_e32 v36, v37, v37
	v_pk_add_f32 v[26:27], v[28:29], v[26:27]
	v_pk_add_f32 v[28:29], v[30:31], v[32:33]
	v_pk_mul_f32 v[12:13], v[14:15], v[14:15]
	v_pk_fma_f32 v[4:5], v[6:7], s[42:43], v[22:23] op_sel_hi:[1,0,0]
	v_pk_mul_f32 v[12:13], v[12:13], s[64:65] op_sel_hi:[1,0]
	v_pk_fma_f32 v[4:5], v[6:7], v[4:5], s[48:49] op_sel_hi:[1,1,0]
	v_exp_f32_e32 v12, v12
	v_exp_f32_e32 v13, v13
	v_pk_fma_f32 v[4:5], v[6:7], v[4:5], s[50:51] op_sel_hi:[1,1,0]
	v_pk_fma_f32 v[4:5], v[6:7], v[4:5], s[56:57] op_sel_hi:[1,1,0]
	v_mul_f32_e32 v38, v39, v39
	v_pk_mul_f32 v[4:5], v[6:7], v[4:5]
	v_mul_f32_e32 v40, v41, v41
	v_pk_mul_f32 v[4:5], v[12:13], v[4:5]
	v_pk_add_f32 v[26:27], v[28:29], v[26:27]
	v_max_f32_e32 v91, 0, v14
	v_fma_f32 v43, -|v14|, v4, v91
	v_max_f32_e32 v92, 0, v15
	v_fma_f32 v45, -|v15|, v5, v92
	global_load_dwordx4 v[4:7], v[24:25], off offset:768
	v_pk_add_f32 v[28:29], v[34:35], v[36:37]
	s_waitcnt vmcnt(1)
	v_lshlrev_b32_e32 v48, 16, v8
	v_and_b32_e32 v49, 0xffff0000, v8
	v_fma_f32 v46, |v48|, s40, 1.0
	v_fma_f32 v47, |v49|, s40, 1.0
	v_pk_mul_f32 v[14:15], v[48:49], v[48:49]
	v_rcp_f32_e32 v46, v46
	v_rcp_f32_e32 v47, v47
	v_pk_mul_f32 v[14:15], v[14:15], s[64:65] op_sel_hi:[1,0]
	v_lshlrev_b32_e32 v50, 16, v9
	v_pk_fma_f32 v[12:13], v[46:47], s[42:43], v[22:23] op_sel_hi:[1,0,0]
	v_exp_f32_e32 v14, v14
	v_pk_fma_f32 v[12:13], v[46:47], v[12:13], s[48:49] op_sel_hi:[1,1,0]
	v_exp_f32_e32 v15, v15
	v_and_b32_e32 v51, 0xffff0000, v9
	v_pk_fma_f32 v[12:13], v[46:47], v[12:13], s[50:51] op_sel_hi:[1,1,0]
	v_pk_fma_f32 v[12:13], v[46:47], v[12:13], s[56:57] op_sel_hi:[1,1,0]
	v_fma_f32 v8, |v50|, s40, 1.0
	v_fma_f32 v9, |v51|, s40, 1.0
	v_pk_mul_f32 v[12:13], v[46:47], v[12:13]
	v_rcp_f32_e32 v52, v8
	v_rcp_f32_e32 v53, v9
	v_pk_mul_f32 v[12:13], v[14:15], v[12:13]
	v_max_f32_e32 v93, 0, v48
	v_fma_f32 v47, -|v48|, v12, v93
	v_max_f32_e32 v94, 0, v49
	v_fma_f32 v9, -|v49|, v13, v94
	v_lshlrev_b32_e32 v60, 16, v10
	v_and_b32_e32 v61, 0xffff0000, v10
	v_lshlrev_b32_e32 v10, 16, v11
	v_pk_fma_f32 v[12:13], v[52:53], s[42:43], v[22:23] op_sel_hi:[1,0,0]
	v_pk_mul_f32 v[14:15], v[50:51], v[50:51]
	v_pk_fma_f32 v[12:13], v[52:53], v[12:13], s[48:49] op_sel_hi:[1,1,0]
	v_pk_mul_f32 v[14:15], v[14:15], s[64:65] op_sel_hi:[1,0]
	v_pk_fma_f32 v[12:13], v[52:53], v[12:13], s[50:51] op_sel_hi:[1,1,0]
	v_exp_f32_e32 v14, v14
	v_exp_f32_e32 v15, v15
	v_pk_fma_f32 v[12:13], v[52:53], v[12:13], s[56:57] op_sel_hi:[1,1,0]
	v_pk_mul_f32 v[12:13], v[52:53], v[12:13]
	v_fma_f32 v52, |v60|, s40, 1.0
	v_fma_f32 v53, |v61|, s40, 1.0
	v_pk_mul_f32 v[12:13], v[14:15], v[12:13]
	v_rcp_f32_e32 v52, v52
	v_rcp_f32_e32 v53, v53
	v_max_f32_e32 v95, 0, v50
	v_fma_f32 v49, -|v50|, v12, v95
	v_max_f32_e32 v96, 0, v51
	v_fma_f32 v51, -|v51|, v13, v96
	v_and_b32_e32 v11, 0xffff0000, v11
	v_pk_mul_f32 v[14:15], v[60:61], v[60:61]
	v_pk_fma_f32 v[12:13], v[52:53], s[42:43], v[22:23] op_sel_hi:[1,0,0]
	v_pk_mul_f32 v[14:15], v[14:15], s[64:65] op_sel_hi:[1,0]
	v_pk_fma_f32 v[12:13], v[52:53], v[12:13], s[48:49] op_sel_hi:[1,1,0]
	v_exp_f32_e32 v14, v14
	v_exp_f32_e32 v15, v15
	v_pk_fma_f32 v[12:13], v[52:53], v[12:13], s[50:51] op_sel_hi:[1,1,0]
	v_fma_f32 v62, |v10|, s40, 1.0
	v_fma_f32 v63, |v11|, s40, 1.0
	v_pk_fma_f32 v[12:13], v[52:53], v[12:13], s[56:57] op_sel_hi:[1,1,0]
	v_rcp_f32_e32 v62, v62
	v_pk_mul_f32 v[12:13], v[52:53], v[12:13]
	v_rcp_f32_e32 v63, v63
	v_pk_mul_f32 v[12:13], v[14:15], v[12:13]
	v_max_f32_e32 v97, 0, v60
	v_fma_f32 v53, -|v60|, v12, v97
	v_max_f32_e32 v98, 0, v61
	v_fma_f32 v61, -|v61|, v13, v98
	v_mul_f32_e32 v42, v43, v43
	s_waitcnt vmcnt(0)
	v_lshlrev_b32_e32 v64, 16, v4
	v_and_b32_e32 v65, 0xffff0000, v4
	v_pk_mul_f32 v[14:15], v[10:11], v[10:11]
	v_pk_fma_f32 v[12:13], v[62:63], s[42:43], v[22:23] op_sel_hi:[1,0,0]
	v_pk_mul_f32 v[14:15], v[14:15], s[64:65] op_sel_hi:[1,0]
	v_pk_fma_f32 v[12:13], v[62:63], v[12:13], s[48:49] op_sel_hi:[1,1,0]
	v_exp_f32_e32 v14, v14
	v_exp_f32_e32 v15, v15
	v_pk_fma_f32 v[12:13], v[62:63], v[12:13], s[50:51] op_sel_hi:[1,1,0]
	v_pk_fma_f32 v[12:13], v[62:63], v[12:13], s[56:57] op_sel_hi:[1,1,0]
	v_pk_mul_f32 v[12:13], v[62:63], v[12:13]
	v_fma_f32 v66, |v64|, s40, 1.0
	v_fma_f32 v67, |v65|, s40, 1.0
	v_pk_mul_f32 v[12:13], v[14:15], v[12:13]
	v_rcp_f32_e32 v66, v66
	v_rcp_f32_e32 v67, v67
	v_max_f32_e32 v99, 0, v10
	v_fma_f32 v63, -|v10|, v12, v99
	v_max_f32_e32 v100, 0, v11
	v_fma_f32 v11, -|v11|, v13, v100
	v_lshlrev_b32_e32 v4, 16, v5
	v_and_b32_e32 v5, 0xffff0000, v5
	v_pk_mul_f32 v[14:15], v[64:65], v[64:65]
	v_pk_fma_f32 v[12:13], v[66:67], s[42:43], v[22:23] op_sel_hi:[1,0,0]
	v_pk_mul_f32 v[14:15], v[14:15], s[64:65] op_sel_hi:[1,0]
	v_pk_fma_f32 v[12:13], v[66:67], v[12:13], s[48:49] op_sel_hi:[1,1,0]
	v_exp_f32_e32 v14, v14
	v_exp_f32_e32 v15, v15
	v_pk_fma_f32 v[12:13], v[66:67], v[12:13], s[50:51] op_sel_hi:[1,1,0]
	v_fma_f32 v68, |v4|, s40, 1.0
	v_fma_f32 v69, |v5|, s40, 1.0
	v_pk_fma_f32 v[12:13], v[66:67], v[12:13], s[56:57] op_sel_hi:[1,1,0]
	v_rcp_f32_e32 v68, v68
	v_pk_mul_f32 v[12:13], v[66:67], v[12:13]
	v_rcp_f32_e32 v69, v69
	v_pk_mul_f32 v[12:13], v[14:15], v[12:13]
	v_max_f32_e32 v104, 0, v64
	v_fma_f32 v67, -|v64|, v12, v104
	v_max_f32_e32 v105, 0, v65
	v_fma_f32 v65, -|v65|, v13, v105
	v_mul_f32_e32 v44, v45, v45
	v_pk_add_f32 v[26:27], v[28:29], v[26:27]
	v_pk_add_f32 v[28:29], v[38:39], v[40:41]
	v_pk_fma_f32 v[12:13], v[68:69], s[42:43], v[22:23] op_sel_hi:[1,0,0]
	v_pk_mul_f32 v[14:15], v[4:5], v[4:5]
	v_pk_fma_f32 v[12:13], v[68:69], v[12:13], s[48:49] op_sel_hi:[1,1,0]
	v_pk_mul_f32 v[14:15], v[14:15], s[64:65] op_sel_hi:[1,0]
	v_pk_fma_f32 v[12:13], v[68:69], v[12:13], s[50:51] op_sel_hi:[1,1,0]
	v_exp_f32_e32 v70, v14
	v_exp_f32_e32 v71, v15
	v_pk_fma_f32 v[72:73], v[68:69], v[12:13], s[56:57] op_sel_hi:[1,1,0]
	global_load_dwordx4 v[12:15], v[24:25], off offset:1024
	v_mul_f32_e32 v46, v47, v47
	v_mul_f32_e32 v8, v9, v9
	v_pk_add_f32 v[26:27], v[28:29], v[26:27]
	v_pk_add_f32 v[28:29], v[42:43], v[44:45]
	v_mul_f32_e32 v48, v49, v49
	v_mul_f32_e32 v50, v51, v51
	v_pk_add_f32 v[26:27], v[28:29], v[26:27]
	v_pk_add_f32 v[8:9], v[46:47], v[8:9]
	v_mul_f32_e32 v52, v53, v53
	v_mul_f32_e32 v60, v61, v61
	v_pk_mul_f32 v[68:69], v[68:69], v[72:73]
	v_pk_add_f32 v[8:9], v[8:9], v[26:27]
	v_pk_add_f32 v[26:27], v[48:49], v[50:51]
	v_pk_mul_f32 v[68:69], v[70:71], v[68:69]
	v_pk_add_f32 v[8:9], v[26:27], v[8:9]
	v_pk_add_f32 v[26:27], v[52:53], v[60:61]
	v_lshlrev_b32_e32 v28, 16, v6
	v_and_b32_e32 v29, 0xffff0000, v6
	v_max_f32_e32 v106, 0, v4
	v_fma_f32 v73, -|v4|, v68, v106
	v_max_f32_e32 v107, 0, v5
	v_fma_f32 v5, -|v5|, v69, v107
	v_pk_add_f32 v[8:9], v[26:27], v[8:9]
	v_mul_f32_e32 v62, v63, v63
	v_mul_f32_e32 v10, v11, v11
	v_fma_f32 v26, |v28|, s40, 1.0
	v_fma_f32 v27, |v29|, s40, 1.0
	v_mul_f32_e32 v66, v67, v67
	v_mul_f32_e32 v64, v65, v65
	v_pk_add_f32 v[10:11], v[62:63], v[10:11]
	v_rcp_f32_e32 v30, v26
	v_rcp_f32_e32 v31, v27
	v_mul_f32_e32 v72, v73, v73
	v_mul_f32_e32 v4, v5, v5
	v_pk_add_f32 v[8:9], v[10:11], v[8:9]
	v_pk_add_f32 v[10:11], v[66:67], v[64:65]
	v_pk_add_f32 v[4:5], v[72:73], v[4:5]
	v_pk_add_f32 v[8:9], v[10:11], v[8:9]
	v_cmp_gt_f32_e64 s[0:1], 0, v28
	v_pk_add_f32 v[26:27], v[4:5], v[8:9]
	v_pk_mul_f32 v[8:9], v[28:29], v[28:29]
	v_pk_fma_f32 v[4:5], v[30:31], s[42:43], v[22:23] op_sel_hi:[1,0,0]
	v_pk_mul_f32 v[8:9], v[8:9], s[64:65] op_sel_hi:[1,0]
	v_pk_fma_f32 v[4:5], v[30:31], v[4:5], s[48:49] op_sel_hi:[1,1,0]
	v_exp_f32_e32 v8, v8
	v_exp_f32_e32 v9, v9
	v_pk_fma_f32 v[4:5], v[30:31], v[4:5], s[50:51] op_sel_hi:[1,1,0]
	v_lshlrev_b32_e32 v6, 16, v7
	v_pk_fma_f32 v[4:5], v[30:31], v[4:5], s[56:57] op_sel_hi:[1,1,0]
	v_and_b32_e32 v7, 0xffff0000, v7
	v_pk_mul_f32 v[4:5], v[30:31], v[4:5]
	s_nop 0
	v_pk_mul_f32 v[4:5], v[8:9], v[4:5]
	s_nop 0
	v_pk_mul_f32 v[8:9], v[28:29], v[4:5]
	v_pk_fma_f32 v[4:5], v[28:29], v[4:5], v[28:29] neg_lo:[1,0,0] neg_hi:[1,0,0]
	s_nop 0
	v_cndmask_b32_e64 v11, v4, v8, s[0:1]
	v_cmp_gt_f32_e64 s[0:1], 0, v29
	v_and_b32_e32 v8, 0x7fffffff, v6
	v_mul_f32_e32 v10, v11, v11
	v_cndmask_b32_e64 v5, v5, v9, s[0:1]
	v_and_b32_e32 v9, 0x7fffffff, v7
	v_pk_fma_f32 v[8:9], v[8:9], s[40:41], 1.0 op_sel_hi:[1,0,0]
	v_mul_f32_e32 v4, v5, v5
	v_rcp_f32_e32 v8, v8
	v_rcp_f32_e32 v9, v9
	v_pk_add_f32 v[28:29], v[10:11], v[4:5]
	v_pk_mul_f32 v[10:11], v[6:7], v[6:7]
	v_cmp_gt_f32_e64 s[0:1], 0, v6
	v_pk_fma_f32 v[4:5], v[8:9], s[42:43], v[22:23] op_sel_hi:[1,0,0]
	v_pk_mul_f32 v[10:11], v[10:11], s[64:65] op_sel_hi:[1,0]
	v_pk_fma_f32 v[4:5], v[8:9], v[4:5], s[48:49] op_sel_hi:[1,1,0]
	v_exp_f32_e32 v10, v10
	v_exp_f32_e32 v11, v11
	v_pk_fma_f32 v[4:5], v[8:9], v[4:5], s[50:51] op_sel_hi:[1,1,0]
	v_pk_add_f32 v[26:27], v[28:29], v[26:27]
	v_pk_fma_f32 v[4:5], v[8:9], v[4:5], s[56:57] op_sel_hi:[1,1,0]
	s_nop 0
	v_pk_mul_f32 v[4:5], v[8:9], v[4:5]
	s_nop 0
	v_pk_mul_f32 v[4:5], v[10:11], v[4:5]
	global_load_dwordx4 v[8:11], v[24:25], off offset:1280
	s_waitcnt vmcnt(1)
	v_lshlrev_b32_e32 v36, 16, v12
	v_and_b32_e32 v37, 0xffff0000, v12
	v_fma_f32 v34, |v36|, s40, 1.0
	v_fma_f32 v35, |v37|, s40, 1.0
	v_pk_mul_f32 v[32:33], v[6:7], v[4:5]
	v_rcp_f32_e32 v34, v34
	v_rcp_f32_e32 v35, v35
	v_pk_fma_f32 v[4:5], v[6:7], v[4:5], v[6:7] neg_lo:[1,0,0] neg_hi:[1,0,0]
	v_lshlrev_b32_e32 v38, 16, v13
	v_cndmask_b32_e64 v31, v4, v32, s[0:1]
	v_cmp_gt_f32_e64 s[0:1], 0, v7
	v_pk_mul_f32 v[6:7], v[36:37], v[36:37]
	v_and_b32_e32 v39, 0xffff0000, v13
	v_cndmask_b32_e64 v33, v5, v33, s[0:1]
	v_pk_fma_f32 v[4:5], v[34:35], s[42:43], v[22:23] op_sel_hi:[1,0,0]
	v_pk_mul_f32 v[6:7], v[6:7], s[64:65] op_sel_hi:[1,0]
	v_pk_fma_f32 v[4:5], v[34:35], v[4:5], s[48:49] op_sel_hi:[1,1,0]
	v_exp_f32_e32 v6, v6
	v_exp_f32_e32 v7, v7
	v_pk_fma_f32 v[4:5], v[34:35], v[4:5], s[50:51] op_sel_hi:[1,1,0]
	v_pk_fma_f32 v[4:5], v[34:35], v[4:5], s[56:57] op_sel_hi:[1,1,0]
	v_fma_f32 v12, |v38|, s40, 1.0
	v_fma_f32 v13, |v39|, s40, 1.0
	v_pk_mul_f32 v[4:5], v[34:35], v[4:5]
	v_rcp_f32_e32 v40, v12
	v_rcp_f32_e32 v41, v13
	v_pk_mul_f32 v[4:5], v[6:7], v[4:5]
	v_max_f32_e32 v108, 0, v36
	v_fma_f32 v35, -|v36|, v4, v108
	v_max_f32_e32 v109, 0, v37
	v_fma_f32 v13, -|v37|, v5, v109
	v_lshlrev_b32_e32 v42, 16, v14
	v_and_b32_e32 v43, 0xffff0000, v14
	v_lshlrev_b32_e32 v44, 16, v15
	v_pk_fma_f32 v[4:5], v[40:41], s[42:43], v[22:23] op_sel_hi:[1,0,0]
	v_pk_mul_f32 v[6:7], v[38:39], v[38:39]
	v_pk_fma_f32 v[4:5], v[40:41], v[4:5], s[48:49] op_sel_hi:[1,1,0]
	v_pk_mul_f32 v[6:7], v[6:7], s[64:65] op_sel_hi:[1,0]
	v_pk_fma_f32 v[4:5], v[40:41], v[4:5], s[50:51] op_sel_hi:[1,1,0]
	v_exp_f32_e32 v6, v6
	v_exp_f32_e32 v7, v7
	v_pk_fma_f32 v[4:5], v[40:41], v[4:5], s[56:57] op_sel_hi:[1,1,0]
	v_pk_mul_f32 v[4:5], v[40:41], v[4:5]
	v_fma_f32 v40, |v42|, s40, 1.0
	v_fma_f32 v41, |v43|, s40, 1.0
	v_pk_mul_f32 v[4:5], v[6:7], v[4:5]
	v_rcp_f32_e32 v40, v40
	v_rcp_f32_e32 v41, v41
	v_max_f32_e32 v110, 0, v38
	v_fma_f32 v37, -|v38|, v4, v110
	v_max_f32_e32 v111, 0, v39
	v_fma_f32 v39, -|v39|, v5, v111
	v_and_b32_e32 v45, 0xffff0000, v15
	v_pk_mul_f32 v[6:7], v[42:43], v[42:43]
	v_pk_fma_f32 v[4:5], v[40:41], s[42:43], v[22:23] op_sel_hi:[1,0,0]
	v_pk_mul_f32 v[6:7], v[6:7], s[64:65] op_sel_hi:[1,0]
	v_pk_fma_f32 v[4:5], v[40:41], v[4:5], s[48:49] op_sel_hi:[1,1,0]
	v_exp_f32_e32 v6, v6
	v_exp_f32_e32 v7, v7
	v_pk_fma_f32 v[4:5], v[40:41], v[4:5], s[50:51] op_sel_hi:[1,1,0]
	v_fma_f32 v14, |v44|, s40, 1.0
	v_fma_f32 v15, |v45|, s40, 1.0
	v_pk_fma_f32 v[4:5], v[40:41], v[4:5], s[56:57] op_sel_hi:[1,1,0]
	v_rcp_f32_e32 v46, v14
	v_pk_mul_f32 v[4:5], v[40:41], v[4:5]
	v_rcp_f32_e32 v47, v15
	v_pk_mul_f32 v[4:5], v[6:7], v[4:5]
	v_max_f32_e32 v112, 0, v42
	v_fma_f32 v41, -|v42|, v4, v112
	v_max_f32_e32 v113, 0, v43
	v_fma_f32 v15, -|v43|, v5, v113
	v_mul_f32_e32 v30, v31, v31
	s_waitcnt vmcnt(0)
	v_lshlrev_b32_e32 v48, 16, v8
	v_and_b32_e32 v49, 0xffff0000, v8
	v_pk_fma_f32 v[4:5], v[46:47], s[42:43], v[22:23] op_sel_hi:[1,0,0]
	v_pk_mul_f32 v[6:7], v[44:45], v[44:45]
	v_pk_fma_f32 v[4:5], v[46:47], v[4:5], s[48:49] op_sel_hi:[1,1,0]
	v_pk_mul_f32 v[6:7], v[6:7], s[64:65] op_sel_hi:[1,0]
	v_pk_fma_f32 v[4:5], v[46:47], v[4:5], s[50:51] op_sel_hi:[1,1,0]
	v_exp_f32_e32 v6, v6
	v_exp_f32_e32 v7, v7
	v_pk_fma_f32 v[4:5], v[46:47], v[4:5], s[56:57] op_sel_hi:[1,1,0]
	v_pk_mul_f32 v[4:5], v[46:47], v[4:5]
	v_fma_f32 v46, |v48|, s40, 1.0
	v_fma_f32 v47, |v49|, s40, 1.0
	v_pk_mul_f32 v[4:5], v[6:7], v[4:5]
	v_rcp_f32_e32 v46, v46
	v_rcp_f32_e32 v47, v47
	v_max_f32_e32 v114, 0, v44
	v_fma_f32 v43, -|v44|, v4, v114
	v_max_f32_e32 v115, 0, v45
	v_fma_f32 v45, -|v45|, v5, v115
	v_lshlrev_b32_e32 v60, 16, v9
	v_and_b32_e32 v61, 0xffff0000, v9
	v_pk_mul_f32 v[6:7], v[48:49], v[48:49]
	v_pk_fma_f32 v[4:5], v[46:47], s[42:43], v[22:23] op_sel_hi:[1,0,0]
	v_pk_mul_f32 v[6:7], v[6:7], s[64:65] op_sel_hi:[1,0]
	v_pk_fma_f32 v[4:5], v[46:47], v[4:5], s[48:49] op_sel_hi:[1,1,0]
	v_exp_f32_e32 v6, v6
	v_exp_f32_e32 v7, v7
	v_pk_fma_f32 v[4:5], v[46:47], v[4:5], s[50:51] op_sel_hi:[1,1,0]
	v_pk_fma_f32 v[4:5], v[46:47], v[4:5], s[56:57] op_sel_hi:[1,1,0]
	v_fma_f32 v8, |v60|, s40, 1.0
	v_fma_f32 v9, |v61|, s40, 1.0
	v_pk_mul_f32 v[4:5], v[46:47], v[4:5]
	v_rcp_f32_e32 v62, v8
	v_pk_mul_f32 v[46:47], v[6:7], v[4:5]
	global_load_dwordx4 v[4:7], v[24:25], off offset:1536
	v_rcp_f32_e32 v63, v9
	v_max_f32_e32 v117, 0, v49
	v_fma_f32 v9, -|v49|, v47, v117
	v_max_f32_e32 v116, 0, v48
	v_fma_f32 v47, -|v48|, v46, v116
	v_lshlrev_b32_e32 v66, 16, v11
	v_and_b32_e32 v67, 0xffff0000, v11
	v_pk_fma_f32 v[48:49], v[62:63], s[42:43], v[22:23] op_sel_hi:[1,0,0]
	v_and_b32_e32 v11, 0x7fffffff, v67
	v_pk_fma_f32 v[48:49], v[62:63], v[48:49], s[48:49] op_sel_hi:[1,1,0]
	v_pk_mul_f32 v[50:51], v[60:61], v[60:61]
	v_pk_fma_f32 v[48:49], v[62:63], v[48:49], s[50:51] op_sel_hi:[1,1,0]
	v_pk_mul_f32 v[50:51], v[50:51], s[64:65] op_sel_hi:[1,0]
	v_pk_fma_f32 v[48:49], v[62:63], v[48:49], s[56:57] op_sel_hi:[1,1,0]
	v_exp_f32_e32 v50, v50
	v_exp_f32_e32 v51, v51
	v_pk_mul_f32 v[48:49], v[62:63], v[48:49]
	v_lshlrev_b32_e32 v62, 16, v10
	v_and_b32_e32 v63, 0xffff0000, v10
	v_fma_f32 v64, |v62|, s40, 1.0
	v_fma_f32 v65, |v63|, s40, 1.0
	v_pk_mul_f32 v[48:49], v[50:51], v[48:49]
	v_rcp_f32_e32 v64, v64
	v_rcp_f32_e32 v65, v65
	v_max_f32_e32 v81, 0, v61
	v_fma_f32 v51, -|v61|, v49, v81
	v_max_f32_e32 v80, 0, v60
	v_fma_f32 v49, -|v60|, v48, v80
	v_and_b32_e32 v10, 0x7fffffff, v66
	v_pk_fma_f32 v[10:11], v[10:11], s[40:41], 1.0 op_sel_hi:[1,0,0]
	v_pk_mul_f32 v[60:61], v[62:63], v[62:63]
	v_rcp_f32_e32 v68, v10
	v_pk_fma_f32 v[52:53], v[64:65], s[42:43], v[22:23] op_sel_hi:[1,0,0]
	v_pk_mul_f32 v[60:61], v[60:61], s[64:65] op_sel_hi:[1,0]
	v_pk_fma_f32 v[52:53], v[64:65], v[52:53], s[48:49] op_sel_hi:[1,1,0]
	v_exp_f32_e32 v60, v60
	v_exp_f32_e32 v61, v61
	v_pk_fma_f32 v[52:53], v[64:65], v[52:53], s[50:51] op_sel_hi:[1,1,0]
	v_rcp_f32_e32 v69, v11
	v_pk_fma_f32 v[52:53], v[64:65], v[52:53], s[56:57] op_sel_hi:[1,1,0]
	v_pk_mul_f32 v[52:53], v[64:65], v[52:53]
	v_mul_f32_e32 v32, v33, v33
	v_pk_mul_f32 v[52:53], v[60:61], v[52:53]
	v_mul_f32_e32 v34, v35, v35
	v_max_f32_e32 v83, 0, v63
	v_fma_f32 v11, -|v63|, v53, v83
	v_max_f32_e32 v82, 0, v62
	v_fma_f32 v53, -|v62|, v52, v82
	v_mul_f32_e32 v12, v13, v13
	v_pk_mul_f32 v[62:63], v[66:67], v[66:67]
	v_pk_add_f32 v[28:29], v[30:31], v[32:33]
	v_pk_fma_f32 v[60:61], v[68:69], s[42:43], v[22:23] op_sel_hi:[1,0,0]
	v_pk_mul_f32 v[62:63], v[62:63], s[64:65] op_sel_hi:[1,0]
	v_pk_fma_f32 v[60:61], v[68:69], v[60:61], s[48:49] op_sel_hi:[1,1,0]
	v_exp_f32_e32 v62, v62
	v_exp_f32_e32 v63, v63
	v_pk_fma_f32 v[60:61], v[68:69], v[60:61], s[50:51] op_sel_hi:[1,1,0]
	v_pk_fma_f32 v[60:61], v[68:69], v[60:61], s[56:57] op_sel_hi:[1,1,0]
	v_mul_f32_e32 v36, v37, v37
	v_pk_mul_f32 v[60:61], v[68:69], v[60:61]
	v_mul_f32_e32 v38, v39, v39
	v_pk_mul_f32 v[60:61], v[62:63], v[60:61]
	v_pk_add_f32 v[26:27], v[28:29], v[26:27]
	v_max_f32_e32 v84, 0, v66
	v_fma_f32 v71, -|v66|, v60, v84
	v_max_f32_e32 v85, 0, v67
	v_fma_f32 v65, -|v67|, v61, v85
	global_load_dwordx4 v[60:63], v[24:25], off offset:1792
	v_pk_add_f32 v[12:13], v[34:35], v[12:13]
	v_mul_f32_e32 v40, v41, v41
	s_waitcnt vmcnt(1)
	v_lshlrev_b32_e32 v24, 16, v4
	v_and_b32_e32 v25, 0xffff0000, v4
	v_fma_f32 v72, |v24|, s40, 1.0
	v_fma_f32 v73, |v25|, s40, 1.0
	v_pk_mul_f32 v[68:69], v[24:25], v[24:25]
	v_rcp_f32_e32 v72, v72
	v_rcp_f32_e32 v73, v73
	v_mul_f32_e32 v14, v15, v15
	v_pk_mul_f32 v[68:69], v[68:69], s[64:65] op_sel_hi:[1,0]
	v_pk_add_f32 v[12:13], v[12:13], v[26:27]
	v_pk_fma_f32 v[66:67], v[72:73], s[42:43], v[22:23] op_sel_hi:[1,0,0]
	v_pk_add_f32 v[26:27], v[36:37], v[38:39]
	v_mul_f32_e32 v42, v43, v43
	v_mul_f32_e32 v44, v45, v45
	v_pk_fma_f32 v[66:67], v[72:73], v[66:67], s[48:49] op_sel_hi:[1,1,0]
	v_exp_f32_e32 v68, v68
	v_exp_f32_e32 v69, v69
	v_pk_add_f32 v[12:13], v[26:27], v[12:13]
	v_pk_add_f32 v[14:15], v[40:41], v[14:15]
	v_mul_f32_e32 v46, v47, v47
	v_mul_f32_e32 v8, v9, v9
	v_pk_fma_f32 v[66:67], v[72:73], v[66:67], s[50:51] op_sel_hi:[1,1,0]
	v_pk_add_f32 v[12:13], v[14:15], v[12:13]
	v_pk_add_f32 v[14:15], v[42:43], v[44:45]
	v_mul_f32_e32 v48, v49, v49
	v_mul_f32_e32 v50, v51, v51
	v_pk_fma_f32 v[66:67], v[72:73], v[66:67], s[56:57] op_sel_hi:[1,1,0]
	v_pk_add_f32 v[12:13], v[14:15], v[12:13]
	v_pk_add_f32 v[8:9], v[46:47], v[8:9]
	v_pk_mul_f32 v[66:67], v[72:73], v[66:67]
	v_pk_add_f32 v[8:9], v[8:9], v[12:13]
	v_pk_add_f32 v[12:13], v[48:49], v[50:51]
	v_lshlrev_b32_e32 v4, 16, v5
	v_and_b32_e32 v5, 0xffff0000, v5
	v_pk_mul_f32 v[66:67], v[68:69], v[66:67]
	v_pk_add_f32 v[8:9], v[12:13], v[8:9]
	v_max_f32_e32 v86, 0, v24
	v_fma_f32 v73, -|v24|, v66, v86
	v_max_f32_e32 v90, 0, v25
	v_fma_f32 v25, -|v25|, v67, v90
	v_fma_f32 v12, |v4|, s40, 1.0
	v_fma_f32 v13, |v5|, s40, 1.0
	v_mul_f32_e32 v52, v53, v53
	v_mul_f32_e32 v10, v11, v11
	v_rcp_f32_e32 v12, v12
	v_rcp_f32_e32 v13, v13
	v_mul_f32_e32 v70, v71, v71
	v_mul_f32_e32 v64, v65, v65
	v_pk_add_f32 v[10:11], v[52:53], v[10:11]
	v_mul_f32_e32 v72, v73, v73
	v_mul_f32_e32 v24, v25, v25
	v_pk_add_f32 v[8:9], v[10:11], v[8:9]
	v_pk_add_f32 v[10:11], v[70:71], v[64:65]
	v_pk_mul_f32 v[14:15], v[4:5], v[4:5]
	v_pk_add_f32 v[8:9], v[10:11], v[8:9]
	v_pk_add_f32 v[10:11], v[72:73], v[24:25]
	v_pk_mul_f32 v[14:15], v[14:15], s[64:65] op_sel_hi:[1,0]
	v_pk_add_f32 v[8:9], v[10:11], v[8:9]
	v_pk_fma_f32 v[10:11], v[12:13], s[42:43], v[22:23] op_sel_hi:[1,0,0]
	v_exp_f32_e32 v14, v14
	v_pk_fma_f32 v[10:11], v[12:13], v[10:11], s[48:49] op_sel_hi:[1,1,0]
	v_exp_f32_e32 v15, v15
	v_pk_fma_f32 v[10:11], v[12:13], v[10:11], s[50:51] op_sel_hi:[1,1,0]
	v_pk_fma_f32 v[10:11], v[12:13], v[10:11], s[56:57] op_sel_hi:[1,1,0]
	s_waitcnt vmcnt(0)
	v_lshlrev_b32_e32 v28, 16, v60
	v_pk_mul_f32 v[10:11], v[12:13], v[10:11]
	v_and_b32_e32 v29, 0xffff0000, v60
	v_pk_mul_f32 v[10:11], v[14:15], v[10:11]
	v_and_b32_e32 v31, 0x7fffffff, v29
	v_max_f32_e32 v91, 0, v4
	v_fma_f32 v15, -|v4|, v10, v91
	v_max_f32_e32 v92, 0, v5
	v_fma_f32 v5, -|v5|, v11, v92
	v_and_b32_e32 v30, 0x7fffffff, v28
	v_lshlrev_b32_e32 v10, 16, v6
	v_and_b32_e32 v12, 0x7fffffff, v10
	v_and_b32_e32 v11, 0xffff0000, v6
	v_and_b32_e32 v13, 0x7fffffff, v11
	v_pk_fma_f32 v[12:13], v[12:13], s[40:41], 1.0 op_sel_hi:[1,0,0]
	v_mul_f32_e32 v14, v15, v15
	v_rcp_f32_e32 v12, v12
	v_rcp_f32_e32 v13, v13
	v_mul_f32_e32 v4, v5, v5
	v_pk_mul_f32 v[24:25], v[10:11], v[10:11]
	v_pk_add_f32 v[4:5], v[14:15], v[4:5]
	v_pk_fma_f32 v[14:15], v[12:13], s[42:43], v[22:23] op_sel_hi:[1,0,0]
	v_pk_mul_f32 v[24:25], v[24:25], s[64:65] op_sel_hi:[1,0]
	v_pk_fma_f32 v[14:15], v[12:13], v[14:15], s[48:49] op_sel_hi:[1,1,0]
	v_exp_f32_e32 v24, v24
	v_exp_f32_e32 v25, v25
	v_pk_fma_f32 v[14:15], v[12:13], v[14:15], s[50:51] op_sel_hi:[1,1,0]
	v_lshlrev_b32_e32 v6, 16, v7
	v_and_b32_e32 v7, 0xffff0000, v7
	v_pk_fma_f32 v[14:15], v[12:13], v[14:15], s[56:57] op_sel_hi:[1,1,0]
	v_pk_mul_f32 v[12:13], v[12:13], v[14:15]
	v_fma_f32 v26, |v6|, s40, 1.0
	v_fma_f32 v27, |v7|, s40, 1.0
	v_pk_mul_f32 v[12:13], v[24:25], v[12:13]
	v_rcp_f32_e32 v26, v26
	v_rcp_f32_e32 v27, v27
	v_max_f32_e32 v93, 0, v10
	v_fma_f32 v25, -|v10|, v12, v93
	v_max_f32_e32 v94, 0, v11
	v_fma_f32 v11, -|v11|, v13, v94
	v_pk_fma_f32 v[30:31], v[30:31], s[40:41], 1.0 op_sel_hi:[1,0,0]
	v_lshlrev_b32_e32 v32, 16, v61
	v_rcp_f32_e32 v30, v30
	v_rcp_f32_e32 v31, v31
	v_pk_mul_f32 v[14:15], v[6:7], v[6:7]
	v_pk_fma_f32 v[12:13], v[26:27], s[42:43], v[22:23] op_sel_hi:[1,0,0]
	v_pk_mul_f32 v[14:15], v[14:15], s[64:65] op_sel_hi:[1,0]
	v_pk_fma_f32 v[12:13], v[26:27], v[12:13], s[48:49] op_sel_hi:[1,1,0]
	v_exp_f32_e32 v14, v14
	v_exp_f32_e32 v15, v15
	v_pk_fma_f32 v[12:13], v[26:27], v[12:13], s[50:51] op_sel_hi:[1,1,0]
	v_pk_fma_f32 v[12:13], v[26:27], v[12:13], s[56:57] op_sel_hi:[1,1,0]
	v_and_b32_e32 v33, 0xffff0000, v61
	v_pk_mul_f32 v[12:13], v[26:27], v[12:13]
	v_pk_mul_f32 v[12:13], v[14:15], v[12:13]
	v_max_f32_e32 v95, 0, v6
	v_fma_f32 v27, -|v6|, v12, v95
	v_max_f32_e32 v96, 0, v7
	v_fma_f32 v7, -|v7|, v13, v96
	v_fma_f32 v34, |v32|, s40, 1.0
	v_fma_f32 v35, |v33|, s40, 1.0
	v_rcp_f32_e32 v34, v34
	v_rcp_f32_e32 v35, v35
	v_pk_mul_f32 v[14:15], v[28:29], v[28:29]
	v_pk_fma_f32 v[12:13], v[30:31], s[42:43], v[22:23] op_sel_hi:[1,0,0]
	v_pk_mul_f32 v[14:15], v[14:15], s[64:65] op_sel_hi:[1,0]
	v_pk_fma_f32 v[12:13], v[30:31], v[12:13], s[48:49] op_sel_hi:[1,1,0]
	v_exp_f32_e32 v14, v14
	v_exp_f32_e32 v15, v15
	v_pk_fma_f32 v[12:13], v[30:31], v[12:13], s[50:51] op_sel_hi:[1,1,0]
	v_pk_fma_f32 v[12:13], v[30:31], v[12:13], s[56:57] op_sel_hi:[1,1,0]
	v_lshlrev_b32_e32 v36, 16, v62
	v_pk_mul_f32 v[12:13], v[30:31], v[12:13]
	v_and_b32_e32 v37, 0xffff0000, v62
	v_pk_mul_f32 v[12:13], v[14:15], v[12:13]
	v_max_f32_e32 v97, 0, v28
	v_fma_f32 v31, -|v28|, v12, v97
	v_max_f32_e32 v98, 0, v29
	v_fma_f32 v13, -|v29|, v13, v98
	v_pk_mul_f32 v[28:29], v[32:33], v[32:33]
	v_fma_f32 v38, |v36|, s40, 1.0
	v_fma_f32 v39, |v37|, s40, 1.0
	v_pk_fma_f32 v[14:15], v[34:35], s[42:43], v[22:23] op_sel_hi:[1,0,0]
	v_pk_mul_f32 v[28:29], v[28:29], s[64:65] op_sel_hi:[1,0]
	v_pk_fma_f32 v[14:15], v[34:35], v[14:15], s[48:49] op_sel_hi:[1,1,0]
	v_exp_f32_e32 v28, v28
	v_exp_f32_e32 v29, v29
	v_pk_fma_f32 v[14:15], v[34:35], v[14:15], s[50:51] op_sel_hi:[1,1,0]
	v_rcp_f32_e32 v38, v38
	v_pk_fma_f32 v[14:15], v[34:35], v[14:15], s[56:57] op_sel_hi:[1,1,0]
	v_rcp_f32_e32 v39, v39
	v_pk_mul_f32 v[14:15], v[34:35], v[14:15]
	v_pk_mul_f32 v[14:15], v[28:29], v[14:15]
	v_lshlrev_b32_e32 v40, 16, v63
	v_max_f32_e32 v99, 0, v32
	v_fma_f32 v35, -|v32|, v14, v99
	v_max_f32_e32 v100, 0, v33
	v_fma_f32 v15, -|v33|, v15, v100
	v_and_b32_e32 v41, 0xffff0000, v63
	v_pk_mul_f32 v[32:33], v[36:37], v[36:37]
	v_pk_fma_f32 v[28:29], v[38:39], s[42:43], v[22:23] op_sel_hi:[1,0,0]
	v_pk_mul_f32 v[32:33], v[32:33], s[64:65] op_sel_hi:[1,0]
	v_pk_fma_f32 v[28:29], v[38:39], v[28:29], s[48:49] op_sel_hi:[1,1,0]
	v_exp_f32_e32 v32, v32
	v_exp_f32_e32 v33, v33
	v_pk_fma_f32 v[28:29], v[38:39], v[28:29], s[50:51] op_sel_hi:[1,1,0]
	v_pk_fma_f32 v[28:29], v[38:39], v[28:29], s[56:57] op_sel_hi:[1,1,0]
	v_fma_f32 v42, |v40|, s40, 1.0
	v_fma_f32 v43, |v41|, s40, 1.0
	v_pk_mul_f32 v[28:29], v[38:39], v[28:29]
	v_rcp_f32_e32 v42, v42
	v_pk_mul_f32 v[28:29], v[32:33], v[28:29]
	v_rcp_f32_e32 v43, v43
	v_max_f32_e32 v104, 0, v36
	v_fma_f32 v39, -|v36|, v28, v104
	v_max_f32_e32 v105, 0, v37
	v_fma_f32 v29, -|v37|, v29, v105
	v_pk_fma_f32 v[22:23], v[42:43], s[42:43], v[22:23] op_sel_hi:[1,0,0]
	v_mul_f32_e32 v24, v25, v25
	v_pk_fma_f32 v[22:23], v[42:43], v[22:23], s[48:49] op_sel_hi:[1,1,0]
	v_mul_f32_e32 v10, v11, v11
	v_pk_mul_f32 v[32:33], v[40:41], v[40:41]
	v_pk_fma_f32 v[22:23], v[42:43], v[22:23], s[50:51] op_sel_hi:[1,1,0]
	v_pk_mul_f32 v[32:33], v[32:33], s[64:65] op_sel_hi:[1,0]
	v_pk_fma_f32 v[22:23], v[42:43], v[22:23], s[56:57] op_sel_hi:[1,1,0]
	v_exp_f32_e32 v32, v32
	v_exp_f32_e32 v33, v33
	v_pk_mul_f32 v[22:23], v[42:43], v[22:23]
	v_mul_f32_e32 v26, v27, v27
	v_mul_f32_e32 v6, v7, v7
	v_pk_mul_f32 v[22:23], v[32:33], v[22:23]
	v_pk_add_f32 v[4:5], v[4:5], v[8:9]
	v_pk_add_f32 v[8:9], v[24:25], v[10:11]
	v_mul_f32_e32 v30, v31, v31
	v_mul_f32_e32 v12, v13, v13
	v_max_f32_e32 v106, 0, v40
	v_fma_f32 v37, -|v40|, v22, v106
	v_max_f32_e32 v107, 0, v41
	v_fma_f32 v23, -|v41|, v23, v107
	v_pk_add_f32 v[4:5], v[8:9], v[4:5]
	v_pk_add_f32 v[6:7], v[26:27], v[6:7]
	v_mul_f32_e32 v34, v35, v35
	v_mul_f32_e32 v14, v15, v15
	v_pk_add_f32 v[4:5], v[6:7], v[4:5]
	v_pk_add_f32 v[6:7], v[30:31], v[12:13]
	v_mul_f32_e32 v38, v39, v39
	v_mul_f32_e32 v28, v29, v29
	v_pk_add_f32 v[4:5], v[6:7], v[4:5]
	v_pk_add_f32 v[6:7], v[34:35], v[14:15]
	v_mul_f32_e32 v36, v37, v37
	v_mul_f32_e32 v22, v23, v23
	v_pk_add_f32 v[4:5], v[6:7], v[4:5]
	v_pk_add_f32 v[6:7], v[38:39], v[28:29]
	s_nop 0
	v_pk_add_f32 v[4:5], v[6:7], v[4:5]
	v_pk_add_f32 v[6:7], v[36:37], v[22:23]
	s_nop 0
	v_pk_add_f32 v[4:5], v[6:7], v[4:5]
	ds_bpermute_b32 v7, v56, v5
	ds_bpermute_b32 v6, v56, v4
	s_waitcnt lgkmcnt(0)
	v_pk_add_f32 v[4:5], v[4:5], v[6:7]
	ds_bpermute_b32 v7, v57, v5
	ds_bpermute_b32 v6, v57, v4
	s_waitcnt lgkmcnt(0)
	v_pk_add_f32 v[4:5], v[4:5], v[6:7]
	ds_bpermute_b32 v7, v58, v5
	ds_bpermute_b32 v6, v58, v4
	s_waitcnt lgkmcnt(0)
	v_pk_add_f32 v[4:5], v[4:5], v[6:7]
	ds_bpermute_b32 v7, v59, v5
	ds_bpermute_b32 v6, v59, v4
	s_and_saveexec_b64 s[8:9], vcc
	s_cbranch_execz .LBB0_447
	s_waitcnt lgkmcnt(0)
	v_pk_add_f32 v[4:5], v[4:5], v[6:7]
	s_nop 0
	v_pk_mul_f32 v[4:5], v[4:5], s[66:67] op_sel_hi:[1,0]
	s_nop 0
	v_fma_f32 v4, -v5, v5, v4
	v_max_f32_e32 v4, 0, v4
	v_add_f32_e32 v4, 0x358637bd, v4
	v_mul_f32_e32 v6, 0x4b800000, v4
	v_cmp_gt_f32_e64 s[0:1], s36, v4
	s_nop 1
	v_cndmask_b32_e64 v4, v4, v6, s[0:1]
	v_rsq_f32_e32 v4, v4
	v_lshl_add_u32 v6, v20, 2, 0
	v_add_u32_e32 v7, 0x11000, v6
	ds_write_b32 v7, v5
	v_mul_f32_e32 v5, 0x45800000, v4
	v_cndmask_b32_e64 v4, v4, v5, s[0:1]
	v_add_u32_e32 v5, 0x11200, v6
	ds_write_b32 v5, v4
.LBB0_447:
	s_or_b64 exec, exec, s[8:9]
	v_or_b32_e32 v20, 8, v16
	v_ashrrev_i32_e32 v21, 31, v20
	v_lshl_add_u64 v[4:5], s[6:7], 0, v[20:21]
	v_lshlrev_b64 v[4:5], 11, v[4:5]
	v_lshl_add_u64 v[4:5], s[4:5], 0, v[4:5]
	v_lshl_add_u64 v[24:25], v[4:5], 0, v[18:19]
	global_load_dwordx4 v[8:11], v[24:25], off
	s_waitcnt lgkmcnt(0)
	global_load_dwordx4 v[4:7], v[24:25], off offset:256
	v_mov_b64_e32 v[22:23], s[44:45]
	v_mov_b32_e32 v13, v2
	s_waitcnt vmcnt(1)
	v_lshlrev_b32_e32 v28, 16, v10
	v_and_b32_e32 v29, 0xffff0000, v10
	v_and_b32_e32 v15, 0xffff0000, v8
	v_and_b32_e32 v27, 0xffff0000, v9
	v_lshlrev_b32_e32 v26, 16, v9
	v_lshlrev_b32_e32 v14, 16, v8
	v_lshlrev_b32_e32 v8, 16, v11
	v_and_b32_e32 v9, 0xffff0000, v11
	v_fma_f32 v10, |v28|, s40, 1.0
	v_fma_f32 v11, |v29|, s40, 1.0
	v_fma_f32 v32, |v14|, s40, 1.0
	v_fma_f32 v33, |v15|, s40, 1.0
	v_rcp_f32_e32 v10, v10
	v_rcp_f32_e32 v11, v11
	v_fma_f32 v36, |v26|, s40, 1.0
	v_fma_f32 v37, |v27|, s40, 1.0
	v_rcp_f32_e32 v32, v32
	v_rcp_f32_e32 v33, v33
	v_rcp_f32_e32 v36, v36
	v_rcp_f32_e32 v37, v37
	v_pk_mul_f32 v[30:31], v[28:29], v[28:29]
	v_pk_mul_f32 v[34:35], v[14:15], v[14:15]
	v_pk_mul_f32 v[30:31], v[30:31], s[64:65] op_sel_hi:[1,0]
	v_pk_fma_f32 v[44:45], v[10:11], s[42:43], v[22:23] op_sel_hi:[1,0,0]
	v_pk_mul_f32 v[38:39], v[26:27], v[26:27]
	v_pk_mul_f32 v[34:35], v[34:35], s[64:65] op_sel_hi:[1,0]
	v_exp_f32_e32 v30, v30
	v_exp_f32_e32 v31, v31
	v_pk_fma_f32 v[46:47], v[32:33], s[42:43], v[22:23] op_sel_hi:[1,0,0]
	v_pk_fma_f32 v[44:45], v[10:11], v[44:45], s[48:49] op_sel_hi:[1,1,0]
	v_pk_mul_f32 v[38:39], v[38:39], s[64:65] op_sel_hi:[1,0]
	v_exp_f32_e32 v34, v34
	v_exp_f32_e32 v35, v35
	v_pk_fma_f32 v[48:49], v[36:37], s[42:43], v[22:23] op_sel_hi:[1,0,0]
	v_pk_fma_f32 v[46:47], v[32:33], v[46:47], s[48:49] op_sel_hi:[1,1,0]
	v_pk_fma_f32 v[44:45], v[10:11], v[44:45], s[50:51] op_sel_hi:[1,1,0]
	v_exp_f32_e32 v38, v38
	v_exp_f32_e32 v39, v39
	v_pk_fma_f32 v[48:49], v[36:37], v[48:49], s[48:49] op_sel_hi:[1,1,0]
	v_pk_fma_f32 v[46:47], v[32:33], v[46:47], s[50:51] op_sel_hi:[1,1,0]
	v_pk_fma_f32 v[44:45], v[10:11], v[44:45], s[56:57] op_sel_hi:[1,1,0]
	v_pk_fma_f32 v[48:49], v[36:37], v[48:49], s[50:51] op_sel_hi:[1,1,0]
	v_pk_fma_f32 v[46:47], v[32:33], v[46:47], s[56:57] op_sel_hi:[1,1,0]
	v_pk_mul_f32 v[10:11], v[10:11], v[44:45]
	v_pk_fma_f32 v[48:49], v[36:37], v[48:49], s[56:57] op_sel_hi:[1,1,0]
	v_pk_mul_f32 v[32:33], v[32:33], v[46:47]
	v_pk_mul_f32 v[10:11], v[30:31], v[10:11]
	v_pk_mul_f32 v[36:37], v[36:37], v[48:49]
	v_pk_mul_f32 v[30:31], v[34:35], v[32:33]
	v_max_f32_e32 v108, 0, v28
	v_fma_f32 v45, -|v28|, v10, v108
	v_max_f32_e32 v109, 0, v29
	v_fma_f32 v11, -|v29|, v11, v109
	v_pk_mul_f32 v[32:33], v[38:39], v[36:37]
	v_max_f32_e32 v110, 0, v26
	v_fma_f32 v29, -|v26|, v32, v110
	v_max_f32_e32 v111, 0, v27
	v_fma_f32 v27, -|v27|, v33, v111
	v_max_f32_e32 v112, 0, v14
	v_fma_f32 v28, -|v14|, v30, v112
	v_max_f32_e32 v113, 0, v15
	v_fma_f32 v15, -|v15|, v31, v113
	v_fma_f32 v40, |v8|, s40, 1.0
	v_fma_f32 v41, |v9|, s40, 1.0
	v_mov_b32_e32 v14, v29
	v_rcp_f32_e32 v40, v40
	v_rcp_f32_e32 v41, v41
	v_mul_f32_e32 v30, v28, v28
	v_mov_b32_e32 v31, v29
	v_mul_f32_e32 v26, v15, v15
	v_mul_f32_e32 v12, v27, v27
	v_pk_add_f32 v[26:27], v[30:31], v[26:27]
	v_pk_mul_f32 v[30:31], v[28:29], v[14:15] op_sel:[1,0] op_sel_hi:[0,1]
	v_pk_add_f32 v[14:15], v[28:29], v[14:15] op_sel:[1,0] op_sel_hi:[0,1]
	v_pk_mul_f32 v[42:43], v[8:9], v[8:9]
	v_mov_b32_e32 v31, v15
	v_pk_mul_f32 v[42:43], v[42:43], s[64:65] op_sel_hi:[1,0]
	v_pk_fma_f32 v[50:51], v[40:41], s[42:43], v[22:23] op_sel_hi:[1,0,0]
	v_mul_f32_e32 v44, v45, v45
	v_mul_f32_e32 v10, v11, v11
	v_pk_add_f32 v[12:13], v[30:31], v[12:13]
	v_exp_f32_e32 v42, v42
	v_exp_f32_e32 v43, v43
	v_pk_fma_f32 v[50:51], v[40:41], v[50:51], s[48:49] op_sel_hi:[1,1,0]
	v_pk_add_f32 v[10:11], v[44:45], v[10:11]
	v_pk_add_f32 v[12:13], v[26:27], v[12:13]
	v_pk_add_f32 v[26:27], v[10:11], v[12:13]
	v_pk_fma_f32 v[10:11], v[40:41], v[50:51], s[50:51] op_sel_hi:[1,1,0]
	s_nop 0
	v_pk_fma_f32 v[10:11], v[40:41], v[10:11], s[56:57] op_sel_hi:[1,1,0]
	s_nop 0
	v_pk_mul_f32 v[10:11], v[40:41], v[10:11]
	s_waitcnt vmcnt(0)
	v_lshlrev_b32_e32 v40, 16, v6
	v_pk_mul_f32 v[10:11], v[42:43], v[10:11]
	v_and_b32_e32 v41, 0xffff0000, v6
	v_max_f32_e32 v114, 0, v8
	v_fma_f32 v15, -|v8|, v10, v114
	v_max_f32_e32 v115, 0, v9
	v_fma_f32 v9, -|v9|, v11, v115
	v_and_b32_e32 v37, 0x7fffffff, v41
	v_lshlrev_b32_e32 v12, 16, v4
	v_and_b32_e32 v10, 0x7fffffff, v12
	v_and_b32_e32 v13, 0xffff0000, v4
	v_and_b32_e32 v11, 0x7fffffff, v13
	v_pk_fma_f32 v[10:11], v[10:11], s[40:41], 1.0 op_sel_hi:[1,0,0]
	v_mul_f32_e32 v14, v15, v15
	v_rcp_f32_e32 v10, v10
	v_rcp_f32_e32 v11, v11
	v_mul_f32_e32 v8, v9, v9
	v_pk_add_f32 v[28:29], v[14:15], v[8:9]
	v_pk_mul_f32 v[14:15], v[12:13], v[12:13]
	v_pk_fma_f32 v[8:9], v[10:11], s[42:43], v[22:23] op_sel_hi:[1,0,0]
	v_pk_mul_f32 v[14:15], v[14:15], s[64:65] op_sel_hi:[1,0]
	v_pk_fma_f32 v[8:9], v[10:11], v[8:9], s[48:49] op_sel_hi:[1,1,0]
	v_exp_f32_e32 v14, v14
	v_exp_f32_e32 v15, v15
	v_pk_fma_f32 v[8:9], v[10:11], v[8:9], s[50:51] op_sel_hi:[1,1,0]
	v_lshlrev_b32_e32 v4, 16, v5
	v_pk_fma_f32 v[8:9], v[10:11], v[8:9], s[56:57] op_sel_hi:[1,1,0]
	v_and_b32_e32 v5, 0xffff0000, v5
	v_pk_mul_f32 v[8:9], v[10:11], v[8:9]
	v_pk_mul_f32 v[14:15], v[14:15], v[8:9]
	global_load_dwordx4 v[8:11], v[24:25], off offset:512
	v_fma_f32 v34, |v4|, s40, 1.0
	v_fma_f32 v35, |v5|, s40, 1.0
	v_rcp_f32_e32 v34, v34
	v_rcp_f32_e32 v35, v35
	v_max_f32_e32 v116, 0, v12
	v_fma_f32 v31, -|v12|, v14, v116
	v_max_f32_e32 v117, 0, v13
	v_fma_f32 v33, -|v13|, v15, v117
	v_and_b32_e32 v36, 0x7fffffff, v40
	v_pk_fma_f32 v[36:37], v[36:37], s[40:41], 1.0 op_sel_hi:[1,0,0]
	v_pk_fma_f32 v[12:13], v[34:35], s[42:43], v[22:23] op_sel_hi:[1,0,0]
	v_rcp_f32_e32 v38, v36
	v_pk_mul_f32 v[14:15], v[4:5], v[4:5]
	v_pk_fma_f32 v[12:13], v[34:35], v[12:13], s[48:49] op_sel_hi:[1,1,0]
	v_pk_mul_f32 v[14:15], v[14:15], s[64:65] op_sel_hi:[1,0]
	v_pk_fma_f32 v[12:13], v[34:35], v[12:13], s[50:51] op_sel_hi:[1,1,0]
	v_exp_f32_e32 v14, v14
	v_exp_f32_e32 v15, v15
	v_pk_fma_f32 v[12:13], v[34:35], v[12:13], s[56:57] op_sel_hi:[1,1,0]
	v_rcp_f32_e32 v39, v37
	v_pk_mul_f32 v[12:13], v[34:35], v[12:13]
	v_pk_mul_f32 v[12:13], v[14:15], v[12:13]
	v_mul_f32_e32 v30, v31, v31
	v_max_f32_e32 v80, 0, v4
	v_fma_f32 v35, -|v4|, v12, v80
	v_max_f32_e32 v81, 0, v5
	v_fma_f32 v37, -|v5|, v13, v81
	v_mul_f32_e32 v32, v33, v33
	v_pk_fma_f32 v[4:5], v[38:39], s[42:43], v[22:23] op_sel_hi:[1,0,0]
	v_lshlrev_b32_e32 v14, 16, v7
	v_pk_mul_f32 v[12:13], v[40:41], v[40:41]
	v_pk_fma_f32 v[4:5], v[38:39], v[4:5], s[48:49] op_sel_hi:[1,1,0]
	v_pk_mul_f32 v[12:13], v[12:13], s[64:65] op_sel_hi:[1,0]
	v_pk_fma_f32 v[4:5], v[38:39], v[4:5], s[50:51] op_sel_hi:[1,1,0]
	v_exp_f32_e32 v12, v12
	v_exp_f32_e32 v13, v13
	v_and_b32_e32 v15, 0xffff0000, v7
	v_pk_fma_f32 v[4:5], v[38:39], v[4:5], s[56:57] op_sel_hi:[1,1,0]
	v_pk_mul_f32 v[4:5], v[38:39], v[4:5]
	v_fma_f32 v6, |v14|, s40, 1.0
	v_fma_f32 v7, |v15|, s40, 1.0
	v_pk_mul_f32 v[4:5], v[12:13], v[4:5]
	v_rcp_f32_e32 v6, v6
	v_rcp_f32_e32 v7, v7
	v_max_f32_e32 v82, 0, v40
	v_fma_f32 v39, -|v40|, v4, v82
	v_max_f32_e32 v83, 0, v41
	v_fma_f32 v41, -|v41|, v5, v83
	v_mul_f32_e32 v34, v35, v35
	v_mul_f32_e32 v36, v37, v37
	v_pk_add_f32 v[26:27], v[28:29], v[26:27]
	v_pk_add_f32 v[28:29], v[30:31], v[32:33]
	v_pk_mul_f32 v[12:13], v[14:15], v[14:15]
	v_pk_fma_f32 v[4:5], v[6:7], s[42:43], v[22:23] op_sel_hi:[1,0,0]
	v_pk_mul_f32 v[12:13], v[12:13], s[64:65] op_sel_hi:[1,0]
	v_pk_fma_f32 v[4:5], v[6:7], v[4:5], s[48:49] op_sel_hi:[1,1,0]
	v_exp_f32_e32 v12, v12
	v_exp_f32_e32 v13, v13
	v_pk_fma_f32 v[4:5], v[6:7], v[4:5], s[50:51] op_sel_hi:[1,1,0]
	v_pk_fma_f32 v[4:5], v[6:7], v[4:5], s[56:57] op_sel_hi:[1,1,0]
	v_mul_f32_e32 v38, v39, v39
	v_pk_mul_f32 v[4:5], v[6:7], v[4:5]
	v_mul_f32_e32 v40, v41, v41
	v_pk_mul_f32 v[4:5], v[12:13], v[4:5]
	v_pk_add_f32 v[26:27], v[28:29], v[26:27]
	v_max_f32_e32 v84, 0, v14
	v_fma_f32 v43, -|v14|, v4, v84
	v_max_f32_e32 v85, 0, v15
	v_fma_f32 v45, -|v15|, v5, v85
	global_load_dwordx4 v[4:7], v[24:25], off offset:768
	v_pk_add_f32 v[28:29], v[34:35], v[36:37]
	s_waitcnt vmcnt(1)
	v_lshlrev_b32_e32 v48, 16, v8
	v_and_b32_e32 v49, 0xffff0000, v8
	v_fma_f32 v46, |v48|, s40, 1.0
	v_fma_f32 v47, |v49|, s40, 1.0
	v_pk_mul_f32 v[14:15], v[48:49], v[48:49]
	v_rcp_f32_e32 v46, v46
	v_rcp_f32_e32 v47, v47
	v_pk_mul_f32 v[14:15], v[14:15], s[64:65] op_sel_hi:[1,0]
	v_lshlrev_b32_e32 v50, 16, v9
	v_pk_fma_f32 v[12:13], v[46:47], s[42:43], v[22:23] op_sel_hi:[1,0,0]
	v_exp_f32_e32 v14, v14
	v_pk_fma_f32 v[12:13], v[46:47], v[12:13], s[48:49] op_sel_hi:[1,1,0]
	v_exp_f32_e32 v15, v15
	v_and_b32_e32 v51, 0xffff0000, v9
	v_pk_fma_f32 v[12:13], v[46:47], v[12:13], s[50:51] op_sel_hi:[1,1,0]
	v_pk_fma_f32 v[12:13], v[46:47], v[12:13], s[56:57] op_sel_hi:[1,1,0]
	v_fma_f32 v8, |v50|, s40, 1.0
	v_fma_f32 v9, |v51|, s40, 1.0
	v_pk_mul_f32 v[12:13], v[46:47], v[12:13]
	v_rcp_f32_e32 v52, v8
	v_rcp_f32_e32 v53, v9
	v_pk_mul_f32 v[12:13], v[14:15], v[12:13]
	v_max_f32_e32 v86, 0, v48
	v_fma_f32 v47, -|v48|, v12, v86
	v_max_f32_e32 v90, 0, v49
	v_fma_f32 v9, -|v49|, v13, v90
	v_lshlrev_b32_e32 v60, 16, v10
	v_and_b32_e32 v61, 0xffff0000, v10
	v_lshlrev_b32_e32 v10, 16, v11
	v_pk_fma_f32 v[12:13], v[52:53], s[42:43], v[22:23] op_sel_hi:[1,0,0]
	v_pk_mul_f32 v[14:15], v[50:51], v[50:51]
	v_pk_fma_f32 v[12:13], v[52:53], v[12:13], s[48:49] op_sel_hi:[1,1,0]
	v_pk_mul_f32 v[14:15], v[14:15], s[64:65] op_sel_hi:[1,0]
	v_pk_fma_f32 v[12:13], v[52:53], v[12:13], s[50:51] op_sel_hi:[1,1,0]
	v_exp_f32_e32 v14, v14
	v_exp_f32_e32 v15, v15
	v_pk_fma_f32 v[12:13], v[52:53], v[12:13], s[56:57] op_sel_hi:[1,1,0]
	v_pk_mul_f32 v[12:13], v[52:53], v[12:13]
	v_fma_f32 v52, |v60|, s40, 1.0
	v_fma_f32 v53, |v61|, s40, 1.0
	v_pk_mul_f32 v[12:13], v[14:15], v[12:13]
	v_rcp_f32_e32 v52, v52
	v_rcp_f32_e32 v53, v53
	v_max_f32_e32 v91, 0, v50
	v_fma_f32 v49, -|v50|, v12, v91
	v_max_f32_e32 v92, 0, v51
	v_fma_f32 v51, -|v51|, v13, v92
	v_and_b32_e32 v11, 0xffff0000, v11
	v_pk_mul_f32 v[14:15], v[60:61], v[60:61]
	v_pk_fma_f32 v[12:13], v[52:53], s[42:43], v[22:23] op_sel_hi:[1,0,0]
	v_pk_mul_f32 v[14:15], v[14:15], s[64:65] op_sel_hi:[1,0]
	v_pk_fma_f32 v[12:13], v[52:53], v[12:13], s[48:49] op_sel_hi:[1,1,0]
	v_exp_f32_e32 v14, v14
	v_exp_f32_e32 v15, v15
	v_pk_fma_f32 v[12:13], v[52:53], v[12:13], s[50:51] op_sel_hi:[1,1,0]
	v_fma_f32 v62, |v10|, s40, 1.0
	v_fma_f32 v63, |v11|, s40, 1.0
	v_pk_fma_f32 v[12:13], v[52:53], v[12:13], s[56:57] op_sel_hi:[1,1,0]
	v_rcp_f32_e32 v62, v62
	v_pk_mul_f32 v[12:13], v[52:53], v[12:13]
	v_rcp_f32_e32 v63, v63
	v_pk_mul_f32 v[12:13], v[14:15], v[12:13]
	v_max_f32_e32 v93, 0, v60
	v_fma_f32 v53, -|v60|, v12, v93
	v_max_f32_e32 v94, 0, v61
	v_fma_f32 v61, -|v61|, v13, v94
	v_mul_f32_e32 v42, v43, v43
	s_waitcnt vmcnt(0)
	v_lshlrev_b32_e32 v64, 16, v4
	v_and_b32_e32 v65, 0xffff0000, v4
	v_pk_mul_f32 v[14:15], v[10:11], v[10:11]
	v_pk_fma_f32 v[12:13], v[62:63], s[42:43], v[22:23] op_sel_hi:[1,0,0]
	v_pk_mul_f32 v[14:15], v[14:15], s[64:65] op_sel_hi:[1,0]
	v_pk_fma_f32 v[12:13], v[62:63], v[12:13], s[48:49] op_sel_hi:[1,1,0]
	v_exp_f32_e32 v14, v14
	v_exp_f32_e32 v15, v15
	v_pk_fma_f32 v[12:13], v[62:63], v[12:13], s[50:51] op_sel_hi:[1,1,0]
	v_pk_fma_f32 v[12:13], v[62:63], v[12:13], s[56:57] op_sel_hi:[1,1,0]
	v_pk_mul_f32 v[12:13], v[62:63], v[12:13]
	v_fma_f32 v66, |v64|, s40, 1.0
	v_fma_f32 v67, |v65|, s40, 1.0
	v_pk_mul_f32 v[12:13], v[14:15], v[12:13]
	v_rcp_f32_e32 v66, v66
	v_rcp_f32_e32 v67, v67
	v_max_f32_e32 v95, 0, v10
	v_fma_f32 v63, -|v10|, v12, v95
	v_max_f32_e32 v96, 0, v11
	v_fma_f32 v11, -|v11|, v13, v96
	v_lshlrev_b32_e32 v4, 16, v5
	v_and_b32_e32 v5, 0xffff0000, v5
	v_pk_mul_f32 v[14:15], v[64:65], v[64:65]
	v_pk_fma_f32 v[12:13], v[66:67], s[42:43], v[22:23] op_sel_hi:[1,0,0]
	v_pk_mul_f32 v[14:15], v[14:15], s[64:65] op_sel_hi:[1,0]
	v_pk_fma_f32 v[12:13], v[66:67], v[12:13], s[48:49] op_sel_hi:[1,1,0]
	v_exp_f32_e32 v14, v14
	v_exp_f32_e32 v15, v15
	v_pk_fma_f32 v[12:13], v[66:67], v[12:13], s[50:51] op_sel_hi:[1,1,0]
	v_fma_f32 v68, |v4|, s40, 1.0
	v_fma_f32 v69, |v5|, s40, 1.0
	v_pk_fma_f32 v[12:13], v[66:67], v[12:13], s[56:57] op_sel_hi:[1,1,0]
	v_rcp_f32_e32 v68, v68
	v_pk_mul_f32 v[12:13], v[66:67], v[12:13]
	v_rcp_f32_e32 v69, v69
	v_pk_mul_f32 v[12:13], v[14:15], v[12:13]
	v_max_f32_e32 v97, 0, v64
	v_fma_f32 v67, -|v64|, v12, v97
	v_max_f32_e32 v98, 0, v65
	v_fma_f32 v65, -|v65|, v13, v98
	v_mul_f32_e32 v44, v45, v45
	v_pk_add_f32 v[26:27], v[28:29], v[26:27]
	v_pk_add_f32 v[28:29], v[38:39], v[40:41]
	v_pk_fma_f32 v[12:13], v[68:69], s[42:43], v[22:23] op_sel_hi:[1,0,0]
	v_pk_mul_f32 v[14:15], v[4:5], v[4:5]
	v_pk_fma_f32 v[12:13], v[68:69], v[12:13], s[48:49] op_sel_hi:[1,1,0]
	v_pk_mul_f32 v[14:15], v[14:15], s[64:65] op_sel_hi:[1,0]
	v_pk_fma_f32 v[12:13], v[68:69], v[12:13], s[50:51] op_sel_hi:[1,1,0]
	v_exp_f32_e32 v70, v14
	v_exp_f32_e32 v71, v15
	v_pk_fma_f32 v[72:73], v[68:69], v[12:13], s[56:57] op_sel_hi:[1,1,0]
	global_load_dwordx4 v[12:15], v[24:25], off offset:1024
	v_mul_f32_e32 v46, v47, v47
	v_mul_f32_e32 v8, v9, v9
	v_pk_add_f32 v[26:27], v[28:29], v[26:27]
	v_pk_add_f32 v[28:29], v[42:43], v[44:45]
	v_mul_f32_e32 v48, v49, v49
	v_mul_f32_e32 v50, v51, v51
	v_pk_add_f32 v[26:27], v[28:29], v[26:27]
	v_pk_add_f32 v[8:9], v[46:47], v[8:9]
	v_mul_f32_e32 v52, v53, v53
	v_mul_f32_e32 v60, v61, v61
	v_pk_mul_f32 v[68:69], v[68:69], v[72:73]
	v_pk_add_f32 v[8:9], v[8:9], v[26:27]
	v_pk_add_f32 v[26:27], v[48:49], v[50:51]
	v_pk_mul_f32 v[68:69], v[70:71], v[68:69]
	v_pk_add_f32 v[8:9], v[26:27], v[8:9]
	v_pk_add_f32 v[26:27], v[52:53], v[60:61]
	v_lshlrev_b32_e32 v28, 16, v6
	v_and_b32_e32 v29, 0xffff0000, v6
	v_max_f32_e32 v99, 0, v4
	v_fma_f32 v73, -|v4|, v68, v99
	v_max_f32_e32 v100, 0, v5
	v_fma_f32 v5, -|v5|, v69, v100
	v_pk_add_f32 v[8:9], v[26:27], v[8:9]
	v_mul_f32_e32 v62, v63, v63
	v_mul_f32_e32 v10, v11, v11
	v_fma_f32 v26, |v28|, s40, 1.0
	v_fma_f32 v27, |v29|, s40, 1.0
	v_mul_f32_e32 v66, v67, v67
	v_mul_f32_e32 v64, v65, v65
	v_pk_add_f32 v[10:11], v[62:63], v[10:11]
	v_rcp_f32_e32 v30, v26
	v_rcp_f32_e32 v31, v27
	v_mul_f32_e32 v72, v73, v73
	v_mul_f32_e32 v4, v5, v5
	v_pk_add_f32 v[8:9], v[10:11], v[8:9]
	v_pk_add_f32 v[10:11], v[66:67], v[64:65]
	v_pk_add_f32 v[4:5], v[72:73], v[4:5]
	v_pk_add_f32 v[8:9], v[10:11], v[8:9]
	v_cmp_gt_f32_e64 s[0:1], 0, v28
	v_pk_add_f32 v[26:27], v[4:5], v[8:9]
	v_pk_mul_f32 v[8:9], v[28:29], v[28:29]
	v_pk_fma_f32 v[4:5], v[30:31], s[42:43], v[22:23] op_sel_hi:[1,0,0]
	v_pk_mul_f32 v[8:9], v[8:9], s[64:65] op_sel_hi:[1,0]
	v_pk_fma_f32 v[4:5], v[30:31], v[4:5], s[48:49] op_sel_hi:[1,1,0]
	v_exp_f32_e32 v8, v8
	v_exp_f32_e32 v9, v9
	v_pk_fma_f32 v[4:5], v[30:31], v[4:5], s[50:51] op_sel_hi:[1,1,0]
	v_lshlrev_b32_e32 v6, 16, v7
	v_pk_fma_f32 v[4:5], v[30:31], v[4:5], s[56:57] op_sel_hi:[1,1,0]
	v_and_b32_e32 v7, 0xffff0000, v7
	v_pk_mul_f32 v[4:5], v[30:31], v[4:5]
	s_nop 0
	v_pk_mul_f32 v[4:5], v[8:9], v[4:5]
	s_nop 0
	v_pk_mul_f32 v[8:9], v[28:29], v[4:5]
	v_pk_fma_f32 v[4:5], v[28:29], v[4:5], v[28:29] neg_lo:[1,0,0] neg_hi:[1,0,0]
	s_nop 0
	v_cndmask_b32_e64 v11, v4, v8, s[0:1]
	v_cmp_gt_f32_e64 s[0:1], 0, v29
	v_and_b32_e32 v8, 0x7fffffff, v6
	v_mul_f32_e32 v10, v11, v11
	v_cndmask_b32_e64 v5, v5, v9, s[0:1]
	v_and_b32_e32 v9, 0x7fffffff, v7
	v_pk_fma_f32 v[8:9], v[8:9], s[40:41], 1.0 op_sel_hi:[1,0,0]
	v_mul_f32_e32 v4, v5, v5
	v_rcp_f32_e32 v8, v8
	v_rcp_f32_e32 v9, v9
	v_pk_add_f32 v[28:29], v[10:11], v[4:5]
	v_pk_mul_f32 v[10:11], v[6:7], v[6:7]
	v_cmp_gt_f32_e64 s[0:1], 0, v6
	v_pk_fma_f32 v[4:5], v[8:9], s[42:43], v[22:23] op_sel_hi:[1,0,0]
	v_pk_mul_f32 v[10:11], v[10:11], s[64:65] op_sel_hi:[1,0]
	v_pk_fma_f32 v[4:5], v[8:9], v[4:5], s[48:49] op_sel_hi:[1,1,0]
	v_exp_f32_e32 v10, v10
	v_exp_f32_e32 v11, v11
	v_pk_fma_f32 v[4:5], v[8:9], v[4:5], s[50:51] op_sel_hi:[1,1,0]
	v_pk_add_f32 v[26:27], v[28:29], v[26:27]
	v_pk_fma_f32 v[4:5], v[8:9], v[4:5], s[56:57] op_sel_hi:[1,1,0]
	s_nop 0
	v_pk_mul_f32 v[4:5], v[8:9], v[4:5]
	s_nop 0
	v_pk_mul_f32 v[4:5], v[10:11], v[4:5]
	global_load_dwordx4 v[8:11], v[24:25], off offset:1280
	s_waitcnt vmcnt(1)
	v_lshlrev_b32_e32 v36, 16, v12
	v_and_b32_e32 v37, 0xffff0000, v12
	v_fma_f32 v34, |v36|, s40, 1.0
	v_fma_f32 v35, |v37|, s40, 1.0
	v_pk_mul_f32 v[32:33], v[6:7], v[4:5]
	v_rcp_f32_e32 v34, v34
	v_rcp_f32_e32 v35, v35
	v_pk_fma_f32 v[4:5], v[6:7], v[4:5], v[6:7] neg_lo:[1,0,0] neg_hi:[1,0,0]
	v_lshlrev_b32_e32 v38, 16, v13
	v_cndmask_b32_e64 v31, v4, v32, s[0:1]
	v_cmp_gt_f32_e64 s[0:1], 0, v7
	v_pk_mul_f32 v[6:7], v[36:37], v[36:37]
	v_and_b32_e32 v39, 0xffff0000, v13
	v_cndmask_b32_e64 v33, v5, v33, s[0:1]
	v_pk_fma_f32 v[4:5], v[34:35], s[42:43], v[22:23] op_sel_hi:[1,0,0]
	v_pk_mul_f32 v[6:7], v[6:7], s[64:65] op_sel_hi:[1,0]
	v_pk_fma_f32 v[4:5], v[34:35], v[4:5], s[48:49] op_sel_hi:[1,1,0]
	v_exp_f32_e32 v6, v6
	v_exp_f32_e32 v7, v7
	v_pk_fma_f32 v[4:5], v[34:35], v[4:5], s[50:51] op_sel_hi:[1,1,0]
	v_pk_fma_f32 v[4:5], v[34:35], v[4:5], s[56:57] op_sel_hi:[1,1,0]
	v_fma_f32 v12, |v38|, s40, 1.0
	v_fma_f32 v13, |v39|, s40, 1.0
	v_pk_mul_f32 v[4:5], v[34:35], v[4:5]
	v_rcp_f32_e32 v40, v12
	v_rcp_f32_e32 v41, v13
	v_pk_mul_f32 v[4:5], v[6:7], v[4:5]
	v_max_f32_e32 v104, 0, v36
	v_fma_f32 v35, -|v36|, v4, v104
	v_max_f32_e32 v105, 0, v37
	v_fma_f32 v13, -|v37|, v5, v105
	v_lshlrev_b32_e32 v42, 16, v14
	v_and_b32_e32 v43, 0xffff0000, v14
	v_lshlrev_b32_e32 v44, 16, v15
	v_pk_fma_f32 v[4:5], v[40:41], s[42:43], v[22:23] op_sel_hi:[1,0,0]
	v_pk_mul_f32 v[6:7], v[38:39], v[38:39]
	v_pk_fma_f32 v[4:5], v[40:41], v[4:5], s[48:49] op_sel_hi:[1,1,0]
	v_pk_mul_f32 v[6:7], v[6:7], s[64:65] op_sel_hi:[1,0]
	v_pk_fma_f32 v[4:5], v[40:41], v[4:5], s[50:51] op_sel_hi:[1,1,0]
	v_exp_f32_e32 v6, v6
	v_exp_f32_e32 v7, v7
	v_pk_fma_f32 v[4:5], v[40:41], v[4:5], s[56:57] op_sel_hi:[1,1,0]
	v_pk_mul_f32 v[4:5], v[40:41], v[4:5]
	v_fma_f32 v40, |v42|, s40, 1.0
	v_fma_f32 v41, |v43|, s40, 1.0
	v_pk_mul_f32 v[4:5], v[6:7], v[4:5]
	v_rcp_f32_e32 v40, v40
	v_rcp_f32_e32 v41, v41
	v_max_f32_e32 v106, 0, v38
	v_fma_f32 v37, -|v38|, v4, v106
	v_max_f32_e32 v107, 0, v39
	v_fma_f32 v39, -|v39|, v5, v107
	v_and_b32_e32 v45, 0xffff0000, v15
	v_pk_mul_f32 v[6:7], v[42:43], v[42:43]
	v_pk_fma_f32 v[4:5], v[40:41], s[42:43], v[22:23] op_sel_hi:[1,0,0]
	v_pk_mul_f32 v[6:7], v[6:7], s[64:65] op_sel_hi:[1,0]
	v_pk_fma_f32 v[4:5], v[40:41], v[4:5], s[48:49] op_sel_hi:[1,1,0]
	v_exp_f32_e32 v6, v6
	v_exp_f32_e32 v7, v7
	v_pk_fma_f32 v[4:5], v[40:41], v[4:5], s[50:51] op_sel_hi:[1,1,0]
	v_fma_f32 v14, |v44|, s40, 1.0
	v_fma_f32 v15, |v45|, s40, 1.0
	v_pk_fma_f32 v[4:5], v[40:41], v[4:5], s[56:57] op_sel_hi:[1,1,0]
	v_rcp_f32_e32 v46, v14
	v_pk_mul_f32 v[4:5], v[40:41], v[4:5]
	v_rcp_f32_e32 v47, v15
	v_pk_mul_f32 v[4:5], v[6:7], v[4:5]
	v_max_f32_e32 v108, 0, v42
	v_fma_f32 v41, -|v42|, v4, v108
	v_max_f32_e32 v109, 0, v43
	v_fma_f32 v15, -|v43|, v5, v109
	v_mul_f32_e32 v30, v31, v31
	s_waitcnt vmcnt(0)
	v_lshlrev_b32_e32 v48, 16, v8
	v_and_b32_e32 v49, 0xffff0000, v8
	v_pk_fma_f32 v[4:5], v[46:47], s[42:43], v[22:23] op_sel_hi:[1,0,0]
	v_pk_mul_f32 v[6:7], v[44:45], v[44:45]
	v_pk_fma_f32 v[4:5], v[46:47], v[4:5], s[48:49] op_sel_hi:[1,1,0]
	v_pk_mul_f32 v[6:7], v[6:7], s[64:65] op_sel_hi:[1,0]
	v_pk_fma_f32 v[4:5], v[46:47], v[4:5], s[50:51] op_sel_hi:[1,1,0]
	v_exp_f32_e32 v6, v6
	v_exp_f32_e32 v7, v7
	v_pk_fma_f32 v[4:5], v[46:47], v[4:5], s[56:57] op_sel_hi:[1,1,0]
	v_pk_mul_f32 v[4:5], v[46:47], v[4:5]
	v_fma_f32 v46, |v48|, s40, 1.0
	v_fma_f32 v47, |v49|, s40, 1.0
	v_pk_mul_f32 v[4:5], v[6:7], v[4:5]
	v_rcp_f32_e32 v46, v46
	v_rcp_f32_e32 v47, v47
	v_max_f32_e32 v110, 0, v44
	v_fma_f32 v43, -|v44|, v4, v110
	v_max_f32_e32 v111, 0, v45
	v_fma_f32 v45, -|v45|, v5, v111
	v_lshlrev_b32_e32 v60, 16, v9
	v_and_b32_e32 v61, 0xffff0000, v9
	v_pk_mul_f32 v[6:7], v[48:49], v[48:49]
	v_pk_fma_f32 v[4:5], v[46:47], s[42:43], v[22:23] op_sel_hi:[1,0,0]
	v_pk_mul_f32 v[6:7], v[6:7], s[64:65] op_sel_hi:[1,0]
	v_pk_fma_f32 v[4:5], v[46:47], v[4:5], s[48:49] op_sel_hi:[1,1,0]
	v_exp_f32_e32 v6, v6
	v_exp_f32_e32 v7, v7
	v_pk_fma_f32 v[4:5], v[46:47], v[4:5], s[50:51] op_sel_hi:[1,1,0]
	v_pk_fma_f32 v[4:5], v[46:47], v[4:5], s[56:57] op_sel_hi:[1,1,0]
	v_fma_f32 v8, |v60|, s40, 1.0
	v_fma_f32 v9, |v61|, s40, 1.0
	v_pk_mul_f32 v[4:5], v[46:47], v[4:5]
	v_rcp_f32_e32 v62, v8
	v_pk_mul_f32 v[46:47], v[6:7], v[4:5]
	global_load_dwordx4 v[4:7], v[24:25], off offset:1536
	v_rcp_f32_e32 v63, v9
	v_max_f32_e32 v113, 0, v49
	v_fma_f32 v9, -|v49|, v47, v113
	v_max_f32_e32 v112, 0, v48
	v_fma_f32 v47, -|v48|, v46, v112
	v_lshlrev_b32_e32 v66, 16, v11
	v_and_b32_e32 v67, 0xffff0000, v11
	v_pk_fma_f32 v[48:49], v[62:63], s[42:43], v[22:23] op_sel_hi:[1,0,0]
	v_and_b32_e32 v11, 0x7fffffff, v67
	v_pk_fma_f32 v[48:49], v[62:63], v[48:49], s[48:49] op_sel_hi:[1,1,0]
	v_pk_mul_f32 v[50:51], v[60:61], v[60:61]
	v_pk_fma_f32 v[48:49], v[62:63], v[48:49], s[50:51] op_sel_hi:[1,1,0]
	v_pk_mul_f32 v[50:51], v[50:51], s[64:65] op_sel_hi:[1,0]
	v_pk_fma_f32 v[48:49], v[62:63], v[48:49], s[56:57] op_sel_hi:[1,1,0]
	v_exp_f32_e32 v50, v50
	v_exp_f32_e32 v51, v51
	v_pk_mul_f32 v[48:49], v[62:63], v[48:49]
	v_lshlrev_b32_e32 v62, 16, v10
	v_and_b32_e32 v63, 0xffff0000, v10
	v_fma_f32 v64, |v62|, s40, 1.0
	v_fma_f32 v65, |v63|, s40, 1.0
	v_pk_mul_f32 v[48:49], v[50:51], v[48:49]
	v_rcp_f32_e32 v64, v64
	v_rcp_f32_e32 v65, v65
	v_max_f32_e32 v115, 0, v61
	v_fma_f32 v51, -|v61|, v49, v115
	v_max_f32_e32 v114, 0, v60
	v_fma_f32 v49, -|v60|, v48, v114
	v_and_b32_e32 v10, 0x7fffffff, v66
	v_pk_fma_f32 v[10:11], v[10:11], s[40:41], 1.0 op_sel_hi:[1,0,0]
	v_pk_mul_f32 v[60:61], v[62:63], v[62:63]
	v_rcp_f32_e32 v68, v10
	v_pk_fma_f32 v[52:53], v[64:65], s[42:43], v[22:23] op_sel_hi:[1,0,0]
	v_pk_mul_f32 v[60:61], v[60:61], s[64:65] op_sel_hi:[1,0]
	v_pk_fma_f32 v[52:53], v[64:65], v[52:53], s[48:49] op_sel_hi:[1,1,0]
	v_exp_f32_e32 v60, v60
	v_exp_f32_e32 v61, v61
	v_pk_fma_f32 v[52:53], v[64:65], v[52:53], s[50:51] op_sel_hi:[1,1,0]
	v_rcp_f32_e32 v69, v11
	v_pk_fma_f32 v[52:53], v[64:65], v[52:53], s[56:57] op_sel_hi:[1,1,0]
	v_pk_mul_f32 v[52:53], v[64:65], v[52:53]
	v_mul_f32_e32 v32, v33, v33
	v_pk_mul_f32 v[52:53], v[60:61], v[52:53]
	v_mul_f32_e32 v34, v35, v35
	v_max_f32_e32 v117, 0, v63
	v_fma_f32 v11, -|v63|, v53, v117
	v_max_f32_e32 v116, 0, v62
	v_fma_f32 v53, -|v62|, v52, v116
	v_mul_f32_e32 v12, v13, v13
	v_pk_mul_f32 v[62:63], v[66:67], v[66:67]
	v_pk_add_f32 v[28:29], v[30:31], v[32:33]
	v_pk_fma_f32 v[60:61], v[68:69], s[42:43], v[22:23] op_sel_hi:[1,0,0]
	v_pk_mul_f32 v[62:63], v[62:63], s[64:65] op_sel_hi:[1,0]
	v_pk_fma_f32 v[60:61], v[68:69], v[60:61], s[48:49] op_sel_hi:[1,1,0]
	v_exp_f32_e32 v62, v62
	v_exp_f32_e32 v63, v63
	v_pk_fma_f32 v[60:61], v[68:69], v[60:61], s[50:51] op_sel_hi:[1,1,0]
	v_pk_fma_f32 v[60:61], v[68:69], v[60:61], s[56:57] op_sel_hi:[1,1,0]
	v_mul_f32_e32 v36, v37, v37
	v_pk_mul_f32 v[60:61], v[68:69], v[60:61]
	v_mul_f32_e32 v38, v39, v39
	v_pk_mul_f32 v[60:61], v[62:63], v[60:61]
	v_pk_add_f32 v[26:27], v[28:29], v[26:27]
	v_max_f32_e32 v80, 0, v66
	v_fma_f32 v71, -|v66|, v60, v80
	v_max_f32_e32 v81, 0, v67
	v_fma_f32 v65, -|v67|, v61, v81
	global_load_dwordx4 v[60:63], v[24:25], off offset:1792
	v_pk_add_f32 v[12:13], v[34:35], v[12:13]
	v_mul_f32_e32 v40, v41, v41
	s_waitcnt vmcnt(1)
	v_lshlrev_b32_e32 v24, 16, v4
	v_and_b32_e32 v25, 0xffff0000, v4
	v_fma_f32 v72, |v24|, s40, 1.0
	v_fma_f32 v73, |v25|, s40, 1.0
	v_pk_mul_f32 v[68:69], v[24:25], v[24:25]
	v_rcp_f32_e32 v72, v72
	v_rcp_f32_e32 v73, v73
	v_mul_f32_e32 v14, v15, v15
	v_pk_mul_f32 v[68:69], v[68:69], s[64:65] op_sel_hi:[1,0]
	v_pk_add_f32 v[12:13], v[12:13], v[26:27]
	v_pk_fma_f32 v[66:67], v[72:73], s[42:43], v[22:23] op_sel_hi:[1,0,0]
	v_pk_add_f32 v[26:27], v[36:37], v[38:39]
	v_mul_f32_e32 v42, v43, v43
	v_mul_f32_e32 v44, v45, v45
	v_pk_fma_f32 v[66:67], v[72:73], v[66:67], s[48:49] op_sel_hi:[1,1,0]
	v_exp_f32_e32 v68, v68
	v_exp_f32_e32 v69, v69
	v_pk_add_f32 v[12:13], v[26:27], v[12:13]
	v_pk_add_f32 v[14:15], v[40:41], v[14:15]
	v_mul_f32_e32 v46, v47, v47
	v_mul_f32_e32 v8, v9, v9
	v_pk_fma_f32 v[66:67], v[72:73], v[66:67], s[50:51] op_sel_hi:[1,1,0]
	v_pk_add_f32 v[12:13], v[14:15], v[12:13]
	v_pk_add_f32 v[14:15], v[42:43], v[44:45]
	v_mul_f32_e32 v48, v49, v49
	v_mul_f32_e32 v50, v51, v51
	v_pk_fma_f32 v[66:67], v[72:73], v[66:67], s[56:57] op_sel_hi:[1,1,0]
	v_pk_add_f32 v[12:13], v[14:15], v[12:13]
	v_pk_add_f32 v[8:9], v[46:47], v[8:9]
	v_pk_mul_f32 v[66:67], v[72:73], v[66:67]
	v_pk_add_f32 v[8:9], v[8:9], v[12:13]
	v_pk_add_f32 v[12:13], v[48:49], v[50:51]
	v_lshlrev_b32_e32 v4, 16, v5
	v_and_b32_e32 v5, 0xffff0000, v5
	v_pk_mul_f32 v[66:67], v[68:69], v[66:67]
	v_pk_add_f32 v[8:9], v[12:13], v[8:9]
	v_max_f32_e32 v82, 0, v24
	v_fma_f32 v73, -|v24|, v66, v82
	v_max_f32_e32 v83, 0, v25
	v_fma_f32 v25, -|v25|, v67, v83
	v_fma_f32 v12, |v4|, s40, 1.0
	v_fma_f32 v13, |v5|, s40, 1.0
	v_mul_f32_e32 v52, v53, v53
	v_mul_f32_e32 v10, v11, v11
	v_rcp_f32_e32 v12, v12
	v_rcp_f32_e32 v13, v13
	v_mul_f32_e32 v70, v71, v71
	v_mul_f32_e32 v64, v65, v65
	v_pk_add_f32 v[10:11], v[52:53], v[10:11]
	v_mul_f32_e32 v72, v73, v73
	v_mul_f32_e32 v24, v25, v25
	v_pk_add_f32 v[8:9], v[10:11], v[8:9]
	v_pk_add_f32 v[10:11], v[70:71], v[64:65]
	v_pk_mul_f32 v[14:15], v[4:5], v[4:5]
	v_pk_add_f32 v[8:9], v[10:11], v[8:9]
	v_pk_add_f32 v[10:11], v[72:73], v[24:25]
	v_pk_mul_f32 v[14:15], v[14:15], s[64:65] op_sel_hi:[1,0]
	v_pk_add_f32 v[8:9], v[10:11], v[8:9]
	v_pk_fma_f32 v[10:11], v[12:13], s[42:43], v[22:23] op_sel_hi:[1,0,0]
	v_exp_f32_e32 v14, v14
	v_pk_fma_f32 v[10:11], v[12:13], v[10:11], s[48:49] op_sel_hi:[1,1,0]
	v_exp_f32_e32 v15, v15
	v_pk_fma_f32 v[10:11], v[12:13], v[10:11], s[50:51] op_sel_hi:[1,1,0]
	v_pk_fma_f32 v[10:11], v[12:13], v[10:11], s[56:57] op_sel_hi:[1,1,0]
	s_waitcnt vmcnt(0)
	v_lshlrev_b32_e32 v28, 16, v60
	v_pk_mul_f32 v[10:11], v[12:13], v[10:11]
	v_and_b32_e32 v29, 0xffff0000, v60
	v_pk_mul_f32 v[10:11], v[14:15], v[10:11]
	v_and_b32_e32 v31, 0x7fffffff, v29
	v_max_f32_e32 v84, 0, v4
	v_fma_f32 v15, -|v4|, v10, v84
	v_max_f32_e32 v85, 0, v5
	v_fma_f32 v5, -|v5|, v11, v85
	v_and_b32_e32 v30, 0x7fffffff, v28
	v_lshlrev_b32_e32 v10, 16, v6
	v_and_b32_e32 v12, 0x7fffffff, v10
	v_and_b32_e32 v11, 0xffff0000, v6
	v_and_b32_e32 v13, 0x7fffffff, v11
	v_pk_fma_f32 v[12:13], v[12:13], s[40:41], 1.0 op_sel_hi:[1,0,0]
	v_mul_f32_e32 v14, v15, v15
	v_rcp_f32_e32 v12, v12
	v_rcp_f32_e32 v13, v13
	v_mul_f32_e32 v4, v5, v5
	v_pk_mul_f32 v[24:25], v[10:11], v[10:11]
	v_pk_add_f32 v[4:5], v[14:15], v[4:5]
	v_pk_fma_f32 v[14:15], v[12:13], s[42:43], v[22:23] op_sel_hi:[1,0,0]
	v_pk_mul_f32 v[24:25], v[24:25], s[64:65] op_sel_hi:[1,0]
	v_pk_fma_f32 v[14:15], v[12:13], v[14:15], s[48:49] op_sel_hi:[1,1,0]
	v_exp_f32_e32 v24, v24
	v_exp_f32_e32 v25, v25
	v_pk_fma_f32 v[14:15], v[12:13], v[14:15], s[50:51] op_sel_hi:[1,1,0]
	v_lshlrev_b32_e32 v6, 16, v7
	v_and_b32_e32 v7, 0xffff0000, v7
	v_pk_fma_f32 v[14:15], v[12:13], v[14:15], s[56:57] op_sel_hi:[1,1,0]
	v_pk_mul_f32 v[12:13], v[12:13], v[14:15]
	v_fma_f32 v26, |v6|, s40, 1.0
	v_fma_f32 v27, |v7|, s40, 1.0
	v_pk_mul_f32 v[12:13], v[24:25], v[12:13]
	v_rcp_f32_e32 v26, v26
	v_rcp_f32_e32 v27, v27
	v_max_f32_e32 v86, 0, v10
	v_fma_f32 v25, -|v10|, v12, v86
	v_max_f32_e32 v90, 0, v11
	v_fma_f32 v11, -|v11|, v13, v90
	v_pk_fma_f32 v[30:31], v[30:31], s[40:41], 1.0 op_sel_hi:[1,0,0]
	v_lshlrev_b32_e32 v32, 16, v61
	v_rcp_f32_e32 v30, v30
	v_rcp_f32_e32 v31, v31
	v_pk_mul_f32 v[14:15], v[6:7], v[6:7]
	v_pk_fma_f32 v[12:13], v[26:27], s[42:43], v[22:23] op_sel_hi:[1,0,0]
	v_pk_mul_f32 v[14:15], v[14:15], s[64:65] op_sel_hi:[1,0]
	v_pk_fma_f32 v[12:13], v[26:27], v[12:13], s[48:49] op_sel_hi:[1,1,0]
	v_exp_f32_e32 v14, v14
	v_exp_f32_e32 v15, v15
	v_pk_fma_f32 v[12:13], v[26:27], v[12:13], s[50:51] op_sel_hi:[1,1,0]
	v_pk_fma_f32 v[12:13], v[26:27], v[12:13], s[56:57] op_sel_hi:[1,1,0]
	v_and_b32_e32 v33, 0xffff0000, v61
	v_pk_mul_f32 v[12:13], v[26:27], v[12:13]
	v_pk_mul_f32 v[12:13], v[14:15], v[12:13]
	v_max_f32_e32 v91, 0, v6
	v_fma_f32 v27, -|v6|, v12, v91
	v_max_f32_e32 v92, 0, v7
	v_fma_f32 v7, -|v7|, v13, v92
	v_fma_f32 v34, |v32|, s40, 1.0
	v_fma_f32 v35, |v33|, s40, 1.0
	v_rcp_f32_e32 v34, v34
	v_rcp_f32_e32 v35, v35
	v_pk_mul_f32 v[14:15], v[28:29], v[28:29]
	v_pk_fma_f32 v[12:13], v[30:31], s[42:43], v[22:23] op_sel_hi:[1,0,0]
	v_pk_mul_f32 v[14:15], v[14:15], s[64:65] op_sel_hi:[1,0]
	v_pk_fma_f32 v[12:13], v[30:31], v[12:13], s[48:49] op_sel_hi:[1,1,0]
	v_exp_f32_e32 v14, v14
	v_exp_f32_e32 v15, v15
	v_pk_fma_f32 v[12:13], v[30:31], v[12:13], s[50:51] op_sel_hi:[1,1,0]
	v_pk_fma_f32 v[12:13], v[30:31], v[12:13], s[56:57] op_sel_hi:[1,1,0]
	v_lshlrev_b32_e32 v36, 16, v62
	v_pk_mul_f32 v[12:13], v[30:31], v[12:13]
	v_and_b32_e32 v37, 0xffff0000, v62
	v_pk_mul_f32 v[12:13], v[14:15], v[12:13]
	v_max_f32_e32 v93, 0, v28
	v_fma_f32 v31, -|v28|, v12, v93
	v_max_f32_e32 v94, 0, v29
	v_fma_f32 v13, -|v29|, v13, v94
	v_pk_mul_f32 v[28:29], v[32:33], v[32:33]
	v_fma_f32 v38, |v36|, s40, 1.0
	v_fma_f32 v39, |v37|, s40, 1.0
	v_pk_fma_f32 v[14:15], v[34:35], s[42:43], v[22:23] op_sel_hi:[1,0,0]
	v_pk_mul_f32 v[28:29], v[28:29], s[64:65] op_sel_hi:[1,0]
	v_pk_fma_f32 v[14:15], v[34:35], v[14:15], s[48:49] op_sel_hi:[1,1,0]
	v_exp_f32_e32 v28, v28
	v_exp_f32_e32 v29, v29
	v_pk_fma_f32 v[14:15], v[34:35], v[14:15], s[50:51] op_sel_hi:[1,1,0]
	v_rcp_f32_e32 v38, v38
	v_pk_fma_f32 v[14:15], v[34:35], v[14:15], s[56:57] op_sel_hi:[1,1,0]
	v_rcp_f32_e32 v39, v39
	v_pk_mul_f32 v[14:15], v[34:35], v[14:15]
	v_pk_mul_f32 v[14:15], v[28:29], v[14:15]
	v_lshlrev_b32_e32 v40, 16, v63
	v_max_f32_e32 v95, 0, v32
	v_fma_f32 v35, -|v32|, v14, v95
	v_max_f32_e32 v96, 0, v33
	v_fma_f32 v15, -|v33|, v15, v96
	v_and_b32_e32 v41, 0xffff0000, v63
	v_pk_mul_f32 v[32:33], v[36:37], v[36:37]
	v_pk_fma_f32 v[28:29], v[38:39], s[42:43], v[22:23] op_sel_hi:[1,0,0]
	v_pk_mul_f32 v[32:33], v[32:33], s[64:65] op_sel_hi:[1,0]
	v_pk_fma_f32 v[28:29], v[38:39], v[28:29], s[48:49] op_sel_hi:[1,1,0]
	v_exp_f32_e32 v32, v32
	v_exp_f32_e32 v33, v33
	v_pk_fma_f32 v[28:29], v[38:39], v[28:29], s[50:51] op_sel_hi:[1,1,0]
	v_pk_fma_f32 v[28:29], v[38:39], v[28:29], s[56:57] op_sel_hi:[1,1,0]
	v_fma_f32 v42, |v40|, s40, 1.0
	v_fma_f32 v43, |v41|, s40, 1.0
	v_pk_mul_f32 v[28:29], v[38:39], v[28:29]
	v_rcp_f32_e32 v42, v42
	v_pk_mul_f32 v[28:29], v[32:33], v[28:29]
	v_rcp_f32_e32 v43, v43
	v_max_f32_e32 v97, 0, v36
	v_fma_f32 v39, -|v36|, v28, v97
	v_max_f32_e32 v98, 0, v37
	v_fma_f32 v29, -|v37|, v29, v98
	v_pk_fma_f32 v[22:23], v[42:43], s[42:43], v[22:23] op_sel_hi:[1,0,0]
	v_mul_f32_e32 v24, v25, v25
	v_pk_fma_f32 v[22:23], v[42:43], v[22:23], s[48:49] op_sel_hi:[1,1,0]
	v_mul_f32_e32 v10, v11, v11
	v_pk_mul_f32 v[32:33], v[40:41], v[40:41]
	v_pk_fma_f32 v[22:23], v[42:43], v[22:23], s[50:51] op_sel_hi:[1,1,0]
	v_pk_mul_f32 v[32:33], v[32:33], s[64:65] op_sel_hi:[1,0]
	v_pk_fma_f32 v[22:23], v[42:43], v[22:23], s[56:57] op_sel_hi:[1,1,0]
	v_exp_f32_e32 v32, v32
	v_exp_f32_e32 v33, v33
	v_pk_mul_f32 v[22:23], v[42:43], v[22:23]
	v_mul_f32_e32 v26, v27, v27
	v_mul_f32_e32 v6, v7, v7
	v_pk_mul_f32 v[22:23], v[32:33], v[22:23]
	v_pk_add_f32 v[4:5], v[4:5], v[8:9]
	v_pk_add_f32 v[8:9], v[24:25], v[10:11]
	v_mul_f32_e32 v30, v31, v31
	v_mul_f32_e32 v12, v13, v13
	v_max_f32_e32 v99, 0, v40
	v_fma_f32 v37, -|v40|, v22, v99
	v_max_f32_e32 v100, 0, v41
	v_fma_f32 v23, -|v41|, v23, v100
	v_pk_add_f32 v[4:5], v[8:9], v[4:5]
	v_pk_add_f32 v[6:7], v[26:27], v[6:7]
	v_mul_f32_e32 v34, v35, v35
	v_mul_f32_e32 v14, v15, v15
	v_pk_add_f32 v[4:5], v[6:7], v[4:5]
	v_pk_add_f32 v[6:7], v[30:31], v[12:13]
	v_mul_f32_e32 v38, v39, v39
	v_mul_f32_e32 v28, v29, v29
	v_pk_add_f32 v[4:5], v[6:7], v[4:5]
	v_pk_add_f32 v[6:7], v[34:35], v[14:15]
	v_mul_f32_e32 v36, v37, v37
	v_mul_f32_e32 v22, v23, v23
	v_pk_add_f32 v[4:5], v[6:7], v[4:5]
	v_pk_add_f32 v[6:7], v[38:39], v[28:29]
	s_nop 0
	v_pk_add_f32 v[4:5], v[6:7], v[4:5]
	v_pk_add_f32 v[6:7], v[36:37], v[22:23]
	s_nop 0
	v_pk_add_f32 v[4:5], v[6:7], v[4:5]
	ds_bpermute_b32 v7, v56, v5
	ds_bpermute_b32 v6, v56, v4
	s_waitcnt lgkmcnt(0)
	v_pk_add_f32 v[4:5], v[4:5], v[6:7]
	ds_bpermute_b32 v7, v57, v5
	ds_bpermute_b32 v6, v57, v4
	s_waitcnt lgkmcnt(0)
	v_pk_add_f32 v[4:5], v[4:5], v[6:7]
	ds_bpermute_b32 v7, v58, v5
	ds_bpermute_b32 v6, v58, v4
	s_waitcnt lgkmcnt(0)
	v_pk_add_f32 v[4:5], v[4:5], v[6:7]
	ds_bpermute_b32 v7, v59, v5
	ds_bpermute_b32 v6, v59, v4
	s_and_saveexec_b64 s[8:9], vcc
	s_cbranch_execz .LBB0_449
	s_waitcnt lgkmcnt(0)
	v_pk_add_f32 v[4:5], v[4:5], v[6:7]
	s_nop 0
	v_pk_mul_f32 v[4:5], v[4:5], s[66:67] op_sel_hi:[1,0]
	s_nop 0
	v_fma_f32 v4, -v5, v5, v4
	v_max_f32_e32 v4, 0, v4
	v_add_f32_e32 v4, 0x358637bd, v4
	v_mul_f32_e32 v6, 0x4b800000, v4
	v_cmp_gt_f32_e64 s[0:1], s36, v4
	s_nop 1
	v_cndmask_b32_e64 v4, v4, v6, s[0:1]
	v_rsq_f32_e32 v4, v4
	v_lshl_add_u32 v6, v20, 2, 0
	v_add_u32_e32 v7, 0x11000, v6
	ds_write_b32 v7, v5
	v_mul_f32_e32 v5, 0x45800000, v4
	v_cndmask_b32_e64 v4, v4, v5, s[0:1]
	v_add_u32_e32 v5, 0x11200, v6
	ds_write_b32 v5, v4
.LBB0_449:
	s_or_b64 exec, exec, s[8:9]
	v_or_b32_e32 v16, 12, v16
	v_ashrrev_i32_e32 v17, 31, v16
	v_lshl_add_u64 v[4:5], s[6:7], 0, v[16:17]
	v_lshlrev_b64 v[4:5], 11, v[4:5]
	v_lshl_add_u64 v[4:5], s[4:5], 0, v[4:5]
	v_mov_b32_e32 v19, v2
	v_lshl_add_u64 v[20:21], v[4:5], 0, v[18:19]
	global_load_dwordx4 v[8:11], v[20:21], off
	s_waitcnt lgkmcnt(0)
	global_load_dwordx4 v[4:7], v[20:21], off offset:256
	v_mov_b64_e32 v[18:19], s[44:45]
	v_mov_b32_e32 v13, v2
	s_waitcnt vmcnt(1)
	v_lshlrev_b32_e32 v24, 16, v10
	v_and_b32_e32 v25, 0xffff0000, v10
	v_and_b32_e32 v15, 0xffff0000, v8
	v_and_b32_e32 v23, 0xffff0000, v9
	v_lshlrev_b32_e32 v22, 16, v9
	v_lshlrev_b32_e32 v14, 16, v8
	v_lshlrev_b32_e32 v8, 16, v11
	v_and_b32_e32 v9, 0xffff0000, v11
	v_fma_f32 v10, |v24|, s40, 1.0
	v_fma_f32 v11, |v25|, s40, 1.0
	v_fma_f32 v28, |v14|, s40, 1.0
	v_fma_f32 v29, |v15|, s40, 1.0
	v_rcp_f32_e32 v10, v10
	v_rcp_f32_e32 v11, v11
	v_fma_f32 v32, |v22|, s40, 1.0
	v_fma_f32 v33, |v23|, s40, 1.0
	v_rcp_f32_e32 v28, v28
	v_rcp_f32_e32 v29, v29
	v_rcp_f32_e32 v32, v32
	v_rcp_f32_e32 v33, v33
	v_pk_mul_f32 v[26:27], v[24:25], v[24:25]
	v_pk_mul_f32 v[30:31], v[14:15], v[14:15]
	v_pk_mul_f32 v[26:27], v[26:27], s[64:65] op_sel_hi:[1,0]
	v_pk_fma_f32 v[40:41], v[10:11], s[42:43], v[18:19] op_sel_hi:[1,0,0]
	v_pk_mul_f32 v[34:35], v[22:23], v[22:23]
	v_pk_mul_f32 v[30:31], v[30:31], s[64:65] op_sel_hi:[1,0]
	v_exp_f32_e32 v26, v26
	v_exp_f32_e32 v27, v27
	v_pk_fma_f32 v[42:43], v[28:29], s[42:43], v[18:19] op_sel_hi:[1,0,0]
	v_pk_fma_f32 v[40:41], v[10:11], v[40:41], s[48:49] op_sel_hi:[1,1,0]
	v_pk_mul_f32 v[34:35], v[34:35], s[64:65] op_sel_hi:[1,0]
	v_exp_f32_e32 v30, v30
	v_exp_f32_e32 v31, v31
	v_pk_fma_f32 v[44:45], v[32:33], s[42:43], v[18:19] op_sel_hi:[1,0,0]
	v_pk_fma_f32 v[42:43], v[28:29], v[42:43], s[48:49] op_sel_hi:[1,1,0]
	v_pk_fma_f32 v[40:41], v[10:11], v[40:41], s[50:51] op_sel_hi:[1,1,0]
	v_exp_f32_e32 v34, v34
	v_exp_f32_e32 v35, v35
	v_pk_fma_f32 v[44:45], v[32:33], v[44:45], s[48:49] op_sel_hi:[1,1,0]
	v_pk_fma_f32 v[42:43], v[28:29], v[42:43], s[50:51] op_sel_hi:[1,1,0]
	v_pk_fma_f32 v[40:41], v[10:11], v[40:41], s[56:57] op_sel_hi:[1,1,0]
	v_pk_fma_f32 v[44:45], v[32:33], v[44:45], s[50:51] op_sel_hi:[1,1,0]
	v_pk_fma_f32 v[42:43], v[28:29], v[42:43], s[56:57] op_sel_hi:[1,1,0]
	v_pk_mul_f32 v[10:11], v[10:11], v[40:41]
	v_pk_fma_f32 v[44:45], v[32:33], v[44:45], s[56:57] op_sel_hi:[1,1,0]
	v_pk_mul_f32 v[28:29], v[28:29], v[42:43]
	v_pk_mul_f32 v[10:11], v[26:27], v[10:11]
	v_pk_mul_f32 v[32:33], v[32:33], v[44:45]
	v_pk_mul_f32 v[26:27], v[30:31], v[28:29]
	v_max_f32_e32 v104, 0, v24
	v_fma_f32 v41, -|v24|, v10, v104
	v_max_f32_e32 v105, 0, v25
	v_fma_f32 v11, -|v25|, v11, v105
	v_pk_mul_f32 v[28:29], v[34:35], v[32:33]
	v_max_f32_e32 v106, 0, v22
	v_fma_f32 v25, -|v22|, v28, v106
	v_max_f32_e32 v107, 0, v23
	v_fma_f32 v23, -|v23|, v29, v107
	v_max_f32_e32 v108, 0, v14
	v_fma_f32 v24, -|v14|, v26, v108
	v_max_f32_e32 v109, 0, v15
	v_fma_f32 v15, -|v15|, v27, v109
	v_fma_f32 v36, |v8|, s40, 1.0
	v_fma_f32 v37, |v9|, s40, 1.0
	v_mov_b32_e32 v14, v25
	v_rcp_f32_e32 v36, v36
	v_rcp_f32_e32 v37, v37
	v_mul_f32_e32 v26, v24, v24
	v_mov_b32_e32 v27, v25
	v_mul_f32_e32 v22, v15, v15
	v_mul_f32_e32 v12, v23, v23
	v_pk_add_f32 v[22:23], v[26:27], v[22:23]
	v_pk_mul_f32 v[26:27], v[24:25], v[14:15] op_sel:[1,0] op_sel_hi:[0,1]
	v_pk_add_f32 v[14:15], v[24:25], v[14:15] op_sel:[1,0] op_sel_hi:[0,1]
	v_pk_mul_f32 v[38:39], v[8:9], v[8:9]
	v_mov_b32_e32 v27, v15
	v_pk_mul_f32 v[38:39], v[38:39], s[64:65] op_sel_hi:[1,0]
	v_pk_fma_f32 v[46:47], v[36:37], s[42:43], v[18:19] op_sel_hi:[1,0,0]
	v_mul_f32_e32 v40, v41, v41
	v_mul_f32_e32 v10, v11, v11
	v_pk_add_f32 v[12:13], v[26:27], v[12:13]
	v_exp_f32_e32 v38, v38
	v_pk_fma_f32 v[46:47], v[36:37], v[46:47], s[48:49] op_sel_hi:[1,1,0]
	v_pk_add_f32 v[10:11], v[40:41], v[10:11]
	v_pk_add_f32 v[12:13], v[22:23], v[12:13]
	v_exp_f32_e32 v39, v39
	v_pk_add_f32 v[22:23], v[10:11], v[12:13]
	v_pk_fma_f32 v[10:11], v[36:37], v[46:47], s[50:51] op_sel_hi:[1,1,0]
	v_pk_fma_f32 v[10:11], v[36:37], v[10:11], s[56:57] op_sel_hi:[1,1,0]
	s_nop 0
	v_pk_mul_f32 v[10:11], v[36:37], v[10:11]
	s_waitcnt vmcnt(0)
	v_lshlrev_b32_e32 v36, 16, v6
	v_pk_mul_f32 v[10:11], v[38:39], v[10:11]
	v_and_b32_e32 v37, 0xffff0000, v6
	v_max_f32_e32 v110, 0, v8
	v_fma_f32 v15, -|v8|, v10, v110
	v_max_f32_e32 v111, 0, v9
	v_fma_f32 v9, -|v9|, v11, v111
	v_and_b32_e32 v33, 0x7fffffff, v37
	v_lshlrev_b32_e32 v12, 16, v4
	v_and_b32_e32 v10, 0x7fffffff, v12
	v_and_b32_e32 v13, 0xffff0000, v4
	v_and_b32_e32 v11, 0x7fffffff, v13
	v_pk_fma_f32 v[10:11], v[10:11], s[40:41], 1.0 op_sel_hi:[1,0,0]
	v_mul_f32_e32 v14, v15, v15
	v_rcp_f32_e32 v10, v10
	v_rcp_f32_e32 v11, v11
	v_mul_f32_e32 v8, v9, v9
	v_pk_add_f32 v[24:25], v[14:15], v[8:9]
	v_pk_mul_f32 v[14:15], v[12:13], v[12:13]
	v_pk_fma_f32 v[8:9], v[10:11], s[42:43], v[18:19] op_sel_hi:[1,0,0]
	v_pk_mul_f32 v[14:15], v[14:15], s[64:65] op_sel_hi:[1,0]
	v_pk_fma_f32 v[8:9], v[10:11], v[8:9], s[48:49] op_sel_hi:[1,1,0]
	v_exp_f32_e32 v14, v14
	v_exp_f32_e32 v15, v15
	v_pk_fma_f32 v[8:9], v[10:11], v[8:9], s[50:51] op_sel_hi:[1,1,0]
	v_lshlrev_b32_e32 v4, 16, v5
	v_pk_fma_f32 v[8:9], v[10:11], v[8:9], s[56:57] op_sel_hi:[1,1,0]
	v_and_b32_e32 v5, 0xffff0000, v5
	v_pk_mul_f32 v[8:9], v[10:11], v[8:9]
	v_pk_mul_f32 v[14:15], v[14:15], v[8:9]
	global_load_dwordx4 v[8:11], v[20:21], off offset:512
	v_fma_f32 v30, |v4|, s40, 1.0
	v_fma_f32 v31, |v5|, s40, 1.0
	v_rcp_f32_e32 v30, v30
	v_rcp_f32_e32 v31, v31
	v_max_f32_e32 v112, 0, v12
	v_fma_f32 v27, -|v12|, v14, v112
	v_max_f32_e32 v113, 0, v13
	v_fma_f32 v29, -|v13|, v15, v113
	v_and_b32_e32 v32, 0x7fffffff, v36
	v_pk_fma_f32 v[32:33], v[32:33], s[40:41], 1.0 op_sel_hi:[1,0,0]
	v_pk_fma_f32 v[12:13], v[30:31], s[42:43], v[18:19] op_sel_hi:[1,0,0]
	v_rcp_f32_e32 v34, v32
	v_pk_mul_f32 v[14:15], v[4:5], v[4:5]
	v_pk_fma_f32 v[12:13], v[30:31], v[12:13], s[48:49] op_sel_hi:[1,1,0]
	v_pk_mul_f32 v[14:15], v[14:15], s[64:65] op_sel_hi:[1,0]
	v_pk_fma_f32 v[12:13], v[30:31], v[12:13], s[50:51] op_sel_hi:[1,1,0]
	v_exp_f32_e32 v14, v14
	v_exp_f32_e32 v15, v15
	v_pk_fma_f32 v[12:13], v[30:31], v[12:13], s[56:57] op_sel_hi:[1,1,0]
	v_rcp_f32_e32 v35, v33
	v_pk_mul_f32 v[12:13], v[30:31], v[12:13]
	v_pk_mul_f32 v[12:13], v[14:15], v[12:13]
	v_mul_f32_e32 v26, v27, v27
	v_max_f32_e32 v114, 0, v4
	v_fma_f32 v31, -|v4|, v12, v114
	v_max_f32_e32 v115, 0, v5
	v_fma_f32 v33, -|v5|, v13, v115
	v_mul_f32_e32 v28, v29, v29
	v_pk_fma_f32 v[4:5], v[34:35], s[42:43], v[18:19] op_sel_hi:[1,0,0]
	v_lshlrev_b32_e32 v14, 16, v7
	v_pk_mul_f32 v[12:13], v[36:37], v[36:37]
	v_pk_fma_f32 v[4:5], v[34:35], v[4:5], s[48:49] op_sel_hi:[1,1,0]
	v_pk_mul_f32 v[12:13], v[12:13], s[64:65] op_sel_hi:[1,0]
	v_pk_fma_f32 v[4:5], v[34:35], v[4:5], s[50:51] op_sel_hi:[1,1,0]
	v_exp_f32_e32 v12, v12
	v_exp_f32_e32 v13, v13
	v_and_b32_e32 v15, 0xffff0000, v7
	v_pk_fma_f32 v[4:5], v[34:35], v[4:5], s[56:57] op_sel_hi:[1,1,0]
	v_pk_mul_f32 v[4:5], v[34:35], v[4:5]
	v_fma_f32 v6, |v14|, s40, 1.0
	v_fma_f32 v7, |v15|, s40, 1.0
	v_pk_mul_f32 v[4:5], v[12:13], v[4:5]
	v_rcp_f32_e32 v6, v6
	v_rcp_f32_e32 v7, v7
	v_max_f32_e32 v116, 0, v36
	v_fma_f32 v35, -|v36|, v4, v116
	v_max_f32_e32 v117, 0, v37
	v_fma_f32 v37, -|v37|, v5, v117
	v_mul_f32_e32 v30, v31, v31
	v_mul_f32_e32 v32, v33, v33
	v_pk_add_f32 v[22:23], v[24:25], v[22:23]
	v_pk_add_f32 v[24:25], v[26:27], v[28:29]
	v_pk_mul_f32 v[12:13], v[14:15], v[14:15]
	v_pk_fma_f32 v[4:5], v[6:7], s[42:43], v[18:19] op_sel_hi:[1,0,0]
	v_pk_mul_f32 v[12:13], v[12:13], s[64:65] op_sel_hi:[1,0]
	v_pk_fma_f32 v[4:5], v[6:7], v[4:5], s[48:49] op_sel_hi:[1,1,0]
	v_exp_f32_e32 v12, v12
	v_exp_f32_e32 v13, v13
	v_pk_fma_f32 v[4:5], v[6:7], v[4:5], s[50:51] op_sel_hi:[1,1,0]
	v_pk_fma_f32 v[4:5], v[6:7], v[4:5], s[56:57] op_sel_hi:[1,1,0]
	v_mul_f32_e32 v34, v35, v35
	v_pk_mul_f32 v[4:5], v[6:7], v[4:5]
	v_mul_f32_e32 v36, v37, v37
	v_pk_mul_f32 v[4:5], v[12:13], v[4:5]
	v_pk_add_f32 v[22:23], v[24:25], v[22:23]
	v_max_f32_e32 v80, 0, v14
	v_fma_f32 v39, -|v14|, v4, v80
	v_max_f32_e32 v81, 0, v15
	v_fma_f32 v41, -|v15|, v5, v81
	global_load_dwordx4 v[4:7], v[20:21], off offset:768
	v_pk_add_f32 v[24:25], v[30:31], v[32:33]
	s_waitcnt vmcnt(1)
	v_lshlrev_b32_e32 v44, 16, v8
	v_and_b32_e32 v45, 0xffff0000, v8
	v_fma_f32 v42, |v44|, s40, 1.0
	v_fma_f32 v43, |v45|, s40, 1.0
	v_pk_mul_f32 v[14:15], v[44:45], v[44:45]
	v_rcp_f32_e32 v42, v42
	v_rcp_f32_e32 v43, v43
	v_pk_mul_f32 v[14:15], v[14:15], s[64:65] op_sel_hi:[1,0]
	v_lshlrev_b32_e32 v46, 16, v9
	v_pk_fma_f32 v[12:13], v[42:43], s[42:43], v[18:19] op_sel_hi:[1,0,0]
	v_exp_f32_e32 v14, v14
	v_pk_fma_f32 v[12:13], v[42:43], v[12:13], s[48:49] op_sel_hi:[1,1,0]
	v_exp_f32_e32 v15, v15
	v_and_b32_e32 v47, 0xffff0000, v9
	v_pk_fma_f32 v[12:13], v[42:43], v[12:13], s[50:51] op_sel_hi:[1,1,0]
	v_pk_fma_f32 v[12:13], v[42:43], v[12:13], s[56:57] op_sel_hi:[1,1,0]
	v_fma_f32 v8, |v46|, s40, 1.0
	v_fma_f32 v9, |v47|, s40, 1.0
	v_pk_mul_f32 v[12:13], v[42:43], v[12:13]
	v_rcp_f32_e32 v48, v8
	v_rcp_f32_e32 v49, v9
	v_pk_mul_f32 v[12:13], v[14:15], v[12:13]
	v_max_f32_e32 v82, 0, v44
	v_fma_f32 v43, -|v44|, v12, v82
	v_max_f32_e32 v83, 0, v45
	v_fma_f32 v9, -|v45|, v13, v83
	v_lshlrev_b32_e32 v50, 16, v10
	v_and_b32_e32 v51, 0xffff0000, v10
	v_lshlrev_b32_e32 v10, 16, v11
	v_pk_fma_f32 v[12:13], v[48:49], s[42:43], v[18:19] op_sel_hi:[1,0,0]
	v_pk_mul_f32 v[14:15], v[46:47], v[46:47]
	v_pk_fma_f32 v[12:13], v[48:49], v[12:13], s[48:49] op_sel_hi:[1,1,0]
	v_pk_mul_f32 v[14:15], v[14:15], s[64:65] op_sel_hi:[1,0]
	v_pk_fma_f32 v[12:13], v[48:49], v[12:13], s[50:51] op_sel_hi:[1,1,0]
	v_exp_f32_e32 v14, v14
	v_exp_f32_e32 v15, v15
	v_pk_fma_f32 v[12:13], v[48:49], v[12:13], s[56:57] op_sel_hi:[1,1,0]
	v_pk_mul_f32 v[12:13], v[48:49], v[12:13]
	v_fma_f32 v48, |v50|, s40, 1.0
	v_fma_f32 v49, |v51|, s40, 1.0
	v_pk_mul_f32 v[12:13], v[14:15], v[12:13]
	v_rcp_f32_e32 v48, v48
	v_rcp_f32_e32 v49, v49
	v_max_f32_e32 v84, 0, v46
	v_fma_f32 v45, -|v46|, v12, v84
	v_max_f32_e32 v85, 0, v47
	v_fma_f32 v47, -|v47|, v13, v85
	v_and_b32_e32 v11, 0xffff0000, v11
	v_pk_mul_f32 v[14:15], v[50:51], v[50:51]
	v_pk_fma_f32 v[12:13], v[48:49], s[42:43], v[18:19] op_sel_hi:[1,0,0]
	v_pk_mul_f32 v[14:15], v[14:15], s[64:65] op_sel_hi:[1,0]
	v_pk_fma_f32 v[12:13], v[48:49], v[12:13], s[48:49] op_sel_hi:[1,1,0]
	v_exp_f32_e32 v14, v14
	v_exp_f32_e32 v15, v15
	v_pk_fma_f32 v[12:13], v[48:49], v[12:13], s[50:51] op_sel_hi:[1,1,0]
	v_fma_f32 v52, |v10|, s40, 1.0
	v_fma_f32 v53, |v11|, s40, 1.0
	v_pk_fma_f32 v[12:13], v[48:49], v[12:13], s[56:57] op_sel_hi:[1,1,0]
	v_rcp_f32_e32 v52, v52
	v_pk_mul_f32 v[12:13], v[48:49], v[12:13]
	v_rcp_f32_e32 v53, v53
	v_pk_mul_f32 v[12:13], v[14:15], v[12:13]
	v_max_f32_e32 v86, 0, v50
	v_fma_f32 v49, -|v50|, v12, v86
	v_max_f32_e32 v90, 0, v51
	v_fma_f32 v51, -|v51|, v13, v90
	v_mul_f32_e32 v38, v39, v39
	s_waitcnt vmcnt(0)
	v_lshlrev_b32_e32 v60, 16, v4
	v_and_b32_e32 v61, 0xffff0000, v4
	v_pk_mul_f32 v[14:15], v[10:11], v[10:11]
	v_pk_fma_f32 v[12:13], v[52:53], s[42:43], v[18:19] op_sel_hi:[1,0,0]
	v_pk_mul_f32 v[14:15], v[14:15], s[64:65] op_sel_hi:[1,0]
	v_pk_fma_f32 v[12:13], v[52:53], v[12:13], s[48:49] op_sel_hi:[1,1,0]
	v_exp_f32_e32 v14, v14
	v_exp_f32_e32 v15, v15
	v_pk_fma_f32 v[12:13], v[52:53], v[12:13], s[50:51] op_sel_hi:[1,1,0]
	v_pk_fma_f32 v[12:13], v[52:53], v[12:13], s[56:57] op_sel_hi:[1,1,0]
	v_pk_mul_f32 v[12:13], v[52:53], v[12:13]
	v_fma_f32 v62, |v60|, s40, 1.0
	v_fma_f32 v63, |v61|, s40, 1.0
	v_pk_mul_f32 v[12:13], v[14:15], v[12:13]
	v_rcp_f32_e32 v62, v62
	v_rcp_f32_e32 v63, v63
	v_max_f32_e32 v91, 0, v10
	v_fma_f32 v53, -|v10|, v12, v91
	v_max_f32_e32 v92, 0, v11
	v_fma_f32 v11, -|v11|, v13, v92
	v_lshlrev_b32_e32 v4, 16, v5
	v_and_b32_e32 v5, 0xffff0000, v5
	v_pk_mul_f32 v[14:15], v[60:61], v[60:61]
	v_pk_fma_f32 v[12:13], v[62:63], s[42:43], v[18:19] op_sel_hi:[1,0,0]
	v_pk_mul_f32 v[14:15], v[14:15], s[64:65] op_sel_hi:[1,0]
	v_pk_fma_f32 v[12:13], v[62:63], v[12:13], s[48:49] op_sel_hi:[1,1,0]
	v_exp_f32_e32 v14, v14
	v_exp_f32_e32 v15, v15
	v_pk_fma_f32 v[12:13], v[62:63], v[12:13], s[50:51] op_sel_hi:[1,1,0]
	v_fma_f32 v64, |v4|, s40, 1.0
	v_fma_f32 v65, |v5|, s40, 1.0
	v_pk_fma_f32 v[12:13], v[62:63], v[12:13], s[56:57] op_sel_hi:[1,1,0]
	v_rcp_f32_e32 v64, v64
	v_pk_mul_f32 v[12:13], v[62:63], v[12:13]
	v_rcp_f32_e32 v65, v65
	v_pk_mul_f32 v[12:13], v[14:15], v[12:13]
	v_max_f32_e32 v93, 0, v60
	v_fma_f32 v63, -|v60|, v12, v93
	v_max_f32_e32 v94, 0, v61
	v_fma_f32 v61, -|v61|, v13, v94
	v_mul_f32_e32 v40, v41, v41
	v_pk_add_f32 v[22:23], v[24:25], v[22:23]
	v_pk_add_f32 v[24:25], v[34:35], v[36:37]
	v_pk_fma_f32 v[12:13], v[64:65], s[42:43], v[18:19] op_sel_hi:[1,0,0]
	v_pk_mul_f32 v[14:15], v[4:5], v[4:5]
	v_pk_fma_f32 v[12:13], v[64:65], v[12:13], s[48:49] op_sel_hi:[1,1,0]
	v_pk_mul_f32 v[14:15], v[14:15], s[64:65] op_sel_hi:[1,0]
	v_pk_fma_f32 v[12:13], v[64:65], v[12:13], s[50:51] op_sel_hi:[1,1,0]
	v_exp_f32_e32 v66, v14
	v_exp_f32_e32 v67, v15
	v_pk_fma_f32 v[68:69], v[64:65], v[12:13], s[56:57] op_sel_hi:[1,1,0]
	global_load_dwordx4 v[12:15], v[20:21], off offset:1024
	v_mul_f32_e32 v42, v43, v43
	v_mul_f32_e32 v8, v9, v9
	v_pk_add_f32 v[22:23], v[24:25], v[22:23]
	v_pk_add_f32 v[24:25], v[38:39], v[40:41]
	v_mul_f32_e32 v44, v45, v45
	v_mul_f32_e32 v46, v47, v47
	v_pk_add_f32 v[22:23], v[24:25], v[22:23]
	v_pk_add_f32 v[8:9], v[42:43], v[8:9]
	v_mul_f32_e32 v48, v49, v49
	v_mul_f32_e32 v50, v51, v51
	v_pk_mul_f32 v[64:65], v[64:65], v[68:69]
	v_pk_add_f32 v[8:9], v[8:9], v[22:23]
	v_pk_add_f32 v[22:23], v[44:45], v[46:47]
	v_pk_mul_f32 v[64:65], v[66:67], v[64:65]
	v_pk_add_f32 v[8:9], v[22:23], v[8:9]
	v_pk_add_f32 v[22:23], v[48:49], v[50:51]
	v_lshlrev_b32_e32 v24, 16, v6
	v_and_b32_e32 v25, 0xffff0000, v6
	v_max_f32_e32 v95, 0, v4
	v_fma_f32 v69, -|v4|, v64, v95
	v_max_f32_e32 v96, 0, v5
	v_fma_f32 v5, -|v5|, v65, v96
	v_pk_add_f32 v[8:9], v[22:23], v[8:9]
	v_mul_f32_e32 v52, v53, v53
	v_mul_f32_e32 v10, v11, v11
	v_fma_f32 v22, |v24|, s40, 1.0
	v_fma_f32 v23, |v25|, s40, 1.0
	v_mul_f32_e32 v62, v63, v63
	v_mul_f32_e32 v60, v61, v61
	v_pk_add_f32 v[10:11], v[52:53], v[10:11]
	v_rcp_f32_e32 v26, v22
	v_rcp_f32_e32 v27, v23
	v_mul_f32_e32 v68, v69, v69
	v_mul_f32_e32 v4, v5, v5
	v_pk_add_f32 v[8:9], v[10:11], v[8:9]
	v_pk_add_f32 v[10:11], v[62:63], v[60:61]
	v_pk_add_f32 v[4:5], v[68:69], v[4:5]
	v_pk_add_f32 v[8:9], v[10:11], v[8:9]
	v_cmp_gt_f32_e64 s[0:1], 0, v24
	v_pk_add_f32 v[22:23], v[4:5], v[8:9]
	v_pk_mul_f32 v[8:9], v[24:25], v[24:25]
	v_pk_fma_f32 v[4:5], v[26:27], s[42:43], v[18:19] op_sel_hi:[1,0,0]
	v_pk_mul_f32 v[8:9], v[8:9], s[64:65] op_sel_hi:[1,0]
	v_pk_fma_f32 v[4:5], v[26:27], v[4:5], s[48:49] op_sel_hi:[1,1,0]
	v_exp_f32_e32 v8, v8
	v_exp_f32_e32 v9, v9
	v_pk_fma_f32 v[4:5], v[26:27], v[4:5], s[50:51] op_sel_hi:[1,1,0]
	v_lshlrev_b32_e32 v6, 16, v7
	v_pk_fma_f32 v[4:5], v[26:27], v[4:5], s[56:57] op_sel_hi:[1,1,0]
	v_and_b32_e32 v7, 0xffff0000, v7
	v_pk_mul_f32 v[4:5], v[26:27], v[4:5]
	s_nop 0
	v_pk_mul_f32 v[4:5], v[8:9], v[4:5]
	s_nop 0
	v_pk_mul_f32 v[8:9], v[24:25], v[4:5]
	v_pk_fma_f32 v[4:5], v[24:25], v[4:5], v[24:25] neg_lo:[1,0,0] neg_hi:[1,0,0]
	s_nop 0
	v_cndmask_b32_e64 v11, v4, v8, s[0:1]
	v_cmp_gt_f32_e64 s[0:1], 0, v25
	v_and_b32_e32 v8, 0x7fffffff, v6
	v_mul_f32_e32 v10, v11, v11
	v_cndmask_b32_e64 v5, v5, v9, s[0:1]
	v_and_b32_e32 v9, 0x7fffffff, v7
	v_pk_fma_f32 v[8:9], v[8:9], s[40:41], 1.0 op_sel_hi:[1,0,0]
	v_mul_f32_e32 v4, v5, v5
	v_rcp_f32_e32 v8, v8
	v_rcp_f32_e32 v9, v9
	v_pk_add_f32 v[24:25], v[10:11], v[4:5]
	v_pk_mul_f32 v[10:11], v[6:7], v[6:7]
	v_cmp_gt_f32_e64 s[0:1], 0, v6
	v_pk_fma_f32 v[4:5], v[8:9], s[42:43], v[18:19] op_sel_hi:[1,0,0]
	v_pk_mul_f32 v[10:11], v[10:11], s[64:65] op_sel_hi:[1,0]
	v_pk_fma_f32 v[4:5], v[8:9], v[4:5], s[48:49] op_sel_hi:[1,1,0]
	v_exp_f32_e32 v10, v10
	v_exp_f32_e32 v11, v11
	v_pk_fma_f32 v[4:5], v[8:9], v[4:5], s[50:51] op_sel_hi:[1,1,0]
	v_pk_add_f32 v[22:23], v[24:25], v[22:23]
	v_pk_fma_f32 v[4:5], v[8:9], v[4:5], s[56:57] op_sel_hi:[1,1,0]
	s_nop 0
	v_pk_mul_f32 v[4:5], v[8:9], v[4:5]
	s_nop 0
	v_pk_mul_f32 v[4:5], v[10:11], v[4:5]
	global_load_dwordx4 v[8:11], v[20:21], off offset:1280
	s_waitcnt vmcnt(1)
	v_lshlrev_b32_e32 v32, 16, v12
	v_and_b32_e32 v33, 0xffff0000, v12
	v_fma_f32 v30, |v32|, s40, 1.0
	v_fma_f32 v31, |v33|, s40, 1.0
	v_pk_mul_f32 v[28:29], v[6:7], v[4:5]
	v_rcp_f32_e32 v30, v30
	v_rcp_f32_e32 v31, v31
	v_pk_fma_f32 v[4:5], v[6:7], v[4:5], v[6:7] neg_lo:[1,0,0] neg_hi:[1,0,0]
	v_lshlrev_b32_e32 v34, 16, v13
	v_cndmask_b32_e64 v27, v4, v28, s[0:1]
	v_cmp_gt_f32_e64 s[0:1], 0, v7
	v_pk_mul_f32 v[6:7], v[32:33], v[32:33]
	v_and_b32_e32 v35, 0xffff0000, v13
	v_cndmask_b32_e64 v29, v5, v29, s[0:1]
	v_pk_fma_f32 v[4:5], v[30:31], s[42:43], v[18:19] op_sel_hi:[1,0,0]
	v_pk_mul_f32 v[6:7], v[6:7], s[64:65] op_sel_hi:[1,0]
	v_pk_fma_f32 v[4:5], v[30:31], v[4:5], s[48:49] op_sel_hi:[1,1,0]
	v_exp_f32_e32 v6, v6
	v_exp_f32_e32 v7, v7
	v_pk_fma_f32 v[4:5], v[30:31], v[4:5], s[50:51] op_sel_hi:[1,1,0]
	v_pk_fma_f32 v[4:5], v[30:31], v[4:5], s[56:57] op_sel_hi:[1,1,0]
	v_fma_f32 v12, |v34|, s40, 1.0
	v_fma_f32 v13, |v35|, s40, 1.0
	v_pk_mul_f32 v[4:5], v[30:31], v[4:5]
	v_rcp_f32_e32 v36, v12
	v_rcp_f32_e32 v37, v13
	v_pk_mul_f32 v[4:5], v[6:7], v[4:5]
	v_max_f32_e32 v97, 0, v32
	v_fma_f32 v31, -|v32|, v4, v97
	v_max_f32_e32 v98, 0, v33
	v_fma_f32 v13, -|v33|, v5, v98
	v_lshlrev_b32_e32 v38, 16, v14
	v_and_b32_e32 v39, 0xffff0000, v14
	v_lshlrev_b32_e32 v40, 16, v15
	v_pk_fma_f32 v[4:5], v[36:37], s[42:43], v[18:19] op_sel_hi:[1,0,0]
	v_pk_mul_f32 v[6:7], v[34:35], v[34:35]
	v_pk_fma_f32 v[4:5], v[36:37], v[4:5], s[48:49] op_sel_hi:[1,1,0]
	v_pk_mul_f32 v[6:7], v[6:7], s[64:65] op_sel_hi:[1,0]
	v_pk_fma_f32 v[4:5], v[36:37], v[4:5], s[50:51] op_sel_hi:[1,1,0]
	v_exp_f32_e32 v6, v6
	v_exp_f32_e32 v7, v7
	v_pk_fma_f32 v[4:5], v[36:37], v[4:5], s[56:57] op_sel_hi:[1,1,0]
	v_pk_mul_f32 v[4:5], v[36:37], v[4:5]
	v_fma_f32 v36, |v38|, s40, 1.0
	v_fma_f32 v37, |v39|, s40, 1.0
	v_pk_mul_f32 v[4:5], v[6:7], v[4:5]
	v_rcp_f32_e32 v36, v36
	v_rcp_f32_e32 v37, v37
	v_max_f32_e32 v99, 0, v34
	v_fma_f32 v33, -|v34|, v4, v99
	v_max_f32_e32 v100, 0, v35
	v_fma_f32 v35, -|v35|, v5, v100
	v_and_b32_e32 v41, 0xffff0000, v15
	v_pk_mul_f32 v[6:7], v[38:39], v[38:39]
	v_pk_fma_f32 v[4:5], v[36:37], s[42:43], v[18:19] op_sel_hi:[1,0,0]
	v_pk_mul_f32 v[6:7], v[6:7], s[64:65] op_sel_hi:[1,0]
	v_pk_fma_f32 v[4:5], v[36:37], v[4:5], s[48:49] op_sel_hi:[1,1,0]
	v_exp_f32_e32 v6, v6
	v_exp_f32_e32 v7, v7
	v_pk_fma_f32 v[4:5], v[36:37], v[4:5], s[50:51] op_sel_hi:[1,1,0]
	v_fma_f32 v14, |v40|, s40, 1.0
	v_fma_f32 v15, |v41|, s40, 1.0
	v_pk_fma_f32 v[4:5], v[36:37], v[4:5], s[56:57] op_sel_hi:[1,1,0]
	v_rcp_f32_e32 v42, v14
	v_pk_mul_f32 v[4:5], v[36:37], v[4:5]
	v_rcp_f32_e32 v43, v15
	v_pk_mul_f32 v[4:5], v[6:7], v[4:5]
	v_max_f32_e32 v104, 0, v38
	v_fma_f32 v37, -|v38|, v4, v104
	v_max_f32_e32 v105, 0, v39
	v_fma_f32 v15, -|v39|, v5, v105
	v_mul_f32_e32 v26, v27, v27
	s_waitcnt vmcnt(0)
	v_lshlrev_b32_e32 v44, 16, v8
	v_and_b32_e32 v45, 0xffff0000, v8
	v_pk_fma_f32 v[4:5], v[42:43], s[42:43], v[18:19] op_sel_hi:[1,0,0]
	v_pk_mul_f32 v[6:7], v[40:41], v[40:41]
	v_pk_fma_f32 v[4:5], v[42:43], v[4:5], s[48:49] op_sel_hi:[1,1,0]
	v_pk_mul_f32 v[6:7], v[6:7], s[64:65] op_sel_hi:[1,0]
	v_pk_fma_f32 v[4:5], v[42:43], v[4:5], s[50:51] op_sel_hi:[1,1,0]
	v_exp_f32_e32 v6, v6
	v_exp_f32_e32 v7, v7
	v_pk_fma_f32 v[4:5], v[42:43], v[4:5], s[56:57] op_sel_hi:[1,1,0]
	v_pk_mul_f32 v[4:5], v[42:43], v[4:5]
	v_fma_f32 v42, |v44|, s40, 1.0
	v_fma_f32 v43, |v45|, s40, 1.0
	v_pk_mul_f32 v[4:5], v[6:7], v[4:5]
	v_rcp_f32_e32 v42, v42
	v_rcp_f32_e32 v43, v43
	v_max_f32_e32 v106, 0, v40
	v_fma_f32 v39, -|v40|, v4, v106
	v_max_f32_e32 v107, 0, v41
	v_fma_f32 v41, -|v41|, v5, v107
	v_lshlrev_b32_e32 v50, 16, v9
	v_and_b32_e32 v51, 0xffff0000, v9
	v_pk_mul_f32 v[6:7], v[44:45], v[44:45]
	v_pk_fma_f32 v[4:5], v[42:43], s[42:43], v[18:19] op_sel_hi:[1,0,0]
	v_pk_mul_f32 v[6:7], v[6:7], s[64:65] op_sel_hi:[1,0]
	v_pk_fma_f32 v[4:5], v[42:43], v[4:5], s[48:49] op_sel_hi:[1,1,0]
	v_exp_f32_e32 v6, v6
	v_exp_f32_e32 v7, v7
	v_pk_fma_f32 v[4:5], v[42:43], v[4:5], s[50:51] op_sel_hi:[1,1,0]
	v_pk_fma_f32 v[4:5], v[42:43], v[4:5], s[56:57] op_sel_hi:[1,1,0]
	v_fma_f32 v8, |v50|, s40, 1.0
	v_fma_f32 v9, |v51|, s40, 1.0
	v_pk_mul_f32 v[4:5], v[42:43], v[4:5]
	v_rcp_f32_e32 v52, v8
	v_pk_mul_f32 v[42:43], v[6:7], v[4:5]
	global_load_dwordx4 v[4:7], v[20:21], off offset:1536
	v_rcp_f32_e32 v53, v9
	v_max_f32_e32 v109, 0, v45
	v_fma_f32 v9, -|v45|, v43, v109
	v_max_f32_e32 v108, 0, v44
	v_fma_f32 v43, -|v44|, v42, v108
	v_lshlrev_b32_e32 v62, 16, v11
	v_and_b32_e32 v63, 0xffff0000, v11
	v_pk_fma_f32 v[44:45], v[52:53], s[42:43], v[18:19] op_sel_hi:[1,0,0]
	v_and_b32_e32 v11, 0x7fffffff, v63
	v_pk_fma_f32 v[44:45], v[52:53], v[44:45], s[48:49] op_sel_hi:[1,1,0]
	v_pk_mul_f32 v[46:47], v[50:51], v[50:51]
	v_pk_fma_f32 v[44:45], v[52:53], v[44:45], s[50:51] op_sel_hi:[1,1,0]
	v_pk_mul_f32 v[46:47], v[46:47], s[64:65] op_sel_hi:[1,0]
	v_pk_fma_f32 v[44:45], v[52:53], v[44:45], s[56:57] op_sel_hi:[1,1,0]
	v_exp_f32_e32 v46, v46
	v_exp_f32_e32 v47, v47
	v_pk_mul_f32 v[44:45], v[52:53], v[44:45]
	v_lshlrev_b32_e32 v52, 16, v10
	v_and_b32_e32 v53, 0xffff0000, v10
	v_fma_f32 v60, |v52|, s40, 1.0
	v_fma_f32 v61, |v53|, s40, 1.0
	v_pk_mul_f32 v[44:45], v[46:47], v[44:45]
	v_rcp_f32_e32 v60, v60
	v_rcp_f32_e32 v61, v61
	v_max_f32_e32 v111, 0, v51
	v_fma_f32 v47, -|v51|, v45, v111
	v_max_f32_e32 v110, 0, v50
	v_fma_f32 v45, -|v50|, v44, v110
	v_and_b32_e32 v10, 0x7fffffff, v62
	v_pk_fma_f32 v[10:11], v[10:11], s[40:41], 1.0 op_sel_hi:[1,0,0]
	v_pk_mul_f32 v[50:51], v[52:53], v[52:53]
	v_rcp_f32_e32 v64, v10
	v_pk_fma_f32 v[48:49], v[60:61], s[42:43], v[18:19] op_sel_hi:[1,0,0]
	v_pk_mul_f32 v[50:51], v[50:51], s[64:65] op_sel_hi:[1,0]
	v_pk_fma_f32 v[48:49], v[60:61], v[48:49], s[48:49] op_sel_hi:[1,1,0]
	v_exp_f32_e32 v50, v50
	v_exp_f32_e32 v51, v51
	v_pk_fma_f32 v[48:49], v[60:61], v[48:49], s[50:51] op_sel_hi:[1,1,0]
	v_rcp_f32_e32 v65, v11
	v_pk_fma_f32 v[48:49], v[60:61], v[48:49], s[56:57] op_sel_hi:[1,1,0]
	v_pk_mul_f32 v[48:49], v[60:61], v[48:49]
	v_mul_f32_e32 v28, v29, v29
	v_pk_mul_f32 v[48:49], v[50:51], v[48:49]
	v_mul_f32_e32 v30, v31, v31
	v_max_f32_e32 v113, 0, v53
	v_fma_f32 v11, -|v53|, v49, v113
	v_max_f32_e32 v112, 0, v52
	v_fma_f32 v49, -|v52|, v48, v112
	v_mul_f32_e32 v12, v13, v13
	v_pk_mul_f32 v[52:53], v[62:63], v[62:63]
	v_pk_add_f32 v[24:25], v[26:27], v[28:29]
	v_pk_fma_f32 v[50:51], v[64:65], s[42:43], v[18:19] op_sel_hi:[1,0,0]
	v_pk_mul_f32 v[52:53], v[52:53], s[64:65] op_sel_hi:[1,0]
	v_pk_fma_f32 v[50:51], v[64:65], v[50:51], s[48:49] op_sel_hi:[1,1,0]
	v_exp_f32_e32 v52, v52
	v_exp_f32_e32 v53, v53
	v_pk_fma_f32 v[50:51], v[64:65], v[50:51], s[50:51] op_sel_hi:[1,1,0]
	v_pk_fma_f32 v[50:51], v[64:65], v[50:51], s[56:57] op_sel_hi:[1,1,0]
	v_mul_f32_e32 v32, v33, v33
	v_pk_mul_f32 v[50:51], v[64:65], v[50:51]
	v_mul_f32_e32 v34, v35, v35
	v_pk_mul_f32 v[50:51], v[52:53], v[50:51]
	v_pk_add_f32 v[22:23], v[24:25], v[22:23]
	v_max_f32_e32 v114, 0, v62
	v_fma_f32 v67, -|v62|, v50, v114
	v_max_f32_e32 v115, 0, v63
	v_fma_f32 v61, -|v63|, v51, v115
	global_load_dwordx4 v[50:53], v[20:21], off offset:1792
	v_pk_add_f32 v[12:13], v[30:31], v[12:13]
	v_mul_f32_e32 v36, v37, v37
	s_waitcnt vmcnt(1)
	v_lshlrev_b32_e32 v20, 16, v4
	v_and_b32_e32 v21, 0xffff0000, v4
	v_fma_f32 v68, |v20|, s40, 1.0
	v_fma_f32 v69, |v21|, s40, 1.0
	v_pk_mul_f32 v[64:65], v[20:21], v[20:21]
	v_rcp_f32_e32 v68, v68
	v_rcp_f32_e32 v69, v69
	v_mul_f32_e32 v14, v15, v15
	v_pk_mul_f32 v[64:65], v[64:65], s[64:65] op_sel_hi:[1,0]
	v_pk_add_f32 v[12:13], v[12:13], v[22:23]
	v_pk_fma_f32 v[62:63], v[68:69], s[42:43], v[18:19] op_sel_hi:[1,0,0]
	v_pk_add_f32 v[22:23], v[32:33], v[34:35]
	v_mul_f32_e32 v38, v39, v39
	v_mul_f32_e32 v40, v41, v41
	v_pk_fma_f32 v[62:63], v[68:69], v[62:63], s[48:49] op_sel_hi:[1,1,0]
	v_exp_f32_e32 v64, v64
	v_exp_f32_e32 v65, v65
	v_pk_add_f32 v[12:13], v[22:23], v[12:13]
	v_pk_add_f32 v[14:15], v[36:37], v[14:15]
	v_mul_f32_e32 v42, v43, v43
	v_mul_f32_e32 v8, v9, v9
	v_pk_fma_f32 v[62:63], v[68:69], v[62:63], s[50:51] op_sel_hi:[1,1,0]
	v_pk_add_f32 v[12:13], v[14:15], v[12:13]
	v_pk_add_f32 v[14:15], v[38:39], v[40:41]
	v_mul_f32_e32 v44, v45, v45
	v_mul_f32_e32 v46, v47, v47
	v_pk_fma_f32 v[62:63], v[68:69], v[62:63], s[56:57] op_sel_hi:[1,1,0]
	v_pk_add_f32 v[12:13], v[14:15], v[12:13]
	v_pk_add_f32 v[8:9], v[42:43], v[8:9]
	v_pk_mul_f32 v[62:63], v[68:69], v[62:63]
	v_pk_add_f32 v[8:9], v[8:9], v[12:13]
	v_pk_add_f32 v[12:13], v[44:45], v[46:47]
	v_lshlrev_b32_e32 v4, 16, v5
	v_and_b32_e32 v5, 0xffff0000, v5
	v_pk_mul_f32 v[62:63], v[64:65], v[62:63]
	v_pk_add_f32 v[8:9], v[12:13], v[8:9]
	v_max_f32_e32 v116, 0, v20
	v_fma_f32 v69, -|v20|, v62, v116
	v_max_f32_e32 v117, 0, v21
	v_fma_f32 v21, -|v21|, v63, v117
	v_fma_f32 v12, |v4|, s40, 1.0
	v_fma_f32 v13, |v5|, s40, 1.0
	v_mul_f32_e32 v48, v49, v49
	v_mul_f32_e32 v10, v11, v11
	v_rcp_f32_e32 v12, v12
	v_rcp_f32_e32 v13, v13
	v_mul_f32_e32 v66, v67, v67
	v_mul_f32_e32 v60, v61, v61
	v_pk_add_f32 v[10:11], v[48:49], v[10:11]
	v_mul_f32_e32 v68, v69, v69
	v_mul_f32_e32 v20, v21, v21
	v_pk_add_f32 v[8:9], v[10:11], v[8:9]
	v_pk_add_f32 v[10:11], v[66:67], v[60:61]
	v_pk_mul_f32 v[14:15], v[4:5], v[4:5]
	v_pk_add_f32 v[8:9], v[10:11], v[8:9]
	v_pk_add_f32 v[10:11], v[68:69], v[20:21]
	v_pk_mul_f32 v[14:15], v[14:15], s[64:65] op_sel_hi:[1,0]
	v_pk_add_f32 v[8:9], v[10:11], v[8:9]
	v_pk_fma_f32 v[10:11], v[12:13], s[42:43], v[18:19] op_sel_hi:[1,0,0]
	v_exp_f32_e32 v14, v14
	v_pk_fma_f32 v[10:11], v[12:13], v[10:11], s[48:49] op_sel_hi:[1,1,0]
	v_exp_f32_e32 v15, v15
	v_pk_fma_f32 v[10:11], v[12:13], v[10:11], s[50:51] op_sel_hi:[1,1,0]
	v_pk_fma_f32 v[10:11], v[12:13], v[10:11], s[56:57] op_sel_hi:[1,1,0]
	s_waitcnt vmcnt(0)
	v_lshlrev_b32_e32 v24, 16, v50
	v_pk_mul_f32 v[10:11], v[12:13], v[10:11]
	v_and_b32_e32 v25, 0xffff0000, v50
	v_pk_mul_f32 v[10:11], v[14:15], v[10:11]
	v_and_b32_e32 v27, 0x7fffffff, v25
	v_max_f32_e32 v80, 0, v4
	v_fma_f32 v15, -|v4|, v10, v80
	v_max_f32_e32 v81, 0, v5
	v_fma_f32 v5, -|v5|, v11, v81
	v_and_b32_e32 v26, 0x7fffffff, v24
	v_lshlrev_b32_e32 v10, 16, v6
	v_and_b32_e32 v12, 0x7fffffff, v10
	v_and_b32_e32 v11, 0xffff0000, v6
	v_and_b32_e32 v13, 0x7fffffff, v11
	v_pk_fma_f32 v[12:13], v[12:13], s[40:41], 1.0 op_sel_hi:[1,0,0]
	v_mul_f32_e32 v14, v15, v15
	v_rcp_f32_e32 v12, v12
	v_rcp_f32_e32 v13, v13
	v_mul_f32_e32 v4, v5, v5
	v_pk_mul_f32 v[20:21], v[10:11], v[10:11]
	v_pk_add_f32 v[4:5], v[14:15], v[4:5]
	v_pk_fma_f32 v[14:15], v[12:13], s[42:43], v[18:19] op_sel_hi:[1,0,0]
	v_pk_mul_f32 v[20:21], v[20:21], s[64:65] op_sel_hi:[1,0]
	v_pk_fma_f32 v[14:15], v[12:13], v[14:15], s[48:49] op_sel_hi:[1,1,0]
	v_exp_f32_e32 v20, v20
	v_exp_f32_e32 v21, v21
	v_pk_fma_f32 v[14:15], v[12:13], v[14:15], s[50:51] op_sel_hi:[1,1,0]
	v_lshlrev_b32_e32 v6, 16, v7
	v_and_b32_e32 v7, 0xffff0000, v7
	v_pk_fma_f32 v[14:15], v[12:13], v[14:15], s[56:57] op_sel_hi:[1,1,0]
	v_pk_mul_f32 v[12:13], v[12:13], v[14:15]
	v_fma_f32 v22, |v6|, s40, 1.0
	v_fma_f32 v23, |v7|, s40, 1.0
	v_pk_mul_f32 v[12:13], v[20:21], v[12:13]
	v_rcp_f32_e32 v22, v22
	v_rcp_f32_e32 v23, v23
	v_max_f32_e32 v82, 0, v10
	v_fma_f32 v21, -|v10|, v12, v82
	v_max_f32_e32 v83, 0, v11
	v_fma_f32 v11, -|v11|, v13, v83
	v_pk_fma_f32 v[26:27], v[26:27], s[40:41], 1.0 op_sel_hi:[1,0,0]
	v_lshlrev_b32_e32 v28, 16, v51
	v_rcp_f32_e32 v26, v26
	v_rcp_f32_e32 v27, v27
	v_pk_mul_f32 v[14:15], v[6:7], v[6:7]
	v_pk_fma_f32 v[12:13], v[22:23], s[42:43], v[18:19] op_sel_hi:[1,0,0]
	v_pk_mul_f32 v[14:15], v[14:15], s[64:65] op_sel_hi:[1,0]
	v_pk_fma_f32 v[12:13], v[22:23], v[12:13], s[48:49] op_sel_hi:[1,1,0]
	v_exp_f32_e32 v14, v14
	v_exp_f32_e32 v15, v15
	v_pk_fma_f32 v[12:13], v[22:23], v[12:13], s[50:51] op_sel_hi:[1,1,0]
	v_pk_fma_f32 v[12:13], v[22:23], v[12:13], s[56:57] op_sel_hi:[1,1,0]
	v_and_b32_e32 v29, 0xffff0000, v51
	v_pk_mul_f32 v[12:13], v[22:23], v[12:13]
	v_pk_mul_f32 v[12:13], v[14:15], v[12:13]
	v_max_f32_e32 v84, 0, v6
	v_fma_f32 v23, -|v6|, v12, v84
	v_max_f32_e32 v85, 0, v7
	v_fma_f32 v7, -|v7|, v13, v85
	v_fma_f32 v30, |v28|, s40, 1.0
	v_fma_f32 v31, |v29|, s40, 1.0
	v_rcp_f32_e32 v30, v30
	v_rcp_f32_e32 v31, v31
	v_pk_mul_f32 v[14:15], v[24:25], v[24:25]
	v_pk_fma_f32 v[12:13], v[26:27], s[42:43], v[18:19] op_sel_hi:[1,0,0]
	v_pk_mul_f32 v[14:15], v[14:15], s[64:65] op_sel_hi:[1,0]
	v_pk_fma_f32 v[12:13], v[26:27], v[12:13], s[48:49] op_sel_hi:[1,1,0]
	v_exp_f32_e32 v14, v14
	v_exp_f32_e32 v15, v15
	v_pk_fma_f32 v[12:13], v[26:27], v[12:13], s[50:51] op_sel_hi:[1,1,0]
	v_pk_fma_f32 v[12:13], v[26:27], v[12:13], s[56:57] op_sel_hi:[1,1,0]
	v_lshlrev_b32_e32 v32, 16, v52
	v_pk_mul_f32 v[12:13], v[26:27], v[12:13]
	v_and_b32_e32 v33, 0xffff0000, v52
	v_pk_mul_f32 v[12:13], v[14:15], v[12:13]
	v_max_f32_e32 v86, 0, v24
	v_fma_f32 v27, -|v24|, v12, v86
	v_max_f32_e32 v90, 0, v25
	v_fma_f32 v13, -|v25|, v13, v90
	v_pk_mul_f32 v[24:25], v[28:29], v[28:29]
	v_fma_f32 v34, |v32|, s40, 1.0
	v_fma_f32 v35, |v33|, s40, 1.0
	v_pk_fma_f32 v[14:15], v[30:31], s[42:43], v[18:19] op_sel_hi:[1,0,0]
	v_pk_mul_f32 v[24:25], v[24:25], s[64:65] op_sel_hi:[1,0]
	v_pk_fma_f32 v[14:15], v[30:31], v[14:15], s[48:49] op_sel_hi:[1,1,0]
	v_exp_f32_e32 v24, v24
	v_exp_f32_e32 v25, v25
	v_pk_fma_f32 v[14:15], v[30:31], v[14:15], s[50:51] op_sel_hi:[1,1,0]
	v_rcp_f32_e32 v34, v34
	v_pk_fma_f32 v[14:15], v[30:31], v[14:15], s[56:57] op_sel_hi:[1,1,0]
	v_rcp_f32_e32 v35, v35
	v_pk_mul_f32 v[14:15], v[30:31], v[14:15]
	v_pk_mul_f32 v[14:15], v[24:25], v[14:15]
	v_lshlrev_b32_e32 v36, 16, v53
	v_max_f32_e32 v91, 0, v28
	v_fma_f32 v31, -|v28|, v14, v91
	v_max_f32_e32 v92, 0, v29
	v_fma_f32 v15, -|v29|, v15, v92
	v_and_b32_e32 v37, 0xffff0000, v53
	v_pk_mul_f32 v[28:29], v[32:33], v[32:33]
	v_pk_fma_f32 v[24:25], v[34:35], s[42:43], v[18:19] op_sel_hi:[1,0,0]
	v_pk_mul_f32 v[28:29], v[28:29], s[64:65] op_sel_hi:[1,0]
	v_pk_fma_f32 v[24:25], v[34:35], v[24:25], s[48:49] op_sel_hi:[1,1,0]
	v_exp_f32_e32 v28, v28
	v_exp_f32_e32 v29, v29
	v_pk_fma_f32 v[24:25], v[34:35], v[24:25], s[50:51] op_sel_hi:[1,1,0]
	v_pk_fma_f32 v[24:25], v[34:35], v[24:25], s[56:57] op_sel_hi:[1,1,0]
	v_fma_f32 v38, |v36|, s40, 1.0
	v_fma_f32 v39, |v37|, s40, 1.0
	v_pk_mul_f32 v[24:25], v[34:35], v[24:25]
	v_rcp_f32_e32 v38, v38
	v_pk_mul_f32 v[24:25], v[28:29], v[24:25]
	v_rcp_f32_e32 v39, v39
	v_max_f32_e32 v93, 0, v32
	v_fma_f32 v35, -|v32|, v24, v93
	v_max_f32_e32 v94, 0, v33
	v_fma_f32 v25, -|v33|, v25, v94
	v_pk_fma_f32 v[18:19], v[38:39], s[42:43], v[18:19] op_sel_hi:[1,0,0]
	v_mul_f32_e32 v20, v21, v21
	v_pk_fma_f32 v[18:19], v[38:39], v[18:19], s[48:49] op_sel_hi:[1,1,0]
	v_mul_f32_e32 v10, v11, v11
	v_pk_mul_f32 v[28:29], v[36:37], v[36:37]
	v_pk_fma_f32 v[18:19], v[38:39], v[18:19], s[50:51] op_sel_hi:[1,1,0]
	v_pk_mul_f32 v[28:29], v[28:29], s[64:65] op_sel_hi:[1,0]
	v_pk_fma_f32 v[18:19], v[38:39], v[18:19], s[56:57] op_sel_hi:[1,1,0]
	v_exp_f32_e32 v28, v28
	v_exp_f32_e32 v29, v29
	v_pk_mul_f32 v[18:19], v[38:39], v[18:19]
	v_mul_f32_e32 v22, v23, v23
	v_mul_f32_e32 v6, v7, v7
	v_pk_mul_f32 v[18:19], v[28:29], v[18:19]
	v_pk_add_f32 v[4:5], v[4:5], v[8:9]
	v_pk_add_f32 v[8:9], v[20:21], v[10:11]
	v_mul_f32_e32 v26, v27, v27
	v_mul_f32_e32 v12, v13, v13
	v_max_f32_e32 v95, 0, v36
	v_fma_f32 v33, -|v36|, v18, v95
	v_max_f32_e32 v96, 0, v37
	v_fma_f32 v19, -|v37|, v19, v96
	v_pk_add_f32 v[4:5], v[8:9], v[4:5]
	v_pk_add_f32 v[6:7], v[22:23], v[6:7]
	v_mul_f32_e32 v30, v31, v31
	v_mul_f32_e32 v14, v15, v15
	v_pk_add_f32 v[4:5], v[6:7], v[4:5]
	v_pk_add_f32 v[6:7], v[26:27], v[12:13]
	v_mul_f32_e32 v34, v35, v35
	v_mul_f32_e32 v24, v25, v25
	v_pk_add_f32 v[4:5], v[6:7], v[4:5]
	v_pk_add_f32 v[6:7], v[30:31], v[14:15]
	v_mul_f32_e32 v32, v33, v33
	v_mul_f32_e32 v18, v19, v19
	v_pk_add_f32 v[4:5], v[6:7], v[4:5]
	v_pk_add_f32 v[6:7], v[34:35], v[24:25]
	s_nop 0
	v_pk_add_f32 v[4:5], v[6:7], v[4:5]
	v_pk_add_f32 v[6:7], v[32:33], v[18:19]
	s_nop 0
	v_pk_add_f32 v[4:5], v[6:7], v[4:5]
	ds_bpermute_b32 v7, v56, v5
	ds_bpermute_b32 v6, v56, v4
	s_waitcnt lgkmcnt(0)
	v_pk_add_f32 v[4:5], v[4:5], v[6:7]
	ds_bpermute_b32 v7, v57, v5
	ds_bpermute_b32 v6, v57, v4
	s_waitcnt lgkmcnt(0)
	v_pk_add_f32 v[4:5], v[4:5], v[6:7]
	ds_bpermute_b32 v7, v58, v5
	ds_bpermute_b32 v6, v58, v4
	s_waitcnt lgkmcnt(0)
	v_pk_add_f32 v[4:5], v[4:5], v[6:7]
	ds_bpermute_b32 v7, v59, v5
	ds_bpermute_b32 v6, v59, v4
	s_and_saveexec_b64 s[0:1], vcc
	s_cbranch_execz .LBB0_451
	s_waitcnt lgkmcnt(0)
	v_pk_add_f32 v[4:5], v[4:5], v[6:7]
	s_nop 0
	v_pk_mul_f32 v[4:5], v[4:5], s[66:67] op_sel_hi:[1,0]
	s_nop 0
	v_fma_f32 v4, -v5, v5, v4
	v_max_f32_e32 v4, 0, v4
	v_add_f32_e32 v4, 0x358637bd, v4
	v_mul_f32_e32 v6, 0x4b800000, v4
	v_cmp_gt_f32_e32 vcc, s36, v4
	s_nop 1
	v_cndmask_b32_e32 v4, v4, v6, vcc
	v_rsq_f32_e32 v4, v4
	v_lshl_add_u32 v6, v16, 2, 0
	v_add_u32_e32 v7, 0x11000, v6
	ds_write_b32 v7, v5
	v_mul_f32_e32 v5, 0x45800000, v4
	v_cndmask_b32_e32 v4, v4, v5, vcc
	v_add_u32_e32 v5, 0x11200, v6
	ds_write_b32 v5, v4

.LBB0_453:
	v_lshl_add_u64 v[4:5], s[12:13], 0, v[32:33]
	v_add_co_u32_e32 v18, vcc, 0x696e000, v4
	s_add_u32 s0, s16, s70
	s_nop 0
	v_addc_co_u32_e32 v19, vcc, 0, v5, vcc
	global_load_dwordx4 v[8:11], v[18:19], off
	global_load_dwordx4 v[4:7], v[18:19], off offset:2048
	s_addc_u32 s1, s38, s71
	s_add_u32 s4, s88, s70
	s_addc_u32 s5, s89, s71
	global_load_dwordx2 v[20:21], v2, s[0:1]
	global_load_dwordx2 v[22:23], v2, s[4:5]
	v_mov_b64_e32 v[16:17], s[44:45]
	ds_read_b64 v[14:15], v68
	ds_read_b64 v[12:13], v69
	s_waitcnt vmcnt(3)
	v_lshlrev_b32_e32 v24, 16, v8
	v_and_b32_e32 v25, 0xffff0000, v8
	s_waitcnt vmcnt(2)
	v_lshlrev_b32_e32 v34, 16, v4
	v_and_b32_e32 v35, 0xffff0000, v4
	v_fma_f32 v36, |v24|, s40, 1.0
	v_fma_f32 v37, |v25|, s40, 1.0
	v_fma_f32 v40, |v34|, s40, 1.0
	v_fma_f32 v41, |v35|, s40, 1.0
	v_rcp_f32_e32 v36, v36
	v_rcp_f32_e32 v37, v37
	v_rcp_f32_e32 v40, v40
	v_rcp_f32_e32 v41, v41
	v_pk_mul_f32 v[38:39], v[24:25], v[24:25]
	v_pk_mul_f32 v[42:43], v[34:35], v[34:35]
	v_pk_mul_f32 v[38:39], v[38:39], s[64:65] op_sel_hi:[1,0]
	v_pk_fma_f32 v[44:45], v[36:37], s[42:43], v[16:17] op_sel_hi:[1,0,0]
	v_pk_mul_f32 v[42:43], v[42:43], s[64:65] op_sel_hi:[1,0]
	v_exp_f32_e32 v38, v38
	v_exp_f32_e32 v39, v39
	v_pk_fma_f32 v[46:47], v[40:41], s[42:43], v[16:17] op_sel_hi:[1,0,0]
	v_pk_fma_f32 v[44:45], v[36:37], v[44:45], s[48:49] op_sel_hi:[1,1,0]
	v_exp_f32_e32 v42, v42
	v_exp_f32_e32 v43, v43
	v_pk_fma_f32 v[46:47], v[40:41], v[46:47], s[48:49] op_sel_hi:[1,1,0]
	v_pk_fma_f32 v[44:45], v[36:37], v[44:45], s[50:51] op_sel_hi:[1,1,0]
	v_pk_fma_f32 v[46:47], v[40:41], v[46:47], s[50:51] op_sel_hi:[1,1,0]
	v_pk_fma_f32 v[44:45], v[36:37], v[44:45], s[56:57] op_sel_hi:[1,1,0]
	v_pk_fma_f32 v[46:47], v[40:41], v[46:47], s[56:57] op_sel_hi:[1,1,0]
	v_pk_mul_f32 v[36:37], v[36:37], v[44:45]
	v_pk_mul_f32 v[40:41], v[40:41], v[46:47]
	v_pk_mul_f32 v[36:37], v[38:39], v[36:37]
	v_pk_mul_f32 v[38:39], v[42:43], v[40:41]
	v_max_f32_e32 v97, 0, v24
	v_fma_f32 v3, -|v24|, v36, v97
	v_max_f32_e32 v98, 0, v25
	v_fma_f32 v4, -|v25|, v37, v98
	v_max_f32_e32 v99, 0, v34
	v_fma_f32 v8, -|v34|, v38, v99
	v_max_f32_e32 v100, 0, v35
	v_fma_f32 v24, -|v35|, v39, v100
	s_waitcnt lgkmcnt(1)
	v_sub_f32_e32 v3, v3, v14
	s_waitcnt lgkmcnt(0)
	v_mul_f32_e32 v3, v12, v3
	v_sub_f32_e32 v4, v4, v14
	v_mul_f32_e32 v4, v12, v4
	v_sub_f32_e32 v8, v8, v15
	v_mul_f32_e32 v8, v13, v8
	v_sub_f32_e32 v24, v24, v15
	v_mul_f32_e32 v24, v13, v24
	s_waitcnt vmcnt(0)
	v_fma_f32 v3, v20, v3, v22
	v_fma_f32 v4, v21, v4, v23
	v_fma_f32 v8, v20, v8, v22
	v_fmac_f32_e32 v23, v21, v24
	v_cvt_pk_bf16_f32 v3, v3, v8
	ds_write_b32 v70, v3
	v_cvt_pk_bf16_f32 v3, v4, v23
	global_load_dwordx2 v[22:23], v2, s[0:1] offset:8
	global_load_dwordx2 v[20:21], v2, s[4:5] offset:8
	v_lshlrev_b32_e32 v8, 16, v9
	v_and_b32_e32 v9, 0xffff0000, v9
	v_lshlrev_b32_e32 v4, 16, v5
	v_and_b32_e32 v5, 0xffff0000, v5
	v_fma_f32 v24, |v8|, s40, 1.0
	v_fma_f32 v25, |v9|, s40, 1.0
	v_fma_f32 v36, |v4|, s40, 1.0
	v_fma_f32 v37, |v5|, s40, 1.0
	v_rcp_f32_e32 v24, v24
	v_rcp_f32_e32 v25, v25
	v_rcp_f32_e32 v36, v36
	v_rcp_f32_e32 v37, v37
	v_pk_mul_f32 v[34:35], v[8:9], v[8:9]
	v_pk_mul_f32 v[38:39], v[4:5], v[4:5]
	v_pk_mul_f32 v[34:35], v[34:35], s[64:65] op_sel_hi:[1,0]
	v_pk_fma_f32 v[40:41], v[24:25], s[42:43], v[16:17] op_sel_hi:[1,0,0]
	v_pk_mul_f32 v[38:39], v[38:39], s[64:65] op_sel_hi:[1,0]
	v_exp_f32_e32 v34, v34
	v_exp_f32_e32 v35, v35
	v_pk_fma_f32 v[42:43], v[36:37], s[42:43], v[16:17] op_sel_hi:[1,0,0]
	v_pk_fma_f32 v[40:41], v[24:25], v[40:41], s[48:49] op_sel_hi:[1,1,0]
	v_exp_f32_e32 v38, v38
	v_exp_f32_e32 v39, v39
	v_pk_fma_f32 v[42:43], v[36:37], v[42:43], s[48:49] op_sel_hi:[1,1,0]
	v_pk_fma_f32 v[40:41], v[24:25], v[40:41], s[50:51] op_sel_hi:[1,1,0]
	v_pk_fma_f32 v[42:43], v[36:37], v[42:43], s[50:51] op_sel_hi:[1,1,0]
	v_pk_fma_f32 v[40:41], v[24:25], v[40:41], s[56:57] op_sel_hi:[1,1,0]
	v_pk_fma_f32 v[42:43], v[36:37], v[42:43], s[56:57] op_sel_hi:[1,1,0]
	v_pk_mul_f32 v[24:25], v[24:25], v[40:41]
	v_pk_mul_f32 v[36:37], v[36:37], v[42:43]
	v_pk_mul_f32 v[24:25], v[34:35], v[24:25]
	v_pk_mul_f32 v[34:35], v[38:39], v[36:37]
	v_max_f32_e32 v104, 0, v8
	v_fma_f32 v8, -|v8|, v24, v104
	v_max_f32_e32 v105, 0, v9
	v_fma_f32 v9, -|v9|, v25, v105
	v_max_f32_e32 v106, 0, v4
	v_fma_f32 v4, -|v4|, v34, v106
	v_max_f32_e32 v107, 0, v5
	v_fma_f32 v5, -|v5|, v35, v107
	v_sub_f32_e32 v8, v8, v14
	v_mul_f32_e32 v8, v12, v8
	v_sub_f32_e32 v9, v9, v14
	v_mul_f32_e32 v9, v12, v9
	v_sub_f32_e32 v4, v4, v15
	v_mul_f32_e32 v4, v13, v4
	v_sub_f32_e32 v5, v5, v15
	ds_write_b32 v70, v3 offset:272
	v_mul_f32_e32 v5, v13, v5
	s_waitcnt vmcnt(0)
	v_fma_f32 v3, v22, v8, v20
	v_fma_f32 v8, v23, v9, v21
	v_fma_f32 v4, v22, v4, v20
	v_cvt_pk_bf16_f32 v3, v3, v4
	v_fmac_f32_e32 v21, v23, v5
	ds_write_b32 v70, v3 offset:544
	v_cvt_pk_bf16_f32 v3, v8, v21
	global_load_dwordx2 v[8:9], v2, s[0:1] offset:16
	global_load_dwordx2 v[4:5], v2, s[4:5] offset:16
	v_lshlrev_b32_e32 v20, 16, v10
	v_and_b32_e32 v21, 0xffff0000, v10
	v_lshlrev_b32_e32 v22, 16, v6
	v_and_b32_e32 v23, 0xffff0000, v6
	v_fma_f32 v24, |v20|, s40, 1.0
	v_fma_f32 v25, |v21|, s40, 1.0
	v_fma_f32 v36, |v22|, s40, 1.0
	v_fma_f32 v37, |v23|, s40, 1.0
	v_rcp_f32_e32 v24, v24
	v_rcp_f32_e32 v25, v25
	v_rcp_f32_e32 v36, v36
	v_rcp_f32_e32 v37, v37
	v_pk_mul_f32 v[34:35], v[20:21], v[20:21]
	v_pk_mul_f32 v[38:39], v[22:23], v[22:23]
	v_pk_mul_f32 v[34:35], v[34:35], s[64:65] op_sel_hi:[1,0]
	v_pk_fma_f32 v[40:41], v[24:25], s[42:43], v[16:17] op_sel_hi:[1,0,0]
	v_pk_mul_f32 v[38:39], v[38:39], s[64:65] op_sel_hi:[1,0]
	v_exp_f32_e32 v34, v34
	v_exp_f32_e32 v35, v35
	v_pk_fma_f32 v[42:43], v[36:37], s[42:43], v[16:17] op_sel_hi:[1,0,0]
	v_pk_fma_f32 v[40:41], v[24:25], v[40:41], s[48:49] op_sel_hi:[1,1,0]
	v_exp_f32_e32 v38, v38
	v_exp_f32_e32 v39, v39
	v_pk_fma_f32 v[42:43], v[36:37], v[42:43], s[48:49] op_sel_hi:[1,1,0]
	v_pk_fma_f32 v[40:41], v[24:25], v[40:41], s[50:51] op_sel_hi:[1,1,0]
	v_pk_fma_f32 v[42:43], v[36:37], v[42:43], s[50:51] op_sel_hi:[1,1,0]
	v_pk_fma_f32 v[40:41], v[24:25], v[40:41], s[56:57] op_sel_hi:[1,1,0]
	v_pk_fma_f32 v[42:43], v[36:37], v[42:43], s[56:57] op_sel_hi:[1,1,0]
	v_pk_mul_f32 v[24:25], v[24:25], v[40:41]
	v_pk_mul_f32 v[36:37], v[36:37], v[42:43]
	v_pk_mul_f32 v[24:25], v[34:35], v[24:25]
	v_pk_mul_f32 v[34:35], v[38:39], v[36:37]
	v_max_f32_e32 v108, 0, v20
	v_fma_f32 v6, -|v20|, v24, v108
	v_max_f32_e32 v109, 0, v21
	v_fma_f32 v10, -|v21|, v25, v109
	v_max_f32_e32 v110, 0, v22
	v_fma_f32 v20, -|v22|, v34, v110
	v_max_f32_e32 v111, 0, v23
	v_fma_f32 v21, -|v23|, v35, v111
	v_sub_f32_e32 v6, v6, v14
	v_mul_f32_e32 v6, v12, v6
	v_sub_f32_e32 v10, v10, v14
	v_mul_f32_e32 v10, v12, v10
	v_sub_f32_e32 v20, v20, v15
	v_mul_f32_e32 v20, v13, v20
	v_sub_f32_e32 v21, v21, v15
	v_mul_f32_e32 v21, v13, v21
	ds_write_b32 v70, v3 offset:816
	s_waitcnt vmcnt(0)
	v_fma_f32 v3, v8, v6, v4
	v_fma_f32 v6, v9, v10, v5
	v_fma_f32 v4, v8, v20, v4
	v_fmac_f32_e32 v5, v9, v21
	v_cvt_pk_bf16_f32 v3, v3, v4
	ds_write_b32 v70, v3 offset:1088
	v_cvt_pk_bf16_f32 v3, v6, v5
	global_load_dwordx2 v[8:9], v2, s[0:1] offset:24
	global_load_dwordx2 v[4:5], v2, s[4:5] offset:24
	v_lshlrev_b32_e32 v10, 16, v11
	v_and_b32_e32 v11, 0xffff0000, v11
	v_lshlrev_b32_e32 v6, 16, v7
	v_and_b32_e32 v7, 0xffff0000, v7
	v_fma_f32 v20, |v10|, s40, 1.0
	v_fma_f32 v21, |v11|, s40, 1.0
	v_fma_f32 v24, |v6|, s40, 1.0
	v_fma_f32 v25, |v7|, s40, 1.0
	v_rcp_f32_e32 v20, v20
	v_rcp_f32_e32 v21, v21
	v_rcp_f32_e32 v24, v24
	v_rcp_f32_e32 v25, v25
	v_pk_mul_f32 v[22:23], v[10:11], v[10:11]
	v_pk_mul_f32 v[34:35], v[6:7], v[6:7]
	v_pk_mul_f32 v[22:23], v[22:23], s[64:65] op_sel_hi:[1,0]
	v_pk_fma_f32 v[36:37], v[20:21], s[42:43], v[16:17] op_sel_hi:[1,0,0]
	v_pk_mul_f32 v[34:35], v[34:35], s[64:65] op_sel_hi:[1,0]
	v_exp_f32_e32 v22, v22
	v_exp_f32_e32 v23, v23
	v_pk_fma_f32 v[38:39], v[24:25], s[42:43], v[16:17] op_sel_hi:[1,0,0]
	v_pk_fma_f32 v[36:37], v[20:21], v[36:37], s[48:49] op_sel_hi:[1,1,0]
	v_exp_f32_e32 v34, v34
	v_exp_f32_e32 v35, v35
	v_pk_fma_f32 v[38:39], v[24:25], v[38:39], s[48:49] op_sel_hi:[1,1,0]
	v_pk_fma_f32 v[36:37], v[20:21], v[36:37], s[50:51] op_sel_hi:[1,1,0]
	v_pk_fma_f32 v[38:39], v[24:25], v[38:39], s[50:51] op_sel_hi:[1,1,0]
	v_pk_fma_f32 v[36:37], v[20:21], v[36:37], s[56:57] op_sel_hi:[1,1,0]
	v_pk_fma_f32 v[38:39], v[24:25], v[38:39], s[56:57] op_sel_hi:[1,1,0]
	v_pk_mul_f32 v[20:21], v[20:21], v[36:37]
	v_pk_mul_f32 v[24:25], v[24:25], v[38:39]
	v_pk_mul_f32 v[20:21], v[22:23], v[20:21]
	v_pk_mul_f32 v[22:23], v[34:35], v[24:25]
	v_max_f32_e32 v112, 0, v10
	v_fma_f32 v10, -|v10|, v20, v112
	v_max_f32_e32 v113, 0, v11
	v_fma_f32 v11, -|v11|, v21, v113
	v_max_f32_e32 v114, 0, v6
	v_fma_f32 v6, -|v6|, v22, v114
	v_max_f32_e32 v115, 0, v7
	v_fma_f32 v7, -|v7|, v23, v115
	v_sub_f32_e32 v10, v10, v14
	v_mul_f32_e32 v10, v12, v10
	v_sub_f32_e32 v11, v11, v14
	v_mul_f32_e32 v11, v12, v11
	v_sub_f32_e32 v6, v6, v15
	v_mul_f32_e32 v6, v13, v6
	v_sub_f32_e32 v7, v7, v15
	v_mul_f32_e32 v7, v13, v7
	ds_write_b32 v70, v3 offset:1360
	s_waitcnt vmcnt(0)
	v_fma_f32 v3, v8, v10, v4
	v_fma_f32 v10, v9, v11, v5
	v_fma_f32 v4, v8, v6, v4
	v_fmac_f32_e32 v5, v9, v7
	v_cvt_pk_bf16_f32 v3, v3, v4
	ds_write_b32 v70, v3 offset:1632
	v_cvt_pk_bf16_f32 v3, v10, v5
	global_load_dwordx4 v[8:11], v[18:19], off offset:16
	global_load_dwordx4 v[4:7], v[18:19], off offset:2064
	global_load_dwordx2 v[22:23], v2, s[0:1] offset:32
	global_load_dwordx2 v[20:21], v2, s[4:5] offset:32
	ds_write_b32 v70, v3 offset:1904
	s_waitcnt vmcnt(3)
	v_lshlrev_b32_e32 v24, 16, v8
	v_and_b32_e32 v25, 0xffff0000, v8
	s_waitcnt vmcnt(2)
	v_lshlrev_b32_e32 v34, 16, v4
	v_and_b32_e32 v35, 0xffff0000, v4
	v_fma_f32 v36, |v24|, s40, 1.0
	v_fma_f32 v37, |v25|, s40, 1.0
	v_fma_f32 v40, |v34|, s40, 1.0
	v_fma_f32 v41, |v35|, s40, 1.0
	v_rcp_f32_e32 v36, v36
	v_rcp_f32_e32 v37, v37
	v_rcp_f32_e32 v40, v40
	v_rcp_f32_e32 v41, v41
	v_pk_mul_f32 v[38:39], v[24:25], v[24:25]
	v_pk_mul_f32 v[42:43], v[34:35], v[34:35]
	v_pk_mul_f32 v[38:39], v[38:39], s[64:65] op_sel_hi:[1,0]
	v_pk_fma_f32 v[44:45], v[36:37], s[42:43], v[16:17] op_sel_hi:[1,0,0]
	v_pk_mul_f32 v[42:43], v[42:43], s[64:65] op_sel_hi:[1,0]
	v_exp_f32_e32 v38, v38
	v_exp_f32_e32 v39, v39
	v_pk_fma_f32 v[46:47], v[40:41], s[42:43], v[16:17] op_sel_hi:[1,0,0]
	v_pk_fma_f32 v[44:45], v[36:37], v[44:45], s[48:49] op_sel_hi:[1,1,0]
	v_exp_f32_e32 v42, v42
	v_exp_f32_e32 v43, v43
	v_pk_fma_f32 v[46:47], v[40:41], v[46:47], s[48:49] op_sel_hi:[1,1,0]
	v_pk_fma_f32 v[44:45], v[36:37], v[44:45], s[50:51] op_sel_hi:[1,1,0]
	v_pk_fma_f32 v[46:47], v[40:41], v[46:47], s[50:51] op_sel_hi:[1,1,0]
	v_pk_fma_f32 v[44:45], v[36:37], v[44:45], s[56:57] op_sel_hi:[1,1,0]
	v_pk_fma_f32 v[46:47], v[40:41], v[46:47], s[56:57] op_sel_hi:[1,1,0]
	v_pk_mul_f32 v[36:37], v[36:37], v[44:45]
	v_pk_mul_f32 v[40:41], v[40:41], v[46:47]
	v_pk_mul_f32 v[36:37], v[38:39], v[36:37]
	v_pk_mul_f32 v[38:39], v[42:43], v[40:41]
	v_max_f32_e32 v116, 0, v24
	v_fma_f32 v3, -|v24|, v36, v116
	v_max_f32_e32 v117, 0, v25
	v_fma_f32 v4, -|v25|, v37, v117
	v_max_f32_e32 v80, 0, v34
	v_fma_f32 v8, -|v34|, v38, v80
	v_max_f32_e32 v81, 0, v35
	v_fma_f32 v24, -|v35|, v39, v81
	v_sub_f32_e32 v3, v3, v14
	v_mul_f32_e32 v3, v12, v3
	v_sub_f32_e32 v4, v4, v14
	v_mul_f32_e32 v4, v12, v4
	v_sub_f32_e32 v8, v8, v15
	v_mul_f32_e32 v8, v13, v8
	v_sub_f32_e32 v24, v24, v15
	v_mul_f32_e32 v24, v13, v24
	s_waitcnt vmcnt(0)
	v_fma_f32 v3, v22, v3, v20
	v_fma_f32 v4, v23, v4, v21
	v_fma_f32 v8, v22, v8, v20
	v_fmac_f32_e32 v21, v23, v24
	v_cvt_pk_bf16_f32 v3, v3, v8
	ds_write_b32 v70, v3 offset:2176
	v_cvt_pk_bf16_f32 v3, v4, v21
	global_load_dwordx2 v[22:23], v2, s[0:1] offset:40
	global_load_dwordx2 v[20:21], v2, s[4:5] offset:40
	v_lshlrev_b32_e32 v8, 16, v9
	v_and_b32_e32 v9, 0xffff0000, v9
	v_lshlrev_b32_e32 v4, 16, v5
	v_and_b32_e32 v5, 0xffff0000, v5
	v_fma_f32 v24, |v8|, s40, 1.0
	v_fma_f32 v25, |v9|, s40, 1.0
	v_fma_f32 v36, |v4|, s40, 1.0
	v_fma_f32 v37, |v5|, s40, 1.0
	v_rcp_f32_e32 v24, v24
	v_rcp_f32_e32 v25, v25
	v_rcp_f32_e32 v36, v36
	v_rcp_f32_e32 v37, v37
	v_pk_mul_f32 v[34:35], v[8:9], v[8:9]
	v_pk_mul_f32 v[38:39], v[4:5], v[4:5]
	v_pk_mul_f32 v[34:35], v[34:35], s[64:65] op_sel_hi:[1,0]
	v_pk_fma_f32 v[40:41], v[24:25], s[42:43], v[16:17] op_sel_hi:[1,0,0]
	v_pk_mul_f32 v[38:39], v[38:39], s[64:65] op_sel_hi:[1,0]
	v_exp_f32_e32 v34, v34
	v_exp_f32_e32 v35, v35
	v_pk_fma_f32 v[42:43], v[36:37], s[42:43], v[16:17] op_sel_hi:[1,0,0]
	v_pk_fma_f32 v[40:41], v[24:25], v[40:41], s[48:49] op_sel_hi:[1,1,0]
	v_exp_f32_e32 v38, v38
	v_exp_f32_e32 v39, v39
	v_pk_fma_f32 v[42:43], v[36:37], v[42:43], s[48:49] op_sel_hi:[1,1,0]
	v_pk_fma_f32 v[40:41], v[24:25], v[40:41], s[50:51] op_sel_hi:[1,1,0]
	v_pk_fma_f32 v[42:43], v[36:37], v[42:43], s[50:51] op_sel_hi:[1,1,0]
	v_pk_fma_f32 v[40:41], v[24:25], v[40:41], s[56:57] op_sel_hi:[1,1,0]
	v_pk_fma_f32 v[42:43], v[36:37], v[42:43], s[56:57] op_sel_hi:[1,1,0]
	v_pk_mul_f32 v[24:25], v[24:25], v[40:41]
	v_pk_mul_f32 v[36:37], v[36:37], v[42:43]
	v_pk_mul_f32 v[24:25], v[34:35], v[24:25]
	v_pk_mul_f32 v[34:35], v[38:39], v[36:37]
	v_max_f32_e32 v82, 0, v8
	v_fma_f32 v8, -|v8|, v24, v82
	v_max_f32_e32 v83, 0, v9
	v_fma_f32 v9, -|v9|, v25, v83
	v_max_f32_e32 v84, 0, v4
	v_fma_f32 v4, -|v4|, v34, v84
	v_max_f32_e32 v85, 0, v5
	v_fma_f32 v5, -|v5|, v35, v85
	v_sub_f32_e32 v8, v8, v14
	v_mul_f32_e32 v8, v12, v8
	v_sub_f32_e32 v9, v9, v14
	v_mul_f32_e32 v9, v12, v9
	v_sub_f32_e32 v4, v4, v15
	v_mul_f32_e32 v4, v13, v4
	v_sub_f32_e32 v5, v5, v15
	ds_write_b32 v70, v3 offset:2448
	v_mul_f32_e32 v5, v13, v5
	s_waitcnt vmcnt(0)
	v_fma_f32 v3, v22, v8, v20
	v_fma_f32 v8, v23, v9, v21
	v_fma_f32 v4, v22, v4, v20
	v_cvt_pk_bf16_f32 v3, v3, v4
	v_fmac_f32_e32 v21, v23, v5
	ds_write_b32 v70, v3 offset:2720
	v_cvt_pk_bf16_f32 v3, v8, v21
	global_load_dwordx2 v[8:9], v2, s[0:1] offset:48
	global_load_dwordx2 v[4:5], v2, s[4:5] offset:48
	v_lshlrev_b32_e32 v20, 16, v10
	v_and_b32_e32 v21, 0xffff0000, v10
	v_lshlrev_b32_e32 v22, 16, v6
	v_and_b32_e32 v23, 0xffff0000, v6
	v_fma_f32 v24, |v20|, s40, 1.0
	v_fma_f32 v25, |v21|, s40, 1.0
	v_fma_f32 v36, |v22|, s40, 1.0
	v_fma_f32 v37, |v23|, s40, 1.0
	v_rcp_f32_e32 v24, v24
	v_rcp_f32_e32 v25, v25
	v_rcp_f32_e32 v36, v36
	v_rcp_f32_e32 v37, v37
	v_pk_mul_f32 v[34:35], v[20:21], v[20:21]
	v_pk_mul_f32 v[38:39], v[22:23], v[22:23]
	v_pk_mul_f32 v[34:35], v[34:35], s[64:65] op_sel_hi:[1,0]
	v_pk_fma_f32 v[40:41], v[24:25], s[42:43], v[16:17] op_sel_hi:[1,0,0]
	v_pk_mul_f32 v[38:39], v[38:39], s[64:65] op_sel_hi:[1,0]
	v_exp_f32_e32 v34, v34
	v_exp_f32_e32 v35, v35
	v_pk_fma_f32 v[42:43], v[36:37], s[42:43], v[16:17] op_sel_hi:[1,0,0]
	v_pk_fma_f32 v[40:41], v[24:25], v[40:41], s[48:49] op_sel_hi:[1,1,0]
	v_exp_f32_e32 v38, v38
	v_exp_f32_e32 v39, v39
	v_pk_fma_f32 v[42:43], v[36:37], v[42:43], s[48:49] op_sel_hi:[1,1,0]
	v_pk_fma_f32 v[40:41], v[24:25], v[40:41], s[50:51] op_sel_hi:[1,1,0]
	v_pk_fma_f32 v[42:43], v[36:37], v[42:43], s[50:51] op_sel_hi:[1,1,0]
	v_pk_fma_f32 v[40:41], v[24:25], v[40:41], s[56:57] op_sel_hi:[1,1,0]
	v_pk_fma_f32 v[42:43], v[36:37], v[42:43], s[56:57] op_sel_hi:[1,1,0]
	v_pk_mul_f32 v[24:25], v[24:25], v[40:41]
	v_pk_mul_f32 v[36:37], v[36:37], v[42:43]
	v_pk_mul_f32 v[24:25], v[34:35], v[24:25]
	v_pk_mul_f32 v[34:35], v[38:39], v[36:37]
	v_max_f32_e32 v86, 0, v20
	v_fma_f32 v6, -|v20|, v24, v86
	v_max_f32_e32 v90, 0, v21
	v_fma_f32 v10, -|v21|, v25, v90
	v_max_f32_e32 v91, 0, v22
	v_fma_f32 v20, -|v22|, v34, v91
	v_max_f32_e32 v92, 0, v23
	v_fma_f32 v21, -|v23|, v35, v92
	v_sub_f32_e32 v6, v6, v14
	v_mul_f32_e32 v6, v12, v6
	v_sub_f32_e32 v10, v10, v14
	v_mul_f32_e32 v10, v12, v10
	v_sub_f32_e32 v20, v20, v15
	v_mul_f32_e32 v20, v13, v20
	v_sub_f32_e32 v21, v21, v15
	v_mul_f32_e32 v21, v13, v21
	ds_write_b32 v70, v3 offset:2992
	s_waitcnt vmcnt(0)
	v_fma_f32 v3, v8, v6, v4
	v_fma_f32 v6, v9, v10, v5
	v_fma_f32 v4, v8, v20, v4
	v_fmac_f32_e32 v5, v9, v21
	v_cvt_pk_bf16_f32 v3, v3, v4
	ds_write_b32 v70, v3 offset:3264
	v_cvt_pk_bf16_f32 v3, v6, v5
	global_load_dwordx2 v[8:9], v2, s[0:1] offset:56
	global_load_dwordx2 v[4:5], v2, s[4:5] offset:56
	v_lshlrev_b32_e32 v10, 16, v11
	v_and_b32_e32 v11, 0xffff0000, v11
	v_lshlrev_b32_e32 v6, 16, v7
	v_and_b32_e32 v7, 0xffff0000, v7
	v_fma_f32 v20, |v10|, s40, 1.0
	v_fma_f32 v21, |v11|, s40, 1.0
	v_fma_f32 v24, |v6|, s40, 1.0
	v_fma_f32 v25, |v7|, s40, 1.0
	v_rcp_f32_e32 v20, v20
	v_rcp_f32_e32 v21, v21
	v_rcp_f32_e32 v24, v24
	v_rcp_f32_e32 v25, v25
	v_pk_mul_f32 v[22:23], v[10:11], v[10:11]
	v_pk_mul_f32 v[34:35], v[6:7], v[6:7]
	v_pk_mul_f32 v[22:23], v[22:23], s[64:65] op_sel_hi:[1,0]
	v_pk_fma_f32 v[36:37], v[20:21], s[42:43], v[16:17] op_sel_hi:[1,0,0]
	v_pk_mul_f32 v[34:35], v[34:35], s[64:65] op_sel_hi:[1,0]
	v_exp_f32_e32 v22, v22
	v_exp_f32_e32 v23, v23
	v_pk_fma_f32 v[38:39], v[24:25], s[42:43], v[16:17] op_sel_hi:[1,0,0]
	v_pk_fma_f32 v[36:37], v[20:21], v[36:37], s[48:49] op_sel_hi:[1,1,0]
	v_exp_f32_e32 v34, v34
	v_exp_f32_e32 v35, v35
	v_pk_fma_f32 v[38:39], v[24:25], v[38:39], s[48:49] op_sel_hi:[1,1,0]
	v_pk_fma_f32 v[36:37], v[20:21], v[36:37], s[50:51] op_sel_hi:[1,1,0]
	v_pk_fma_f32 v[38:39], v[24:25], v[38:39], s[50:51] op_sel_hi:[1,1,0]
	v_pk_fma_f32 v[36:37], v[20:21], v[36:37], s[56:57] op_sel_hi:[1,1,0]
	v_pk_fma_f32 v[38:39], v[24:25], v[38:39], s[56:57] op_sel_hi:[1,1,0]
	v_pk_mul_f32 v[20:21], v[20:21], v[36:37]
	v_pk_mul_f32 v[24:25], v[24:25], v[38:39]
	v_pk_mul_f32 v[20:21], v[22:23], v[20:21]
	v_pk_mul_f32 v[22:23], v[34:35], v[24:25]
	v_max_f32_e32 v93, 0, v10
	v_fma_f32 v10, -|v10|, v20, v93
	v_max_f32_e32 v94, 0, v11
	v_fma_f32 v11, -|v11|, v21, v94
	v_max_f32_e32 v95, 0, v6
	v_fma_f32 v6, -|v6|, v22, v95
	v_max_f32_e32 v96, 0, v7
	v_fma_f32 v7, -|v7|, v23, v96
	v_sub_f32_e32 v10, v10, v14
	v_mul_f32_e32 v10, v12, v10
	v_sub_f32_e32 v11, v11, v14
	v_mul_f32_e32 v11, v12, v11
	v_sub_f32_e32 v6, v6, v15
	v_mul_f32_e32 v6, v13, v6
	v_sub_f32_e32 v7, v7, v15
	v_mul_f32_e32 v7, v13, v7
	ds_write_b32 v70, v3 offset:3536
	s_waitcnt vmcnt(0)
	v_fma_f32 v3, v8, v10, v4
	v_fma_f32 v10, v9, v11, v5
	v_fma_f32 v4, v8, v6, v4
	v_fmac_f32_e32 v5, v9, v7
	v_cvt_pk_bf16_f32 v3, v3, v4
	ds_write_b32 v70, v3 offset:3808
	v_cvt_pk_bf16_f32 v3, v10, v5
	global_load_dwordx4 v[8:11], v[18:19], off offset:32
	global_load_dwordx4 v[4:7], v[18:19], off offset:2080
	global_load_dwordx2 v[22:23], v2, s[0:1] offset:64
	global_load_dwordx2 v[20:21], v2, s[4:5] offset:64
	ds_write_b32 v70, v3 offset:4080
	s_waitcnt vmcnt(3)
	v_lshlrev_b32_e32 v24, 16, v8
	v_and_b32_e32 v25, 0xffff0000, v8
	s_waitcnt vmcnt(2)
	v_lshlrev_b32_e32 v34, 16, v4
	v_and_b32_e32 v35, 0xffff0000, v4
	v_fma_f32 v36, |v24|, s40, 1.0
	v_fma_f32 v37, |v25|, s40, 1.0
	v_fma_f32 v40, |v34|, s40, 1.0
	v_fma_f32 v41, |v35|, s40, 1.0
	v_rcp_f32_e32 v36, v36
	v_rcp_f32_e32 v37, v37
	v_rcp_f32_e32 v40, v40
	v_rcp_f32_e32 v41, v41
	v_pk_mul_f32 v[38:39], v[24:25], v[24:25]
	v_pk_mul_f32 v[42:43], v[34:35], v[34:35]
	v_pk_mul_f32 v[38:39], v[38:39], s[64:65] op_sel_hi:[1,0]
	v_pk_fma_f32 v[44:45], v[36:37], s[42:43], v[16:17] op_sel_hi:[1,0,0]
	v_pk_mul_f32 v[42:43], v[42:43], s[64:65] op_sel_hi:[1,0]
	v_exp_f32_e32 v38, v38
	v_exp_f32_e32 v39, v39
	v_pk_fma_f32 v[46:47], v[40:41], s[42:43], v[16:17] op_sel_hi:[1,0,0]
	v_pk_fma_f32 v[44:45], v[36:37], v[44:45], s[48:49] op_sel_hi:[1,1,0]
	v_exp_f32_e32 v42, v42
	v_exp_f32_e32 v43, v43
	v_pk_fma_f32 v[46:47], v[40:41], v[46:47], s[48:49] op_sel_hi:[1,1,0]
	v_pk_fma_f32 v[44:45], v[36:37], v[44:45], s[50:51] op_sel_hi:[1,1,0]
	v_pk_fma_f32 v[46:47], v[40:41], v[46:47], s[50:51] op_sel_hi:[1,1,0]
	v_pk_fma_f32 v[44:45], v[36:37], v[44:45], s[56:57] op_sel_hi:[1,1,0]
	v_pk_fma_f32 v[46:47], v[40:41], v[46:47], s[56:57] op_sel_hi:[1,1,0]
	v_pk_mul_f32 v[36:37], v[36:37], v[44:45]
	v_pk_mul_f32 v[40:41], v[40:41], v[46:47]
	v_pk_mul_f32 v[36:37], v[38:39], v[36:37]
	v_pk_mul_f32 v[38:39], v[42:43], v[40:41]
	v_max_f32_e32 v97, 0, v24
	v_fma_f32 v3, -|v24|, v36, v97
	v_max_f32_e32 v98, 0, v25
	v_fma_f32 v4, -|v25|, v37, v98
	v_max_f32_e32 v99, 0, v34
	v_fma_f32 v8, -|v34|, v38, v99
	v_max_f32_e32 v100, 0, v35
	v_fma_f32 v24, -|v35|, v39, v100
	v_sub_f32_e32 v3, v3, v14
	v_mul_f32_e32 v3, v12, v3
	v_sub_f32_e32 v4, v4, v14
	v_mul_f32_e32 v4, v12, v4
	v_sub_f32_e32 v8, v8, v15
	v_mul_f32_e32 v8, v13, v8
	v_sub_f32_e32 v24, v24, v15
	v_mul_f32_e32 v24, v13, v24
	s_waitcnt vmcnt(0)
	v_fma_f32 v3, v22, v3, v20
	v_fma_f32 v4, v23, v4, v21
	v_fma_f32 v8, v22, v8, v20
	v_fmac_f32_e32 v21, v23, v24
	v_cvt_pk_bf16_f32 v3, v3, v8
	ds_write_b32 v70, v3 offset:4352
	v_cvt_pk_bf16_f32 v3, v4, v21
	global_load_dwordx2 v[22:23], v2, s[0:1] offset:72
	global_load_dwordx2 v[20:21], v2, s[4:5] offset:72
	v_lshlrev_b32_e32 v8, 16, v9
	v_and_b32_e32 v9, 0xffff0000, v9
	v_lshlrev_b32_e32 v4, 16, v5
	v_and_b32_e32 v5, 0xffff0000, v5
	v_fma_f32 v24, |v8|, s40, 1.0
	v_fma_f32 v25, |v9|, s40, 1.0
	v_fma_f32 v36, |v4|, s40, 1.0
	v_fma_f32 v37, |v5|, s40, 1.0
	v_rcp_f32_e32 v24, v24
	v_rcp_f32_e32 v25, v25
	v_rcp_f32_e32 v36, v36
	v_rcp_f32_e32 v37, v37
	v_pk_mul_f32 v[34:35], v[8:9], v[8:9]
	v_pk_mul_f32 v[38:39], v[4:5], v[4:5]
	v_pk_mul_f32 v[34:35], v[34:35], s[64:65] op_sel_hi:[1,0]
	v_pk_fma_f32 v[40:41], v[24:25], s[42:43], v[16:17] op_sel_hi:[1,0,0]
	v_pk_mul_f32 v[38:39], v[38:39], s[64:65] op_sel_hi:[1,0]
	v_exp_f32_e32 v34, v34
	v_exp_f32_e32 v35, v35
	v_pk_fma_f32 v[42:43], v[36:37], s[42:43], v[16:17] op_sel_hi:[1,0,0]
	v_pk_fma_f32 v[40:41], v[24:25], v[40:41], s[48:49] op_sel_hi:[1,1,0]
	v_exp_f32_e32 v38, v38
	v_exp_f32_e32 v39, v39
	v_pk_fma_f32 v[42:43], v[36:37], v[42:43], s[48:49] op_sel_hi:[1,1,0]
	v_pk_fma_f32 v[40:41], v[24:25], v[40:41], s[50:51] op_sel_hi:[1,1,0]
	v_pk_fma_f32 v[42:43], v[36:37], v[42:43], s[50:51] op_sel_hi:[1,1,0]
	v_pk_fma_f32 v[40:41], v[24:25], v[40:41], s[56:57] op_sel_hi:[1,1,0]
	v_pk_fma_f32 v[42:43], v[36:37], v[42:43], s[56:57] op_sel_hi:[1,1,0]
	v_pk_mul_f32 v[24:25], v[24:25], v[40:41]
	v_pk_mul_f32 v[36:37], v[36:37], v[42:43]
	v_pk_mul_f32 v[24:25], v[34:35], v[24:25]
	v_pk_mul_f32 v[34:35], v[38:39], v[36:37]
	v_max_f32_e32 v104, 0, v8
	v_fma_f32 v8, -|v8|, v24, v104
	v_max_f32_e32 v105, 0, v9
	v_fma_f32 v9, -|v9|, v25, v105
	v_max_f32_e32 v106, 0, v4
	v_fma_f32 v4, -|v4|, v34, v106
	v_max_f32_e32 v107, 0, v5
	v_fma_f32 v5, -|v5|, v35, v107
	v_sub_f32_e32 v8, v8, v14
	v_mul_f32_e32 v8, v12, v8
	v_sub_f32_e32 v9, v9, v14
	v_mul_f32_e32 v9, v12, v9
	v_sub_f32_e32 v4, v4, v15
	v_mul_f32_e32 v4, v13, v4
	v_sub_f32_e32 v5, v5, v15
	ds_write_b32 v70, v3 offset:4624
	v_mul_f32_e32 v5, v13, v5
	s_waitcnt vmcnt(0)
	v_fma_f32 v3, v22, v8, v20
	v_fma_f32 v8, v23, v9, v21
	v_fma_f32 v4, v22, v4, v20
	v_cvt_pk_bf16_f32 v3, v3, v4
	v_fmac_f32_e32 v21, v23, v5
	ds_write_b32 v70, v3 offset:4896
	v_cvt_pk_bf16_f32 v3, v8, v21
	global_load_dwordx2 v[8:9], v2, s[0:1] offset:80
	global_load_dwordx2 v[4:5], v2, s[4:5] offset:80
	v_lshlrev_b32_e32 v20, 16, v10
	v_and_b32_e32 v21, 0xffff0000, v10
	v_lshlrev_b32_e32 v22, 16, v6
	v_and_b32_e32 v23, 0xffff0000, v6
	v_fma_f32 v24, |v20|, s40, 1.0
	v_fma_f32 v25, |v21|, s40, 1.0
	v_fma_f32 v36, |v22|, s40, 1.0
	v_fma_f32 v37, |v23|, s40, 1.0
	v_rcp_f32_e32 v24, v24
	v_rcp_f32_e32 v25, v25
	v_rcp_f32_e32 v36, v36
	v_rcp_f32_e32 v37, v37
	v_pk_mul_f32 v[34:35], v[20:21], v[20:21]
	v_pk_mul_f32 v[38:39], v[22:23], v[22:23]
	v_pk_mul_f32 v[34:35], v[34:35], s[64:65] op_sel_hi:[1,0]
	v_pk_fma_f32 v[40:41], v[24:25], s[42:43], v[16:17] op_sel_hi:[1,0,0]
	v_pk_mul_f32 v[38:39], v[38:39], s[64:65] op_sel_hi:[1,0]
	v_exp_f32_e32 v34, v34
	v_exp_f32_e32 v35, v35
	v_pk_fma_f32 v[42:43], v[36:37], s[42:43], v[16:17] op_sel_hi:[1,0,0]
	v_pk_fma_f32 v[40:41], v[24:25], v[40:41], s[48:49] op_sel_hi:[1,1,0]
	v_exp_f32_e32 v38, v38
	v_exp_f32_e32 v39, v39
	v_pk_fma_f32 v[42:43], v[36:37], v[42:43], s[48:49] op_sel_hi:[1,1,0]
	v_pk_fma_f32 v[40:41], v[24:25], v[40:41], s[50:51] op_sel_hi:[1,1,0]
	v_pk_fma_f32 v[42:43], v[36:37], v[42:43], s[50:51] op_sel_hi:[1,1,0]
	v_pk_fma_f32 v[40:41], v[24:25], v[40:41], s[56:57] op_sel_hi:[1,1,0]
	v_pk_fma_f32 v[42:43], v[36:37], v[42:43], s[56:57] op_sel_hi:[1,1,0]
	v_pk_mul_f32 v[24:25], v[24:25], v[40:41]
	v_pk_mul_f32 v[36:37], v[36:37], v[42:43]
	v_pk_mul_f32 v[24:25], v[34:35], v[24:25]
	v_pk_mul_f32 v[34:35], v[38:39], v[36:37]
	v_max_f32_e32 v108, 0, v20
	v_fma_f32 v6, -|v20|, v24, v108
	v_max_f32_e32 v109, 0, v21
	v_fma_f32 v10, -|v21|, v25, v109
	v_max_f32_e32 v110, 0, v22
	v_fma_f32 v20, -|v22|, v34, v110
	v_max_f32_e32 v111, 0, v23
	v_fma_f32 v21, -|v23|, v35, v111
	v_sub_f32_e32 v6, v6, v14
	v_mul_f32_e32 v6, v12, v6
	v_sub_f32_e32 v10, v10, v14
	v_mul_f32_e32 v10, v12, v10
	v_sub_f32_e32 v20, v20, v15
	v_mul_f32_e32 v20, v13, v20
	v_sub_f32_e32 v21, v21, v15
	v_mul_f32_e32 v21, v13, v21
	ds_write_b32 v70, v3 offset:5168
	s_waitcnt vmcnt(0)
	v_fma_f32 v3, v8, v6, v4
	v_fma_f32 v6, v9, v10, v5
	v_fma_f32 v4, v8, v20, v4
	v_fmac_f32_e32 v5, v9, v21
	v_cvt_pk_bf16_f32 v3, v3, v4
	ds_write_b32 v70, v3 offset:5440
	v_cvt_pk_bf16_f32 v3, v6, v5
	global_load_dwordx2 v[8:9], v2, s[0:1] offset:88
	global_load_dwordx2 v[4:5], v2, s[4:5] offset:88
	v_lshlrev_b32_e32 v10, 16, v11
	v_and_b32_e32 v11, 0xffff0000, v11
	v_lshlrev_b32_e32 v6, 16, v7
	v_and_b32_e32 v7, 0xffff0000, v7
	v_fma_f32 v20, |v10|, s40, 1.0
	v_fma_f32 v21, |v11|, s40, 1.0
	v_fma_f32 v24, |v6|, s40, 1.0
	v_fma_f32 v25, |v7|, s40, 1.0
	v_rcp_f32_e32 v20, v20
	v_rcp_f32_e32 v21, v21
	v_rcp_f32_e32 v24, v24
	v_rcp_f32_e32 v25, v25
	v_pk_mul_f32 v[22:23], v[10:11], v[10:11]
	v_pk_mul_f32 v[34:35], v[6:7], v[6:7]
	v_pk_mul_f32 v[22:23], v[22:23], s[64:65] op_sel_hi:[1,0]
	v_pk_fma_f32 v[36:37], v[20:21], s[42:43], v[16:17] op_sel_hi:[1,0,0]
	v_pk_mul_f32 v[34:35], v[34:35], s[64:65] op_sel_hi:[1,0]
	v_exp_f32_e32 v22, v22
	v_exp_f32_e32 v23, v23
	v_pk_fma_f32 v[38:39], v[24:25], s[42:43], v[16:17] op_sel_hi:[1,0,0]
	v_pk_fma_f32 v[36:37], v[20:21], v[36:37], s[48:49] op_sel_hi:[1,1,0]
	v_exp_f32_e32 v34, v34
	v_exp_f32_e32 v35, v35
	v_pk_fma_f32 v[38:39], v[24:25], v[38:39], s[48:49] op_sel_hi:[1,1,0]
	v_pk_fma_f32 v[36:37], v[20:21], v[36:37], s[50:51] op_sel_hi:[1,1,0]
	v_pk_fma_f32 v[38:39], v[24:25], v[38:39], s[50:51] op_sel_hi:[1,1,0]
	v_pk_fma_f32 v[36:37], v[20:21], v[36:37], s[56:57] op_sel_hi:[1,1,0]
	v_pk_fma_f32 v[38:39], v[24:25], v[38:39], s[56:57] op_sel_hi:[1,1,0]
	v_pk_mul_f32 v[20:21], v[20:21], v[36:37]
	v_pk_mul_f32 v[24:25], v[24:25], v[38:39]
	v_pk_mul_f32 v[20:21], v[22:23], v[20:21]
	v_pk_mul_f32 v[22:23], v[34:35], v[24:25]
	v_max_f32_e32 v112, 0, v10
	v_fma_f32 v10, -|v10|, v20, v112
	v_max_f32_e32 v113, 0, v11
	v_fma_f32 v11, -|v11|, v21, v113
	v_max_f32_e32 v114, 0, v6
	v_fma_f32 v6, -|v6|, v22, v114
	v_max_f32_e32 v115, 0, v7
	v_fma_f32 v7, -|v7|, v23, v115
	v_sub_f32_e32 v10, v10, v14
	v_mul_f32_e32 v10, v12, v10
	v_sub_f32_e32 v11, v11, v14
	v_mul_f32_e32 v11, v12, v11
	v_sub_f32_e32 v6, v6, v15
	v_mul_f32_e32 v6, v13, v6
	v_sub_f32_e32 v7, v7, v15
	v_mul_f32_e32 v7, v13, v7
	ds_write_b32 v70, v3 offset:5712
	s_waitcnt vmcnt(0)
	v_fma_f32 v3, v8, v10, v4
	v_fma_f32 v10, v9, v11, v5
	v_fma_f32 v4, v8, v6, v4
	v_fmac_f32_e32 v5, v9, v7
	v_cvt_pk_bf16_f32 v3, v3, v4
	ds_write_b32 v70, v3 offset:5984
	v_cvt_pk_bf16_f32 v3, v10, v5
	global_load_dwordx4 v[8:11], v[18:19], off offset:48
	global_load_dwordx4 v[4:7], v[18:19], off offset:2096
	global_load_dwordx2 v[20:21], v2, s[0:1] offset:96
	s_nop 0
	global_load_dwordx2 v[18:19], v2, s[4:5] offset:96
	ds_write_b32 v70, v3 offset:6256
	s_waitcnt vmcnt(3)
	v_lshlrev_b32_e32 v22, 16, v8
	v_and_b32_e32 v23, 0xffff0000, v8
	s_waitcnt vmcnt(2)
	v_lshlrev_b32_e32 v24, 16, v4
	v_and_b32_e32 v25, 0xffff0000, v4
	v_fma_f32 v34, |v22|, s40, 1.0
	v_fma_f32 v35, |v23|, s40, 1.0
	v_fma_f32 v38, |v24|, s40, 1.0
	v_fma_f32 v39, |v25|, s40, 1.0
	v_rcp_f32_e32 v34, v34
	v_rcp_f32_e32 v35, v35
	v_rcp_f32_e32 v38, v38
	v_rcp_f32_e32 v39, v39
	v_pk_mul_f32 v[36:37], v[22:23], v[22:23]
	v_pk_mul_f32 v[40:41], v[24:25], v[24:25]
	v_pk_mul_f32 v[36:37], v[36:37], s[64:65] op_sel_hi:[1,0]
	v_pk_fma_f32 v[42:43], v[34:35], s[42:43], v[16:17] op_sel_hi:[1,0,0]
	v_pk_mul_f32 v[40:41], v[40:41], s[64:65] op_sel_hi:[1,0]
	v_exp_f32_e32 v36, v36
	v_exp_f32_e32 v37, v37
	v_pk_fma_f32 v[44:45], v[38:39], s[42:43], v[16:17] op_sel_hi:[1,0,0]
	v_pk_fma_f32 v[42:43], v[34:35], v[42:43], s[48:49] op_sel_hi:[1,1,0]
	v_exp_f32_e32 v40, v40
	v_exp_f32_e32 v41, v41
	v_pk_fma_f32 v[44:45], v[38:39], v[44:45], s[48:49] op_sel_hi:[1,1,0]
	v_pk_fma_f32 v[42:43], v[34:35], v[42:43], s[50:51] op_sel_hi:[1,1,0]
	v_pk_fma_f32 v[44:45], v[38:39], v[44:45], s[50:51] op_sel_hi:[1,1,0]
	v_pk_fma_f32 v[42:43], v[34:35], v[42:43], s[56:57] op_sel_hi:[1,1,0]
	v_pk_fma_f32 v[44:45], v[38:39], v[44:45], s[56:57] op_sel_hi:[1,1,0]
	v_pk_mul_f32 v[34:35], v[34:35], v[42:43]
	v_pk_mul_f32 v[38:39], v[38:39], v[44:45]
	v_pk_mul_f32 v[34:35], v[36:37], v[34:35]
	v_pk_mul_f32 v[36:37], v[40:41], v[38:39]
	v_max_f32_e32 v116, 0, v22
	v_fma_f32 v3, -|v22|, v34, v116
	v_max_f32_e32 v117, 0, v23
	v_fma_f32 v4, -|v23|, v35, v117
	v_max_f32_e32 v80, 0, v24
	v_fma_f32 v8, -|v24|, v36, v80
	v_max_f32_e32 v81, 0, v25
	v_fma_f32 v22, -|v25|, v37, v81
	v_sub_f32_e32 v3, v3, v14
	v_mul_f32_e32 v3, v12, v3
	v_sub_f32_e32 v4, v4, v14
	v_mul_f32_e32 v4, v12, v4
	v_sub_f32_e32 v8, v8, v15
	v_mul_f32_e32 v8, v13, v8
	v_sub_f32_e32 v22, v22, v15
	v_mul_f32_e32 v22, v13, v22
	s_waitcnt vmcnt(0)
	v_fma_f32 v3, v20, v3, v18
	v_fma_f32 v4, v21, v4, v19
	v_fma_f32 v8, v20, v8, v18
	v_fmac_f32_e32 v19, v21, v22
	v_cvt_pk_bf16_f32 v3, v3, v8
	ds_write_b32 v70, v3 offset:6528
	v_cvt_pk_bf16_f32 v3, v4, v19
	global_load_dwordx2 v[20:21], v2, s[0:1] offset:104
	global_load_dwordx2 v[18:19], v2, s[4:5] offset:104
	v_lshlrev_b32_e32 v8, 16, v9
	v_and_b32_e32 v9, 0xffff0000, v9
	v_lshlrev_b32_e32 v4, 16, v5
	v_and_b32_e32 v5, 0xffff0000, v5
	v_fma_f32 v22, |v8|, s40, 1.0
	v_fma_f32 v23, |v9|, s40, 1.0
	v_fma_f32 v34, |v4|, s40, 1.0
	v_fma_f32 v35, |v5|, s40, 1.0
	v_rcp_f32_e32 v22, v22
	v_rcp_f32_e32 v23, v23
	v_rcp_f32_e32 v34, v34
	v_rcp_f32_e32 v35, v35
	v_pk_mul_f32 v[24:25], v[8:9], v[8:9]
	v_pk_mul_f32 v[36:37], v[4:5], v[4:5]
	v_pk_mul_f32 v[24:25], v[24:25], s[64:65] op_sel_hi:[1,0]
	v_pk_fma_f32 v[38:39], v[22:23], s[42:43], v[16:17] op_sel_hi:[1,0,0]
	v_pk_mul_f32 v[36:37], v[36:37], s[64:65] op_sel_hi:[1,0]
	v_exp_f32_e32 v24, v24
	v_exp_f32_e32 v25, v25
	v_pk_fma_f32 v[40:41], v[34:35], s[42:43], v[16:17] op_sel_hi:[1,0,0]
	v_pk_fma_f32 v[38:39], v[22:23], v[38:39], s[48:49] op_sel_hi:[1,1,0]
	v_exp_f32_e32 v36, v36
	v_exp_f32_e32 v37, v37
	v_pk_fma_f32 v[40:41], v[34:35], v[40:41], s[48:49] op_sel_hi:[1,1,0]
	v_pk_fma_f32 v[38:39], v[22:23], v[38:39], s[50:51] op_sel_hi:[1,1,0]
	v_pk_fma_f32 v[40:41], v[34:35], v[40:41], s[50:51] op_sel_hi:[1,1,0]
	v_pk_fma_f32 v[38:39], v[22:23], v[38:39], s[56:57] op_sel_hi:[1,1,0]
	v_pk_fma_f32 v[40:41], v[34:35], v[40:41], s[56:57] op_sel_hi:[1,1,0]
	v_pk_mul_f32 v[22:23], v[22:23], v[38:39]
	v_pk_mul_f32 v[34:35], v[34:35], v[40:41]
	v_pk_mul_f32 v[22:23], v[24:25], v[22:23]
	v_pk_mul_f32 v[24:25], v[36:37], v[34:35]
	v_max_f32_e32 v82, 0, v8
	v_fma_f32 v8, -|v8|, v22, v82
	v_max_f32_e32 v83, 0, v9
	v_fma_f32 v9, -|v9|, v23, v83
	v_max_f32_e32 v84, 0, v4
	v_fma_f32 v4, -|v4|, v24, v84
	v_max_f32_e32 v85, 0, v5
	v_fma_f32 v5, -|v5|, v25, v85
	v_sub_f32_e32 v8, v8, v14
	v_mul_f32_e32 v8, v12, v8
	v_sub_f32_e32 v9, v9, v14
	v_mul_f32_e32 v9, v12, v9
	v_sub_f32_e32 v4, v4, v15
	v_mul_f32_e32 v4, v13, v4
	v_sub_f32_e32 v5, v5, v15
	ds_write_b32 v70, v3 offset:6800
	v_mul_f32_e32 v5, v13, v5
	s_waitcnt vmcnt(0)
	v_fma_f32 v3, v20, v8, v18
	v_fma_f32 v8, v21, v9, v19
	v_fma_f32 v4, v20, v4, v18
	v_cvt_pk_bf16_f32 v3, v3, v4
	v_fmac_f32_e32 v19, v21, v5
	ds_write_b32 v70, v3 offset:7072
	v_cvt_pk_bf16_f32 v3, v8, v19
	global_load_dwordx2 v[8:9], v2, s[0:1] offset:112
	global_load_dwordx2 v[4:5], v2, s[4:5] offset:112
	v_lshlrev_b32_e32 v18, 16, v10
	v_and_b32_e32 v19, 0xffff0000, v10
	v_lshlrev_b32_e32 v20, 16, v6
	v_and_b32_e32 v21, 0xffff0000, v6
	v_fma_f32 v22, |v18|, s40, 1.0
	v_fma_f32 v23, |v19|, s40, 1.0
	v_fma_f32 v34, |v20|, s40, 1.0
	v_fma_f32 v35, |v21|, s40, 1.0
	v_rcp_f32_e32 v22, v22
	v_rcp_f32_e32 v23, v23
	v_rcp_f32_e32 v34, v34
	v_rcp_f32_e32 v35, v35
	v_pk_mul_f32 v[24:25], v[18:19], v[18:19]
	v_pk_mul_f32 v[36:37], v[20:21], v[20:21]
	v_pk_mul_f32 v[24:25], v[24:25], s[64:65] op_sel_hi:[1,0]
	v_pk_fma_f32 v[38:39], v[22:23], s[42:43], v[16:17] op_sel_hi:[1,0,0]
	v_pk_mul_f32 v[36:37], v[36:37], s[64:65] op_sel_hi:[1,0]
	v_exp_f32_e32 v24, v24
	v_exp_f32_e32 v25, v25
	v_pk_fma_f32 v[40:41], v[34:35], s[42:43], v[16:17] op_sel_hi:[1,0,0]
	v_pk_fma_f32 v[38:39], v[22:23], v[38:39], s[48:49] op_sel_hi:[1,1,0]
	v_exp_f32_e32 v36, v36
	v_exp_f32_e32 v37, v37
	v_pk_fma_f32 v[40:41], v[34:35], v[40:41], s[48:49] op_sel_hi:[1,1,0]
	v_pk_fma_f32 v[38:39], v[22:23], v[38:39], s[50:51] op_sel_hi:[1,1,0]
	v_pk_fma_f32 v[40:41], v[34:35], v[40:41], s[50:51] op_sel_hi:[1,1,0]
	v_pk_fma_f32 v[38:39], v[22:23], v[38:39], s[56:57] op_sel_hi:[1,1,0]
	v_pk_fma_f32 v[40:41], v[34:35], v[40:41], s[56:57] op_sel_hi:[1,1,0]
	v_pk_mul_f32 v[22:23], v[22:23], v[38:39]
	v_pk_mul_f32 v[34:35], v[34:35], v[40:41]
	v_pk_mul_f32 v[22:23], v[24:25], v[22:23]
	v_pk_mul_f32 v[24:25], v[36:37], v[34:35]
	v_max_f32_e32 v86, 0, v18
	v_fma_f32 v6, -|v18|, v22, v86
	v_max_f32_e32 v90, 0, v19
	v_fma_f32 v10, -|v19|, v23, v90
	v_max_f32_e32 v91, 0, v20
	v_fma_f32 v18, -|v20|, v24, v91
	v_max_f32_e32 v92, 0, v21
	v_fma_f32 v19, -|v21|, v25, v92
	v_sub_f32_e32 v6, v6, v14
	v_mul_f32_e32 v6, v12, v6
	v_sub_f32_e32 v10, v10, v14
	v_mul_f32_e32 v10, v12, v10
	v_sub_f32_e32 v18, v18, v15
	v_mul_f32_e32 v18, v13, v18
	v_sub_f32_e32 v19, v19, v15
	v_mul_f32_e32 v19, v13, v19
	ds_write_b32 v70, v3 offset:7344
	s_andn2_b64 vcc, exec, s[80:81]
	s_waitcnt vmcnt(0)
	v_fma_f32 v3, v8, v6, v4
	v_fma_f32 v6, v9, v10, v5
	v_fma_f32 v4, v8, v18, v4
	v_fmac_f32_e32 v5, v9, v19
	v_cvt_pk_bf16_f32 v3, v3, v4
	ds_write_b32 v70, v3 offset:7616
	v_cvt_pk_bf16_f32 v3, v6, v5
	global_load_dwordx2 v[8:9], v2, s[0:1] offset:120
	global_load_dwordx2 v[4:5], v2, s[4:5] offset:120
	v_lshlrev_b32_e32 v10, 16, v11
	v_and_b32_e32 v11, 0xffff0000, v11
	v_cndmask_b32_e64 v6, 0, 1, s[80:81]
	v_cmp_ne_u32_e64 s[4:5], 1, v6
	v_lshlrev_b32_e32 v6, 16, v7
	v_and_b32_e32 v7, 0xffff0000, v7
	v_fma_f32 v18, |v10|, s40, 1.0
	v_fma_f32 v19, |v11|, s40, 1.0
	v_rcp_f32_e32 v18, v18
	v_rcp_f32_e32 v19, v19
	v_fma_f32 v22, |v6|, s40, 1.0
	v_fma_f32 v23, |v7|, s40, 1.0
	v_pk_mul_f32 v[20:21], v[10:11], v[10:11]
	v_rcp_f32_e32 v22, v22
	v_rcp_f32_e32 v23, v23
	v_pk_mul_f32 v[20:21], v[20:21], s[64:65] op_sel_hi:[1,0]
	v_pk_fma_f32 v[34:35], v[18:19], s[42:43], v[16:17] op_sel_hi:[1,0,0]
	v_pk_mul_f32 v[24:25], v[6:7], v[6:7]
	v_exp_f32_e32 v20, v20
	v_exp_f32_e32 v21, v21
	v_pk_fma_f32 v[34:35], v[18:19], v[34:35], s[48:49] op_sel_hi:[1,1,0]
	v_pk_mul_f32 v[24:25], v[24:25], s[64:65] op_sel_hi:[1,0]
	v_pk_fma_f32 v[16:17], v[22:23], s[42:43], v[16:17] op_sel_hi:[1,0,0]
	v_pk_fma_f32 v[34:35], v[18:19], v[34:35], s[50:51] op_sel_hi:[1,1,0]
	v_exp_f32_e32 v24, v24
	v_exp_f32_e32 v25, v25
	v_pk_fma_f32 v[16:17], v[22:23], v[16:17], s[48:49] op_sel_hi:[1,1,0]
	v_pk_fma_f32 v[34:35], v[18:19], v[34:35], s[56:57] op_sel_hi:[1,1,0]
	v_pk_fma_f32 v[16:17], v[22:23], v[16:17], s[50:51] op_sel_hi:[1,1,0]
	v_pk_mul_f32 v[18:19], v[18:19], v[34:35]
	v_pk_fma_f32 v[16:17], v[22:23], v[16:17], s[56:57] op_sel_hi:[1,1,0]
	v_pk_mul_f32 v[18:19], v[20:21], v[18:19]
	v_pk_mul_f32 v[16:17], v[22:23], v[16:17]
	v_max_f32_e32 v93, 0, v10
	v_fma_f32 v10, -|v10|, v18, v93
	v_max_f32_e32 v94, 0, v11
	v_fma_f32 v11, -|v11|, v19, v94
	v_pk_mul_f32 v[16:17], v[24:25], v[16:17]
	ds_write_b32 v70, v3 offset:7888
	v_max_f32_e32 v95, 0, v6
	v_fma_f32 v6, -|v6|, v16, v95
	v_max_f32_e32 v96, 0, v7
	v_fma_f32 v7, -|v7|, v17, v96
	v_sub_f32_e32 v10, v10, v14
	v_sub_f32_e32 v11, v11, v14
	v_sub_f32_e32 v6, v6, v15
	v_mul_f32_e32 v10, v12, v10
	v_sub_f32_e32 v7, v7, v15
	v_mul_f32_e32 v11, v12, v11
	v_mul_f32_e32 v6, v13, v6
	v_mul_f32_e32 v7, v13, v7
	s_waitcnt vmcnt(0)
	v_fma_f32 v3, v8, v10, v4
	v_fma_f32 v10, v9, v11, v5
	v_fma_f32 v4, v8, v6, v4
	v_fmac_f32_e32 v5, v9, v7
	v_cvt_pk_bf16_f32 v3, v3, v4
	ds_write_b32 v70, v3 offset:8160
	v_cvt_pk_bf16_f32 v3, v10, v5
	v_lshl_add_u64 v[4:5], s[12:13], 0, v[28:29]
	ds_write_b32 v70, v3 offset:8432
	s_cbranch_vccnz .LBB0_458
	v_add_co_u32_e32 v6, vcc, 0x2688000, v4
	s_nop 1
	v_addc_co_u32_e32 v7, vcc, 0, v5, vcc
	global_load_dwordx4 v[6:9], v[6:7], off
	v_cndmask_b32_e64 v3, 0, 1, s[82:83]
	v_cmp_ne_u32_e64 s[6:7], 1, v3
	s_andn2_b64 vcc, exec, s[82:83]
	s_cbranch_vccz .LBB0_459
